# plus: memory cross-attention S phase with K-fragment LDS reads issued 8 MFMAs ahead (both layers)
# speedup vs baseline: 1.0189x; 1.0051x over previous
.LBB0_371:
	s_mov_b32 s0, s35
	s_ashr_i32 s1, s0, 31
	s_lshr_b32 s2, s1, 28
	s_add_i32 s2, s0, s2
	s_ashr_i32 s3, s2, 4
	s_lshr_b32 s4, s3, 30
	s_and_b32 s2, s2, 0x1fffff0
	s_add_i32 s4, s3, s4
	s_lshr_b32 s1, s1, 26
	s_sub_i32 s2, s0, s2
	s_and_b32 s4, s4, 0xfffffc
	s_add_i32 s0, s0, s1
	s_sub_i32 s3, s3, s4
	s_ashr_i32 s4, s0, 6
	s_lshl_b32 s0, s4, 11
	s_lshl_b32 s1, s2, 7
	s_lshl_b32 s4, s4, 8
	s_add_i32 s0, s0, s1
	s_lshl_b32 s2, s3, 8
	s_ashr_i32 s5, s4, 31
	s_ashr_i32 s1, s0, 31
	s_ashr_i32 s3, s2, 31
	s_lshl_b64 s[4:5], s[4:5], 13
	v_readlane_b32 s6, v255, 15
	s_add_u32 s4, s6, s4
	v_readlane_b32 s6, v255, 16
	s_addc_u32 s5, s6, s5
	s_lshl_b64 s[2:3], s[2:3], 1
	s_mov_b32 s6, s81
	s_add_u32 s4, s4, s2
	s_addc_u32 s5, s5, s3
	s_lshl_b32 s6, s6, 10
	s_add_i32 s6, s6, 0
	v_lshl_add_u64 v[0:1], s[4:5], 0, v[90:91]
	v_lshl_add_u64 v[0:1], v[0:1], 0, v[98:99]
	s_mov_b32 m0, s6
	v_lshl_add_u64 v[2:3], s[4:5], 0, v[92:93]
	global_load_lds_dwordx4 v[0:1], off
	v_lshl_add_u64 v[2:3], v[2:3], 0, v[100:101]
	s_add_i32 m0, s6, 0x2000
	s_mov_b64 s[8:9], 0x80
	global_load_lds_dwordx4 v[2:3], off
	s_add_i32 m0, s6, 0x4000
	v_lshl_add_u64 v[4:5], v[0:1], 0, s[8:9]
	global_load_lds_dwordx4 v[4:5], off
	v_lshl_add_u64 v[4:5], v[2:3], 0, s[8:9]
	s_add_i32 m0, s6, 0x6000
	s_mov_b64 s[10:11], 0x100
	global_load_lds_dwordx4 v[4:5], off
	s_add_i32 m0, s6, 0x8000
	v_lshl_add_u64 v[4:5], v[0:1], 0, s[10:11]
	global_load_lds_dwordx4 v[4:5], off
	v_lshl_add_u64 v[4:5], v[2:3], 0, s[10:11]
	s_add_i32 m0, s6, 0xa000
	s_mov_b64 s[12:13], 0x180
	global_load_lds_dwordx4 v[4:5], off
	s_add_i32 m0, s6, 0xc000
	v_lshl_add_u64 v[0:1], v[0:1], 0, s[12:13]
	global_load_lds_dwordx4 v[0:1], off
	v_lshl_add_u64 v[0:1], v[2:3], 0, s[12:13]
	s_add_i32 m0, s6, 0xe000
	v_lshl_add_u64 v[2:3], s[4:5], 0, v[96:97]
	global_load_lds_dwordx4 v[0:1], off
	v_lshl_add_u64 v[0:1], s[4:5], 0, v[94:95]
	s_add_i32 m0, s6, 0x10000
	v_lshl_add_u64 v[0:1], v[0:1], 0, v[98:99]
	global_load_lds_dwordx4 v[0:1], off
	v_lshl_add_u64 v[2:3], v[2:3], 0, v[100:101]
	s_add_i32 m0, s6, 0x12000
	v_lshl_add_u64 v[4:5], v[0:1], 0, s[8:9]
	global_load_lds_dwordx4 v[2:3], off
	s_add_i32 m0, s6, 0x14000
	s_lshl_b64 s[0:1], s[0:1], 13
	global_load_lds_dwordx4 v[4:5], off
	v_lshl_add_u64 v[4:5], v[2:3], 0, s[8:9]
	s_add_i32 m0, s6, 0x16000
	v_readlane_b32 s4, v255, 17
	global_load_lds_dwordx4 v[4:5], off
	s_add_i32 m0, s6, 0x18000
	v_lshl_add_u64 v[4:5], v[0:1], 0, s[10:11]
	global_load_lds_dwordx4 v[4:5], off
	v_lshl_add_u64 v[4:5], v[2:3], 0, s[10:11]
	s_add_i32 m0, s6, 0x1a000
	v_lshl_add_u64 v[0:1], v[0:1], 0, s[12:13]
	global_load_lds_dwordx4 v[4:5], off
	s_add_i32 m0, s6, 0x1c000
	s_nop 0
	global_load_lds_dwordx4 v[0:1], off
	s_add_i32 m0, s6, 0x1e000
	s_add_u32 s0, s4, s0
	v_readlane_b32 s4, v255, 18
	s_addc_u32 s1, s4, s1
	s_add_u32 s0, s0, s2
	v_lshl_add_u64 v[0:1], v[2:3], 0, s[12:13]
	s_addc_u32 s1, s1, s3
	global_load_lds_dwordx4 v[0:1], off
	v_lshl_add_u64 v[0:1], s[0:1], 0, v[102:103]
	v_lshl_add_u64 v[0:1], v[0:1], 0, v[88:89]
	global_load_dwordx4 v[52:55], v[0:1], off
	global_load_dwordx4 v[48:51], v[0:1], off offset:64
	global_load_dwordx4 v[44:47], v[0:1], off offset:128
	global_load_dwordx4 v[40:43], v[0:1], off offset:192
	global_load_dwordx4 v[36:39], v[0:1], off offset:256
	global_load_dwordx4 v[32:35], v[0:1], off offset:320
	global_load_dwordx4 v[28:31], v[0:1], off offset:384
	global_load_dwordx4 v[20:23], v[0:1], off offset:448
	s_mov_b32 s0, s35
	s_waitcnt vmcnt(0) lgkmcnt(0)
	s_waitcnt vmcnt(0)
	s_barrier
	s_mov_b32 s0, s81
	ds_read_b128 v[220:223], v110
	ds_read_b128 v[224:227], v110 offset:1024
	ds_read_b128 v[228:231], v110 offset:16384
	ds_read_b128 v[232:235], v110 offset:17408
	ds_read_b128 v[236:239], v110 offset:32768
	ds_read_b128 v[240:243], v110 offset:33792
	ds_read_b128 v[244:247], v110 offset:49152
	ds_read_b128 v[248:251], v110 offset:50176
	s_waitcnt lgkmcnt(7)
	v_mfma_f32_16x16x32_bf16 v[0:3], v[220:223], v[52:55], 0
	ds_read_b128 v[220:223], v110 offset:2048
	s_waitcnt lgkmcnt(7)
	v_mfma_f32_16x16x32_bf16 v[0:3], v[224:227], v[48:51], v[0:3]
	ds_read_b128 v[224:227], v110 offset:3072
	s_waitcnt lgkmcnt(7)
	v_mfma_f32_16x16x32_bf16 v[0:3], v[228:231], v[44:47], v[0:3]
	ds_read_b128 v[228:231], v110 offset:18432
	s_waitcnt lgkmcnt(7)
	v_mfma_f32_16x16x32_bf16 v[0:3], v[232:235], v[40:43], v[0:3]
	ds_read_b128 v[232:235], v110 offset:19456
	s_waitcnt lgkmcnt(7)
	v_mfma_f32_16x16x32_bf16 v[0:3], v[236:239], v[36:39], v[0:3]
	ds_read_b128 v[236:239], v110 offset:34816
	s_waitcnt lgkmcnt(7)
	v_mfma_f32_16x16x32_bf16 v[0:3], v[240:243], v[32:35], v[0:3]
	ds_read_b128 v[240:243], v110 offset:35840
	s_waitcnt lgkmcnt(7)
	v_mfma_f32_16x16x32_bf16 v[0:3], v[244:247], v[28:31], v[0:3]
	ds_read_b128 v[244:247], v110 offset:51200
	s_waitcnt lgkmcnt(7)
	v_mfma_f32_16x16x32_bf16 v[0:3], v[248:251], v[20:23], v[0:3]
	ds_read_b128 v[248:251], v110 offset:52224
	s_waitcnt lgkmcnt(7)
	v_mfma_f32_16x16x32_bf16 v[4:7], v[220:223], v[52:55], 0
	ds_read_b128 v[220:223], v110 offset:4096
	s_waitcnt lgkmcnt(7)
	v_mfma_f32_16x16x32_bf16 v[4:7], v[224:227], v[48:51], v[4:7]
	ds_read_b128 v[224:227], v110 offset:5120
	s_waitcnt lgkmcnt(7)
	v_mfma_f32_16x16x32_bf16 v[4:7], v[228:231], v[44:47], v[4:7]
	ds_read_b128 v[228:231], v110 offset:20480
	s_waitcnt lgkmcnt(7)
	v_mfma_f32_16x16x32_bf16 v[4:7], v[232:235], v[40:43], v[4:7]
	ds_read_b128 v[232:235], v110 offset:21504
	s_waitcnt lgkmcnt(7)
	v_mfma_f32_16x16x32_bf16 v[4:7], v[236:239], v[36:39], v[4:7]
	ds_read_b128 v[236:239], v110 offset:36864
	s_waitcnt lgkmcnt(7)
	v_mfma_f32_16x16x32_bf16 v[4:7], v[240:243], v[32:35], v[4:7]
	ds_read_b128 v[240:243], v110 offset:37888
	s_waitcnt lgkmcnt(7)
	v_mfma_f32_16x16x32_bf16 v[4:7], v[244:247], v[28:31], v[4:7]
	ds_read_b128 v[244:247], v110 offset:53248
	s_waitcnt lgkmcnt(7)
	v_mfma_f32_16x16x32_bf16 v[4:7], v[248:251], v[20:23], v[4:7]
	ds_read_b128 v[248:251], v110 offset:54272
	s_waitcnt lgkmcnt(7)
	v_mfma_f32_16x16x32_bf16 v[8:11], v[220:223], v[52:55], 0
	ds_read_b128 v[220:223], v110 offset:6144
	s_waitcnt lgkmcnt(7)
	v_mfma_f32_16x16x32_bf16 v[8:11], v[224:227], v[48:51], v[8:11]
	ds_read_b128 v[224:227], v110 offset:7168
	s_waitcnt lgkmcnt(7)
	v_mfma_f32_16x16x32_bf16 v[8:11], v[228:231], v[44:47], v[8:11]
	ds_read_b128 v[228:231], v110 offset:22528
	s_waitcnt lgkmcnt(7)
	v_mfma_f32_16x16x32_bf16 v[8:11], v[232:235], v[40:43], v[8:11]
	ds_read_b128 v[232:235], v110 offset:23552
	s_waitcnt lgkmcnt(7)
	v_mfma_f32_16x16x32_bf16 v[8:11], v[236:239], v[36:39], v[8:11]
	ds_read_b128 v[236:239], v110 offset:38912
	s_waitcnt lgkmcnt(7)
	v_mfma_f32_16x16x32_bf16 v[8:11], v[240:243], v[32:35], v[8:11]
	ds_read_b128 v[240:243], v110 offset:39936
	s_waitcnt lgkmcnt(7)
	v_mfma_f32_16x16x32_bf16 v[8:11], v[244:247], v[28:31], v[8:11]
	ds_read_b128 v[244:247], v110 offset:55296
	s_waitcnt lgkmcnt(7)
	v_mfma_f32_16x16x32_bf16 v[8:11], v[248:251], v[20:23], v[8:11]
	ds_read_b128 v[248:251], v110 offset:56320
	s_waitcnt lgkmcnt(7)
	v_mfma_f32_16x16x32_bf16 v[12:15], v[220:223], v[52:55], 0
	ds_read_b128 v[220:223], v110 offset:8192
	s_waitcnt lgkmcnt(7)
	v_mfma_f32_16x16x32_bf16 v[12:15], v[224:227], v[48:51], v[12:15]
	ds_read_b128 v[224:227], v110 offset:9216
	s_waitcnt lgkmcnt(7)
	v_mfma_f32_16x16x32_bf16 v[12:15], v[228:231], v[44:47], v[12:15]
	ds_read_b128 v[228:231], v110 offset:24576
	s_waitcnt lgkmcnt(7)
	v_mfma_f32_16x16x32_bf16 v[12:15], v[232:235], v[40:43], v[12:15]
	ds_read_b128 v[232:235], v110 offset:25600
	s_waitcnt lgkmcnt(7)
	v_mfma_f32_16x16x32_bf16 v[12:15], v[236:239], v[36:39], v[12:15]
	ds_read_b128 v[236:239], v110 offset:40960
	s_waitcnt lgkmcnt(7)
	v_mfma_f32_16x16x32_bf16 v[12:15], v[240:243], v[32:35], v[12:15]
	ds_read_b128 v[240:243], v110 offset:41984
	s_waitcnt lgkmcnt(7)
	v_mfma_f32_16x16x32_bf16 v[12:15], v[244:247], v[28:31], v[12:15]
	ds_read_b128 v[244:247], v110 offset:57344
	s_waitcnt lgkmcnt(7)
	v_mfma_f32_16x16x32_bf16 v[12:15], v[248:251], v[20:23], v[12:15]
	ds_read_b128 v[248:251], v110 offset:58368
	s_waitcnt lgkmcnt(7)
	v_mfma_f32_16x16x32_bf16 v[16:19], v[220:223], v[52:55], 0
	ds_read_b128 v[220:223], v110 offset:10240
	s_waitcnt lgkmcnt(7)
	v_mfma_f32_16x16x32_bf16 v[16:19], v[224:227], v[48:51], v[16:19]
	ds_read_b128 v[224:227], v110 offset:11264
	s_waitcnt lgkmcnt(7)
	v_mfma_f32_16x16x32_bf16 v[16:19], v[228:231], v[44:47], v[16:19]
	ds_read_b128 v[228:231], v110 offset:26624
	s_waitcnt lgkmcnt(7)
	v_mfma_f32_16x16x32_bf16 v[16:19], v[232:235], v[40:43], v[16:19]
	ds_read_b128 v[232:235], v110 offset:27648
	s_waitcnt lgkmcnt(7)
	v_mfma_f32_16x16x32_bf16 v[16:19], v[236:239], v[36:39], v[16:19]
	ds_read_b128 v[236:239], v110 offset:43008
	s_waitcnt lgkmcnt(7)
	v_mfma_f32_16x16x32_bf16 v[16:19], v[240:243], v[32:35], v[16:19]
	ds_read_b128 v[240:243], v110 offset:44032
	s_waitcnt lgkmcnt(7)
	v_mfma_f32_16x16x32_bf16 v[16:19], v[244:247], v[28:31], v[16:19]
	ds_read_b128 v[244:247], v110 offset:59392
	s_waitcnt lgkmcnt(7)
	v_mfma_f32_16x16x32_bf16 v[16:19], v[248:251], v[20:23], v[16:19]
	ds_read_b128 v[248:251], v110 offset:60416
	s_waitcnt lgkmcnt(7)
	v_mfma_f32_16x16x32_bf16 v[24:27], v[220:223], v[52:55], 0
	ds_read_b128 v[220:223], v110 offset:12288
	s_waitcnt lgkmcnt(7)
	v_mfma_f32_16x16x32_bf16 v[24:27], v[224:227], v[48:51], v[24:27]
	ds_read_b128 v[224:227], v110 offset:13312
	s_waitcnt lgkmcnt(7)
	v_mfma_f32_16x16x32_bf16 v[24:27], v[228:231], v[44:47], v[24:27]
	ds_read_b128 v[228:231], v110 offset:28672
	s_waitcnt lgkmcnt(7)
	v_mfma_f32_16x16x32_bf16 v[24:27], v[232:235], v[40:43], v[24:27]
	ds_read_b128 v[232:235], v110 offset:29696
	s_waitcnt lgkmcnt(7)
	v_mfma_f32_16x16x32_bf16 v[24:27], v[236:239], v[36:39], v[24:27]
	ds_read_b128 v[236:239], v110 offset:45056
	s_waitcnt lgkmcnt(7)
	v_mfma_f32_16x16x32_bf16 v[24:27], v[240:243], v[32:35], v[24:27]
	ds_read_b128 v[240:243], v110 offset:46080
	s_waitcnt lgkmcnt(7)
	v_mfma_f32_16x16x32_bf16 v[24:27], v[244:247], v[28:31], v[24:27]
	ds_read_b128 v[244:247], v110 offset:61440
	s_waitcnt lgkmcnt(7)
	v_mfma_f32_16x16x32_bf16 v[24:27], v[248:251], v[20:23], v[24:27]
	ds_read_b128 v[248:251], v110 offset:62464
	s_waitcnt lgkmcnt(7)
	v_mfma_f32_16x16x32_bf16 v[56:59], v[220:223], v[52:55], 0
	ds_read_b128 v[220:223], v110 offset:14336
	s_waitcnt lgkmcnt(7)
	v_mfma_f32_16x16x32_bf16 v[56:59], v[224:227], v[48:51], v[56:59]
	ds_read_b128 v[224:227], v110 offset:15360
	s_waitcnt lgkmcnt(7)
	v_mfma_f32_16x16x32_bf16 v[56:59], v[228:231], v[44:47], v[56:59]
	ds_read_b128 v[228:231], v110 offset:30720
	s_waitcnt lgkmcnt(7)
	v_mfma_f32_16x16x32_bf16 v[56:59], v[232:235], v[40:43], v[56:59]
	ds_read_b128 v[232:235], v110 offset:31744
	s_waitcnt lgkmcnt(7)
	v_mfma_f32_16x16x32_bf16 v[56:59], v[236:239], v[36:39], v[56:59]
	ds_read_b128 v[236:239], v110 offset:47104
	s_waitcnt lgkmcnt(7)
	v_mfma_f32_16x16x32_bf16 v[56:59], v[240:243], v[32:35], v[56:59]
	ds_read_b128 v[240:243], v110 offset:48128
	s_waitcnt lgkmcnt(7)
	v_mfma_f32_16x16x32_bf16 v[56:59], v[244:247], v[28:31], v[56:59]
	ds_read_b128 v[244:247], v110 offset:63488
	s_waitcnt lgkmcnt(7)
	v_mfma_f32_16x16x32_bf16 v[56:59], v[248:251], v[20:23], v[56:59]
	ds_read_b128 v[248:251], v110 offset:64512
	s_waitcnt lgkmcnt(7)
	v_mfma_f32_16x16x32_bf16 v[60:63], v[220:223], v[52:55], 0
	ds_read_b128 v[220:223], v111
	s_waitcnt lgkmcnt(7)
	v_mfma_f32_16x16x32_bf16 v[60:63], v[224:227], v[48:51], v[60:63]
	ds_read_b128 v[224:227], v112
	s_waitcnt lgkmcnt(7)
	v_mfma_f32_16x16x32_bf16 v[60:63], v[228:231], v[44:47], v[60:63]
	ds_read_b128 v[228:231], v113
	s_waitcnt lgkmcnt(7)
	v_mfma_f32_16x16x32_bf16 v[60:63], v[232:235], v[40:43], v[60:63]
	ds_read_b128 v[232:235], v114
	s_waitcnt lgkmcnt(7)
	v_mfma_f32_16x16x32_bf16 v[60:63], v[236:239], v[36:39], v[60:63]
	ds_read_b128 v[236:239], v115
	s_waitcnt lgkmcnt(7)
	v_mfma_f32_16x16x32_bf16 v[60:63], v[240:243], v[32:35], v[60:63]
	ds_read_b128 v[240:243], v116
	s_waitcnt lgkmcnt(7)
	v_mfma_f32_16x16x32_bf16 v[60:63], v[244:247], v[28:31], v[60:63]
	ds_read_b128 v[244:247], v117
	s_waitcnt lgkmcnt(7)
	v_mfma_f32_16x16x32_bf16 v[60:63], v[248:251], v[20:23], v[60:63]
	ds_read_b128 v[248:251], v118
	s_waitcnt lgkmcnt(7)
	v_mfma_f32_16x16x32_bf16 v[64:67], v[220:223], v[52:55], 0
	ds_read_b128 v[220:223], v119
	s_waitcnt lgkmcnt(7)
	v_mfma_f32_16x16x32_bf16 v[64:67], v[224:227], v[48:51], v[64:67]
	ds_read_b128 v[224:227], v120
	s_waitcnt lgkmcnt(7)
	v_mfma_f32_16x16x32_bf16 v[64:67], v[228:231], v[44:47], v[64:67]
	ds_read_b128 v[228:231], v121
	s_waitcnt lgkmcnt(7)
	v_mfma_f32_16x16x32_bf16 v[64:67], v[232:235], v[40:43], v[64:67]
	ds_read_b128 v[232:235], v122
	s_waitcnt lgkmcnt(7)
	v_mfma_f32_16x16x32_bf16 v[64:67], v[236:239], v[36:39], v[64:67]
	ds_read_b128 v[236:239], v123
	s_waitcnt lgkmcnt(7)
	v_mfma_f32_16x16x32_bf16 v[64:67], v[240:243], v[32:35], v[64:67]
	ds_read_b128 v[240:243], v124
	s_waitcnt lgkmcnt(7)
	v_mfma_f32_16x16x32_bf16 v[64:67], v[244:247], v[28:31], v[64:67]
	ds_read_b128 v[244:247], v125
	s_waitcnt lgkmcnt(7)
	v_mfma_f32_16x16x32_bf16 v[64:67], v[248:251], v[20:23], v[64:67]
	ds_read_b128 v[248:251], v126
	s_waitcnt lgkmcnt(7)
	v_mfma_f32_16x16x32_bf16 v[68:71], v[220:223], v[52:55], 0
	ds_read_b128 v[220:223], v127
	s_waitcnt lgkmcnt(7)
	v_mfma_f32_16x16x32_bf16 v[68:71], v[224:227], v[48:51], v[68:71]
	ds_read_b128 v[224:227], v128
	s_waitcnt lgkmcnt(7)
	v_mfma_f32_16x16x32_bf16 v[68:71], v[228:231], v[44:47], v[68:71]
	ds_read_b128 v[228:231], v129
	s_waitcnt lgkmcnt(7)
	v_mfma_f32_16x16x32_bf16 v[68:71], v[232:235], v[40:43], v[68:71]
	ds_read_b128 v[232:235], v130
	s_waitcnt lgkmcnt(7)
	v_mfma_f32_16x16x32_bf16 v[68:71], v[236:239], v[36:39], v[68:71]
	ds_read_b128 v[236:239], v131
	s_waitcnt lgkmcnt(7)
	v_mfma_f32_16x16x32_bf16 v[68:71], v[240:243], v[32:35], v[68:71]
	ds_read_b128 v[240:243], v132
	s_waitcnt lgkmcnt(7)
	v_mfma_f32_16x16x32_bf16 v[68:71], v[244:247], v[28:31], v[68:71]
	ds_read_b128 v[244:247], v133
	s_waitcnt lgkmcnt(7)
	v_mfma_f32_16x16x32_bf16 v[68:71], v[248:251], v[20:23], v[68:71]
	ds_read_b128 v[248:251], v134
	s_waitcnt lgkmcnt(7)
	v_mfma_f32_16x16x32_bf16 v[72:75], v[220:223], v[52:55], 0
	ds_read_b128 v[220:223], v135
	s_waitcnt lgkmcnt(7)
	v_mfma_f32_16x16x32_bf16 v[72:75], v[224:227], v[48:51], v[72:75]
	ds_read_b128 v[224:227], v136
	s_waitcnt lgkmcnt(7)
	v_mfma_f32_16x16x32_bf16 v[72:75], v[228:231], v[44:47], v[72:75]
	ds_read_b128 v[228:231], v137
	s_waitcnt lgkmcnt(7)
	v_mfma_f32_16x16x32_bf16 v[72:75], v[232:235], v[40:43], v[72:75]
	ds_read_b128 v[232:235], v138
	s_waitcnt lgkmcnt(7)
	v_mfma_f32_16x16x32_bf16 v[72:75], v[236:239], v[36:39], v[72:75]
	ds_read_b128 v[236:239], v139
	s_waitcnt lgkmcnt(7)
	v_mfma_f32_16x16x32_bf16 v[72:75], v[240:243], v[32:35], v[72:75]
	ds_read_b128 v[240:243], v140
	s_waitcnt lgkmcnt(7)
	v_mfma_f32_16x16x32_bf16 v[72:75], v[244:247], v[28:31], v[72:75]
	ds_read_b128 v[244:247], v141
	s_waitcnt lgkmcnt(7)
	v_mfma_f32_16x16x32_bf16 v[72:75], v[248:251], v[20:23], v[72:75]
	ds_read_b128 v[248:251], v142
	s_waitcnt lgkmcnt(7)
	v_mfma_f32_16x16x32_bf16 v[76:79], v[220:223], v[52:55], 0
	ds_read_b128 v[220:223], v143
	s_waitcnt lgkmcnt(7)
	v_mfma_f32_16x16x32_bf16 v[76:79], v[224:227], v[48:51], v[76:79]
	ds_read_b128 v[224:227], v144
	s_waitcnt lgkmcnt(7)
	v_mfma_f32_16x16x32_bf16 v[76:79], v[228:231], v[44:47], v[76:79]
	ds_read_b128 v[228:231], v145
	s_waitcnt lgkmcnt(7)
	v_mfma_f32_16x16x32_bf16 v[76:79], v[232:235], v[40:43], v[76:79]
	ds_read_b128 v[232:235], v146
	s_waitcnt lgkmcnt(7)
	v_mfma_f32_16x16x32_bf16 v[76:79], v[236:239], v[36:39], v[76:79]
	ds_read_b128 v[236:239], v147
	s_waitcnt lgkmcnt(7)
	v_mfma_f32_16x16x32_bf16 v[76:79], v[240:243], v[32:35], v[76:79]
	ds_read_b128 v[240:243], v148
	s_waitcnt lgkmcnt(7)
	v_mfma_f32_16x16x32_bf16 v[76:79], v[244:247], v[28:31], v[76:79]
	ds_read_b128 v[244:247], v149
	s_waitcnt lgkmcnt(7)
	v_mfma_f32_16x16x32_bf16 v[76:79], v[248:251], v[20:23], v[76:79]
	ds_read_b128 v[248:251], v150
	s_waitcnt lgkmcnt(7)
	v_mfma_f32_16x16x32_bf16 v[80:83], v[220:223], v[52:55], 0
	ds_read_b128 v[220:223], v151
	s_waitcnt lgkmcnt(7)
	v_mfma_f32_16x16x32_bf16 v[80:83], v[224:227], v[48:51], v[80:83]
	ds_read_b128 v[224:227], v152
	s_waitcnt lgkmcnt(7)
	v_mfma_f32_16x16x32_bf16 v[80:83], v[228:231], v[44:47], v[80:83]
	ds_read_b128 v[228:231], v153
	s_waitcnt lgkmcnt(7)
	v_mfma_f32_16x16x32_bf16 v[80:83], v[232:235], v[40:43], v[80:83]
	ds_read_b128 v[232:235], v154
	s_waitcnt lgkmcnt(7)
	v_mfma_f32_16x16x32_bf16 v[80:83], v[236:239], v[36:39], v[80:83]
	ds_read_b128 v[236:239], v155
	s_waitcnt lgkmcnt(7)
	v_mfma_f32_16x16x32_bf16 v[80:83], v[240:243], v[32:35], v[80:83]
	ds_read_b128 v[240:243], v156
	s_waitcnt lgkmcnt(7)
	v_mfma_f32_16x16x32_bf16 v[80:83], v[244:247], v[28:31], v[80:83]
	ds_read_b128 v[244:247], v157
	s_waitcnt lgkmcnt(7)
	v_mfma_f32_16x16x32_bf16 v[80:83], v[248:251], v[20:23], v[80:83]
	ds_read_b128 v[248:251], v158
	s_waitcnt lgkmcnt(7)
	v_mfma_f32_16x16x32_bf16 v[84:87], v[220:223], v[52:55], 0
	ds_read_b128 v[220:223], v159
	s_waitcnt lgkmcnt(7)
	v_mfma_f32_16x16x32_bf16 v[84:87], v[224:227], v[48:51], v[84:87]
	ds_read_b128 v[224:227], v160
	s_waitcnt lgkmcnt(7)
	v_mfma_f32_16x16x32_bf16 v[84:87], v[228:231], v[44:47], v[84:87]
	ds_read_b128 v[228:231], v161
	s_waitcnt lgkmcnt(7)
	v_mfma_f32_16x16x32_bf16 v[84:87], v[232:235], v[40:43], v[84:87]
	ds_read_b128 v[232:235], v162
	s_waitcnt lgkmcnt(7)
	v_mfma_f32_16x16x32_bf16 v[84:87], v[236:239], v[36:39], v[84:87]
	ds_read_b128 v[236:239], v163
	s_waitcnt lgkmcnt(7)
	v_mfma_f32_16x16x32_bf16 v[84:87], v[240:243], v[32:35], v[84:87]
	ds_read_b128 v[240:243], v164
	s_waitcnt lgkmcnt(7)
	v_mfma_f32_16x16x32_bf16 v[84:87], v[244:247], v[28:31], v[84:87]
	ds_read_b128 v[244:247], v165
	s_waitcnt lgkmcnt(7)
	v_mfma_f32_16x16x32_bf16 v[84:87], v[248:251], v[20:23], v[84:87]
	ds_read_b128 v[248:251], v166
	s_waitcnt lgkmcnt(7)
	v_mfma_f32_16x16x32_bf16 v[208:211], v[220:223], v[52:55], 0
	s_waitcnt lgkmcnt(6)
	v_mfma_f32_16x16x32_bf16 v[208:211], v[224:227], v[48:51], v[208:211]
	s_waitcnt lgkmcnt(5)
	v_mfma_f32_16x16x32_bf16 v[208:211], v[228:231], v[44:47], v[208:211]
	s_waitcnt lgkmcnt(4)
	v_mfma_f32_16x16x32_bf16 v[208:211], v[232:235], v[40:43], v[208:211]
	s_waitcnt lgkmcnt(3)
	v_mfma_f32_16x16x32_bf16 v[208:211], v[236:239], v[36:39], v[208:211]
	s_waitcnt lgkmcnt(2)
	v_mfma_f32_16x16x32_bf16 v[208:211], v[240:243], v[32:35], v[208:211]
	s_waitcnt lgkmcnt(1)
	v_mfma_f32_16x16x32_bf16 v[208:211], v[244:247], v[28:31], v[208:211]
	s_waitcnt lgkmcnt(0)
	v_mfma_f32_16x16x32_bf16 v[210:213], v[248:251], v[20:23], v[208:211]
	ds_read_b128 v[214:217], v167
	s_waitcnt lgkmcnt(0)
	v_mfma_f32_16x16x32_bf16 v[52:55], v[214:217], v[52:55], 0
	ds_read_b128 v[214:217], v168
	s_waitcnt lgkmcnt(0)
	v_mfma_f32_16x16x32_bf16 v[48:51], v[214:217], v[48:51], v[52:55]
	s_nop 4
	ds_read_b128 v[52:55], v169
	s_waitcnt lgkmcnt(0)
	v_mfma_f32_16x16x32_bf16 v[44:47], v[52:55], v[44:47], v[48:51]
	s_nop 2
	ds_read_b128 v[48:51], v170
	s_waitcnt lgkmcnt(0)
	v_mfma_f32_16x16x32_bf16 v[40:43], v[48:51], v[40:43], v[44:47]
	s_nop 2
	ds_read_b128 v[44:47], v171
	v_mov_b32_e32 v48, v64
	v_mov_b32_e32 v49, v66
	s_waitcnt lgkmcnt(0)
	v_mfma_f32_16x16x32_bf16 v[36:39], v[44:47], v[36:39], v[40:43]
	s_nop 2
	ds_read_b128 v[40:43], v172
	v_mov_b32_e32 v66, v65
	v_mov_b32_e32 v64, v56
	s_waitcnt lgkmcnt(0)
	v_mfma_f32_16x16x32_bf16 v[32:35], v[40:43], v[32:35], v[36:39]
	s_nop 2
	ds_read_b128 v[36:39], v173
	v_mov_b32_e32 v40, v72
	v_mov_b32_e32 v41, v74
	s_waitcnt lgkmcnt(0)
	v_mfma_f32_16x16x32_bf16 v[28:31], v[36:39], v[28:31], v[32:35]
	s_nop 2
	ds_read_b128 v[32:35], v174
	v_pk_mul_f32 v[46:47], v[40:41], s[30:31] op_sel_hi:[1,0]
	v_mov_b32_e32 v40, v76
	s_waitcnt lgkmcnt(0)
	v_mfma_f32_16x16x32_bf16 v[32:35], v[32:35], v[20:23], v[28:31]
	v_lshl_or_b32 v20, s0, 4, v107
	v_and_b32_e32 v21, 64, v207
	v_xor_b32_e32 v20, 16, v207
	v_add_u32_e32 v21, 64, v21
	v_cmp_lt_i32_e32 vcc, v20, v21
	v_mov_b32_e32 v41, v78
	v_mov_b32_e32 v78, v77
	v_cndmask_b32_e32 v20, v207, v20, vcc
	v_lshlrev_b32_e32 v208, 2, v20
	v_xor_b32_e32 v20, 32, v207
	v_cmp_lt_i32_e32 vcc, v20, v21
	v_mov_b32_e32 v21, v212
	v_mov_b32_e32 v212, v211
	v_cndmask_b32_e32 v20, v207, v20, vcc
	v_lshlrev_b32_e32 v105, 2, v20
	v_mov_b32_e32 v20, v210
	v_pk_mul_f32 v[30:31], v[20:21], s[30:31] op_sel_hi:[1,0]
	v_pk_mul_f32 v[28:29], v[212:213], s[30:31] op_sel_hi:[1,0]
	v_cmp_lt_f32_e64 s[0:1], s31, v30
	v_mov_b32_e32 v20, v32
	v_mov_b32_e32 v21, v34
	v_writelane_b32 v255, s0, 22
	v_pk_mul_f32 v[22:23], v[20:21], s[30:31] op_sel_hi:[1,0]
	v_mov_b32_e32 v34, v33
	v_writelane_b32 v255, s1, 23
	v_cmp_lt_f32_e64 s[0:1], s31, v31
	v_pk_mul_f32 v[20:21], v[34:35], s[30:31] op_sel_hi:[1,0]
	v_mov_b32_e32 v32, v80
	v_writelane_b32 v255, s0, 24
	v_mov_b32_e32 v33, v82
	v_pk_mul_f32 v[38:39], v[32:33], s[30:31] op_sel_hi:[1,0]
	v_writelane_b32 v255, s1, 25
	v_cmp_lt_f32_e64 s[0:1], s31, v28
	v_mov_b32_e32 v82, v81
	v_pk_mul_f32 v[36:37], v[82:83], s[30:31] op_sel_hi:[1,0]
	v_writelane_b32 v255, s0, 26
	v_mov_b32_e32 v32, v84
	v_mov_b32_e32 v33, v86
	v_writelane_b32 v255, s1, 27
	v_cmp_lt_f32_e64 s[0:1], s31, v29
	v_pk_mul_f32 v[34:35], v[32:33], s[30:31] op_sel_hi:[1,0]
	v_mov_b32_e32 v86, v85
	v_writelane_b32 v255, s0, 28
	v_pk_mul_f32 v[32:33], v[86:87], s[30:31] op_sel_hi:[1,0]
	v_pk_mul_f32 v[42:43], v[40:41], s[30:31] op_sel_hi:[1,0]
	v_writelane_b32 v255, s1, 29
	v_cmp_lt_f32_e64 s[0:1], s31, v22
	v_pk_mul_f32 v[40:41], v[78:79], s[30:31] op_sel_hi:[1,0]
	v_mov_b32_e32 v65, v58
	v_writelane_b32 v255, s0, 30
	v_mov_b32_e32 v58, v57
	v_mov_b32_e32 v56, v60
	v_writelane_b32 v255, s1, 31
	v_cmp_lt_f32_e64 s[0:1], s31, v23
	v_mov_b32_e32 v57, v62
	v_mov_b32_e32 v62, v61
	v_writelane_b32 v255, s0, 32
	v_mov_b32_e32 v60, v16
	v_mov_b32_e32 v61, v18
	v_writelane_b32 v255, s1, 33
	v_cmp_lt_f32_e64 s[0:1], s31, v20
	v_mov_b32_e32 v18, v17
	v_mov_b32_e32 v16, v24
	v_writelane_b32 v255, s0, 34
	v_mov_b32_e32 v17, v26
	v_mov_b32_e32 v26, v25
	v_writelane_b32 v255, s1, 35
	v_cmp_lt_f32_e64 s[0:1], s31, v21
	v_mov_b32_e32 v24, v8
	v_mov_b32_e32 v25, v10
	v_writelane_b32 v255, s0, 36
	v_mov_b32_e32 v10, v9
	v_mov_b32_e32 v8, v12
	v_writelane_b32 v255, s1, 37
	v_cmp_lt_f32_e64 s[0:1], s31, v38
	v_mov_b32_e32 v9, v14
	v_mov_b32_e32 v14, v13
	v_writelane_b32 v255, s0, 38
	v_mov_b32_e32 v12, v0
	v_mov_b32_e32 v13, v2
	v_writelane_b32 v255, s1, 39
	v_cmp_lt_f32_e64 s[0:1], s31, v39
	v_mov_b32_e32 v2, v1
	v_pk_mul_f32 v[52:53], v[66:67], s[30:31] op_sel_hi:[1,0]
	v_writelane_b32 v255, s0, 40
	v_pk_mul_f32 v[66:67], v[64:65], s[30:31] op_sel_hi:[1,0]
	v_pk_mul_f32 v[64:65], v[58:59], s[30:31] op_sel_hi:[1,0]
	v_writelane_b32 v255, s1, 41
	v_cmp_lt_f32_e64 s[0:1], s31, v36
	v_pk_mul_f32 v[58:59], v[56:57], s[30:31] op_sel_hi:[1,0]
	v_pk_mul_f32 v[56:57], v[62:63], s[30:31] op_sel_hi:[1,0]
	v_writelane_b32 v255, s0, 42
	v_pk_mul_f32 v[62:63], v[60:61], s[30:31] op_sel_hi:[1,0]
	v_pk_mul_f32 v[60:61], v[18:19], s[30:31] op_sel_hi:[1,0]
	v_writelane_b32 v255, s1, 43
	v_cmp_lt_f32_e64 s[0:1], s31, v37
	v_pk_mul_f32 v[18:19], v[16:17], s[30:31] op_sel_hi:[1,0]
	v_pk_mul_f32 v[16:17], v[26:27], s[30:31] op_sel_hi:[1,0]
	v_writelane_b32 v255, s0, 44
	v_pk_mul_f32 v[26:27], v[24:25], s[30:31] op_sel_hi:[1,0]
	v_pk_mul_f32 v[24:25], v[10:11], s[30:31] op_sel_hi:[1,0]
	v_writelane_b32 v255, s1, 45
	v_cmp_lt_f32_e64 s[0:1], s31, v34
	v_pk_mul_f32 v[10:11], v[8:9], s[30:31] op_sel_hi:[1,0]
	v_pk_mul_f32 v[8:9], v[14:15], s[30:31] op_sel_hi:[1,0]
	v_writelane_b32 v255, s0, 46
	v_pk_mul_f32 v[12:13], v[12:13], s[30:31] op_sel_hi:[1,0]
	v_pk_mul_f32 v[14:15], v[2:3], s[30:31] op_sel_hi:[1,0]
	v_writelane_b32 v255, s1, 47
	v_cmp_lt_f32_e64 s[0:1], s31, v35
	v_pk_mul_f32 v[54:55], v[48:49], s[30:31] op_sel_hi:[1,0]
	v_mov_b32_e32 v48, v68
	v_writelane_b32 v255, s0, 48
	v_mov_b32_e32 v49, v70
	v_mov_b32_e32 v70, v69
	v_writelane_b32 v255, s1, 49
	v_cmp_lt_f32_e64 s[0:1], s31, v32
	v_mov_b32_e32 v1, v6
	v_mov_b32_e32 v6, v5
	v_writelane_b32 v255, s0, 50
	v_pk_mul_f32 v[50:51], v[48:49], s[30:31] op_sel_hi:[1,0]
	v_pk_mul_f32 v[48:49], v[70:71], s[30:31] op_sel_hi:[1,0]
	v_writelane_b32 v255, s1, 51
	v_cmp_lt_f32_e64 s[0:1], s31, v33
	v_pk_mul_f32 v[70:71], v[6:7], s[30:31] op_sel_hi:[1,0]
	v_mov_b32_e32 v74, v73
	v_writelane_b32 v255, s0, 52
	v_pk_mul_f32 v[44:45], v[74:75], s[30:31] op_sel_hi:[1,0]
	v_cmp_lt_f32_e64 s[4:5], s31, v14
	v_writelane_b32 v255, s1, 53
	v_cmp_lt_f32_e64 s[0:1], s31, v40
	v_cmp_lt_f32_e32 vcc, s31, v13
	v_cmp_lt_f32_e64 s[2:3], s31, v15
	v_writelane_b32 v255, s0, 54
	v_cmp_lt_f32_e64 s[12:13], s31, v70
	v_cmp_lt_f32_e64 s[10:11], s31, v71
	v_writelane_b32 v255, s1, 55
	s_mov_b32 s0, 0xff61b1e6
	v_max3_f32 v0, v12, s0, v14
	v_max3_f32 v2, v0, v13, v15
	v_mov_b32_e32 v0, v4
	v_pk_mul_f32 v[68:69], v[0:1], s[30:31] op_sel_hi:[1,0]
	v_cmp_lt_f32_e64 s[0:1], s31, v12
	v_max3_f32 v0, v2, v68, v70
	v_max3_f32 v0, v0, v69, v71
	v_max3_f32 v0, v0, v26, v24
	v_max3_f32 v0, v0, v27, v25
	v_max3_f32 v0, v0, v10, v8
	v_max3_f32 v0, v0, v11, v9
	v_max3_f32 v0, v0, v62, v60
	v_max3_f32 v0, v0, v63, v61
	v_max3_f32 v0, v0, v18, v16
	v_max3_f32 v0, v0, v19, v17
	v_max3_f32 v0, v0, v66, v64
	v_max3_f32 v0, v0, v67, v65
	v_max3_f32 v0, v0, v58, v56
	v_max3_f32 v0, v0, v59, v57
	v_max3_f32 v0, v0, v54, v52
	v_max3_f32 v0, v0, v55, v53
	v_max3_f32 v0, v0, v50, v48
	v_max3_f32 v0, v0, v51, v49
	v_max3_f32 v0, v0, v46, v44
	v_max3_f32 v0, v0, v47, v45
	v_max3_f32 v0, v0, v42, v40
	v_max3_f32 v0, v0, v43, v41
	v_max3_f32 v0, v0, v38, v36
	v_max3_f32 v0, v0, v39, v37
	v_max3_f32 v0, v0, v34, v32
	v_max3_f32 v0, v0, v35, v33
	v_max3_f32 v0, v0, v30, v28
	v_max3_f32 v0, v0, v31, v29
	v_max3_f32 v0, v0, v22, v20
	v_max3_f32 v0, v0, v23, v21
	ds_bpermute_b32 v1, v208, v0
	v_cmp_lt_f32_e64 s[8:9], s31, v68
	v_cmp_lt_f32_e64 s[6:7], s31, v69
	v_cmp_lt_f32_e64 s[16:17], s31, v26
	v_cmp_lt_f32_e64 s[22:23], s31, v24
	s_waitcnt lgkmcnt(0)
	v_max_f32_e32 v1, v1, v1
	v_max_f32_e32 v0, v0, v1
	ds_bpermute_b32 v1, v105, v0
	v_cmp_lt_f32_e64 s[24:25], s31, v10
	v_cmp_lt_f32_e64 s[18:19], s31, v25
	v_cmp_lt_f32_e64 s[14:15], s31, v27
	v_cmp_lt_f32_e64 s[28:29], s31, v8
	s_waitcnt lgkmcnt(0)
	v_max_f32_e32 v1, v1, v1
	v_max_f32_e32 v2, v0, v1
	v_sub_f32_e32 v0, v12, v2
	v_mul_f32_e32 v0, 0x3fb8aa3b, v0
	v_sub_f32_e32 v3, v14, v2
	v_exp_f32_e32 v1, v0
	v_sub_f32_e32 v0, v13, v2
	v_mul_f32_e32 v3, 0x3fb8aa3b, v3
	v_mul_f32_e32 v0, 0x3fb8aa3b, v0
	v_exp_f32_e32 v4, v3
	v_sub_f32_e32 v3, v15, v2
	v_exp_f32_e32 v0, v0
	v_mul_f32_e32 v3, 0x3fb8aa3b, v3
	v_exp_f32_e32 v3, v3
	v_cndmask_b32_e64 v1, 0, v1, s[0:1]
	v_add_f32_e32 v5, 0, v1
	v_cndmask_b32_e64 v4, 0, v4, s[4:5]
	v_cndmask_b32_e32 v0, 0, v0, vcc
	v_add_f32_e32 v5, v4, v5
	v_cndmask_b32_e64 v3, 0, v3, s[2:3]
	v_add_f32_e32 v5, v0, v5
	v_add_f32_e32 v7, v3, v5
	v_sub_f32_e32 v5, v68, v2
	v_mul_f32_e32 v5, 0x3fb8aa3b, v5
	v_exp_f32_e32 v6, v5
	v_sub_f32_e32 v5, v69, v2
	v_mul_f32_e32 v5, 0x3fb8aa3b, v5
	v_exp_f32_e32 v5, v5
	v_cndmask_b32_e64 v6, 0, v6, s[8:9]
	v_add_f32_e32 v12, v6, v7
	v_sub_f32_e32 v7, v70, v2
	v_mul_f32_e32 v7, 0x3fb8aa3b, v7
	v_exp_f32_e32 v13, v7
	v_sub_f32_e32 v7, v71, v2
	v_mul_f32_e32 v7, 0x3fb8aa3b, v7
	v_exp_f32_e32 v7, v7
	v_cndmask_b32_e64 v13, 0, v13, s[12:13]
	v_cndmask_b32_e64 v5, 0, v5, s[6:7]
	v_add_f32_e32 v12, v13, v12
	v_cndmask_b32_e64 v7, 0, v7, s[10:11]
	v_add_f32_e32 v12, v5, v12
	v_add_f32_e32 v15, v7, v12
	v_sub_f32_e32 v12, v26, v2
	v_mul_f32_e32 v12, 0x3fb8aa3b, v12
	v_exp_f32_e32 v14, v12
	v_sub_f32_e32 v12, v27, v2
	v_mul_f32_e32 v12, 0x3fb8aa3b, v12
	v_exp_f32_e32 v12, v12
	v_cndmask_b32_e64 v14, 0, v14, s[16:17]
	v_add_f32_e32 v26, v14, v15
	v_sub_f32_e32 v15, v24, v2
	v_mul_f32_e32 v15, 0x3fb8aa3b, v15
	v_exp_f32_e32 v24, v15
	v_sub_f32_e32 v15, v25, v2
	v_mul_f32_e32 v15, 0x3fb8aa3b, v15
	v_sub_f32_e32 v10, v10, v2
	v_exp_f32_e32 v15, v15
	v_cndmask_b32_e64 v24, 0, v24, s[22:23]
	v_mul_f32_e32 v10, 0x3fb8aa3b, v10
	v_add_f32_e32 v25, v24, v26
	v_exp_f32_e32 v26, v10
	v_cndmask_b32_e64 v12, 0, v12, s[14:15]
	v_cndmask_b32_e64 v15, 0, v15, s[18:19]
	v_add_f32_e32 v25, v12, v25
	v_sub_f32_e32 v8, v8, v2
	v_cmp_lt_f32_e64 s[20:21], s31, v11
	v_add_f32_e32 v25, v15, v25
	v_sub_f32_e32 v10, v11, v2
	v_cndmask_b32_e64 v11, 0, v26, s[24:25]
	v_mul_f32_e32 v8, 0x3fb8aa3b, v8
	v_mul_f32_e32 v10, 0x3fb8aa3b, v10
	v_add_f32_e32 v26, v11, v25
	v_exp_f32_e32 v25, v8
	v_sub_f32_e32 v8, v9, v2
	v_exp_f32_e32 v10, v10
	v_mul_f32_e32 v8, 0x3fb8aa3b, v8
	v_exp_f32_e32 v8, v8
	v_cndmask_b32_e64 v25, 0, v25, s[28:29]
	v_cmp_lt_f32_e64 s[26:27], s31, v9
	v_cndmask_b32_e64 v10, 0, v10, s[20:21]
	v_add_f32_e32 v9, v25, v26
	v_cndmask_b32_e64 v8, 0, v8, s[26:27]
	v_add_f32_e32 v9, v10, v9
	v_add_f32_e32 v26, v8, v9
	v_sub_f32_e32 v9, v62, v2
	v_mul_f32_e32 v9, 0x3fb8aa3b, v9
	v_exp_f32_e32 v27, v9
	v_cmp_lt_f32_e64 s[94:95], s31, v62
	v_cmp_lt_f32_e64 s[86:87], s31, v18
	v_sub_f32_e32 v18, v18, v2
	v_cndmask_b32_e64 v62, 0, v27, s[94:95]
	v_sub_f32_e32 v27, v60, v2
	v_mul_f32_e32 v27, 0x3fb8aa3b, v27
	v_exp_f32_e32 v27, v27
	v_cmp_lt_f32_e64 s[88:89], s31, v60
	v_sub_f32_e32 v9, v63, v2
	v_mul_f32_e32 v18, 0x3fb8aa3b, v18
	v_cmp_lt_f32_e64 s[92:93], s31, v61
	v_mul_f32_e32 v9, 0x3fb8aa3b, v9
	v_sub_f32_e32 v60, v61, v2
	v_cndmask_b32_e64 v61, 0, v27, s[88:89]
	v_exp_f32_e32 v27, v18
	v_exp_f32_e32 v9, v9
	v_mul_f32_e32 v60, 0x3fb8aa3b, v60
	v_cmp_lt_f32_e64 s[82:83], s31, v16
	v_exp_f32_e32 v60, v60
	v_sub_f32_e32 v16, v16, v2
	v_sub_f32_e32 v18, v19, v2
	v_mul_f32_e32 v16, 0x3fb8aa3b, v16
	v_cmp_lt_f32_e64 s[96:97], s31, v63
	v_cmp_lt_f32_e64 s[90:91], s31, v19
	v_add_f32_e32 v26, v62, v26
	v_mul_f32_e32 v18, 0x3fb8aa3b, v18
	v_cndmask_b32_e64 v19, 0, v27, s[86:87]
	v_exp_f32_e32 v27, v16
	v_sub_f32_e32 v16, v17, v2
	v_cndmask_b32_e64 v9, 0, v9, s[96:97]
	v_add_f32_e32 v26, v61, v26
	v_exp_f32_e32 v18, v18
	v_mul_f32_e32 v16, 0x3fb8aa3b, v16
	v_cndmask_b32_e64 v60, 0, v60, s[92:93]
	v_add_f32_e32 v26, v9, v26
	v_exp_f32_e32 v16, v16
	v_add_f32_e32 v26, v60, v26
	v_add_f32_e32 v26, v19, v26
	v_cndmask_b32_e64 v63, 0, v27, s[82:83]
	v_cmp_lt_f32_e64 s[84:85], s31, v17
	v_cndmask_b32_e64 v18, 0, v18, s[90:91]
	v_add_f32_e32 v17, v63, v26
	v_cndmask_b32_e64 v16, 0, v16, s[84:85]
	v_add_f32_e32 v17, v18, v17
	v_add_f32_e32 v26, v16, v17
	v_sub_f32_e32 v17, v66, v2
	v_mul_f32_e32 v17, 0x3fb8aa3b, v17
	v_exp_f32_e32 v27, v17
	v_cmp_lt_f32_e64 s[78:79], s31, v66
	v_cmp_lt_f32_e64 s[74:75], s31, v64
	v_cmp_lt_f32_e64 s[76:77], s31, v65
	v_cndmask_b32_e64 v66, 0, v27, s[78:79]
	v_sub_f32_e32 v27, v64, v2
	v_mul_f32_e32 v27, 0x3fb8aa3b, v27
	v_exp_f32_e32 v27, v27
	v_sub_f32_e32 v64, v65, v2
	v_cmp_lt_f32_e64 s[70:71], s31, v58
	v_cmp_lt_f32_e64 s[72:73], s31, v59
	v_cndmask_b32_e64 v65, 0, v27, s[74:75]
	v_sub_f32_e32 v27, v58, v2
	v_mul_f32_e32 v27, 0x3fb8aa3b, v27
	v_exp_f32_e32 v27, v27
	v_sub_f32_e32 v58, v59, v2
	v_cmp_lt_f32_e64 s[66:67], s31, v56
	v_cmp_lt_f32_e64 s[68:69], s31, v57
	v_cndmask_b32_e64 v59, 0, v27, s[70:71]
	v_sub_f32_e32 v27, v56, v2
	v_mul_f32_e32 v27, 0x3fb8aa3b, v27
	v_exp_f32_e32 v27, v27
	v_sub_f32_e32 v56, v57, v2
	v_cmp_lt_f32_e64 s[62:63], s31, v54
	v_cmp_lt_f32_e64 s[64:65], s31, v55
	v_cndmask_b32_e64 v57, 0, v27, s[66:67]
	v_sub_f32_e32 v27, v54, v2
	v_mul_f32_e32 v27, 0x3fb8aa3b, v27
	v_exp_f32_e32 v27, v27
	v_sub_f32_e32 v54, v55, v2
	v_cmp_lt_f32_e64 s[54:55], s31, v52
	v_cmp_lt_f32_e64 s[60:61], s31, v53
	v_cndmask_b32_e64 v55, 0, v27, s[62:63]
	v_sub_f32_e32 v27, v52, v2
	v_mul_f32_e32 v27, 0x3fb8aa3b, v27
	v_exp_f32_e32 v27, v27
	v_sub_f32_e32 v52, v53, v2
	v_cmp_lt_f32_e64 s[56:57], s31, v50
	v_cmp_lt_f32_e64 s[58:59], s31, v51
	v_cndmask_b32_e64 v53, 0, v27, s[54:55]
	v_sub_f32_e32 v27, v50, v2
	v_mul_f32_e32 v27, 0x3fb8aa3b, v27
	v_exp_f32_e32 v27, v27
	v_sub_f32_e32 v50, v51, v2
	v_cmp_lt_f32_e64 s[50:51], s31, v48
	v_cmp_lt_f32_e64 s[52:53], s31, v49
	v_cndmask_b32_e64 v51, 0, v27, s[56:57]
	v_sub_f32_e32 v27, v48, v2
	v_mul_f32_e32 v27, 0x3fb8aa3b, v27
	v_exp_f32_e32 v27, v27
	v_sub_f32_e32 v48, v49, v2
	v_cmp_lt_f32_e64 s[46:47], s31, v46
	v_cmp_lt_f32_e64 s[48:49], s31, v47
	v_cndmask_b32_e64 v49, 0, v27, s[50:51]
	v_sub_f32_e32 v27, v46, v2
	v_mul_f32_e32 v27, 0x3fb8aa3b, v27
	v_exp_f32_e32 v27, v27
	v_sub_f32_e32 v46, v47, v2
	v_cmp_lt_f32_e64 s[42:43], s31, v44
	v_cmp_lt_f32_e64 s[44:45], s31, v45
	v_cndmask_b32_e64 v47, 0, v27, s[46:47]
	v_sub_f32_e32 v27, v44, v2
	v_mul_f32_e32 v27, 0x3fb8aa3b, v27
	v_exp_f32_e32 v27, v27
	v_sub_f32_e32 v44, v45, v2
	v_cmp_lt_f32_e64 s[38:39], s31, v42
	v_cmp_lt_f32_e64 s[40:41], s31, v43
	v_cndmask_b32_e64 v45, 0, v27, s[42:43]
	v_sub_f32_e32 v27, v42, v2
	v_mul_f32_e32 v27, 0x3fb8aa3b, v27
	v_exp_f32_e32 v27, v27
	v_sub_f32_e32 v42, v43, v2
	v_readlane_b32 s0, v255, 54
	v_readlane_b32 s1, v255, 55
	v_cndmask_b32_e64 v43, 0, v27, s[38:39]
	v_sub_f32_e32 v27, v40, v2
	v_mul_f32_e32 v27, 0x3fb8aa3b, v27
	v_exp_f32_e32 v27, v27
	v_cmp_lt_f32_e64 s[36:37], s31, v41
	v_sub_f32_e32 v40, v41, v2
	v_sub_f32_e32 v17, v67, v2
	v_cndmask_b32_e64 v41, 0, v27, s[0:1]
	v_sub_f32_e32 v27, v38, v2
	v_sub_f32_e32 v38, v39, v2
	v_mul_f32_e32 v38, 0x3fb8aa3b, v38
	v_exp_f32_e32 v38, v38
	v_mul_f32_e32 v27, 0x3fb8aa3b, v27
	v_exp_f32_e32 v27, v27
	v_readlane_b32 s0, v255, 40
	v_readlane_b32 s1, v255, 41
	v_mul_f32_e32 v17, 0x3fb8aa3b, v17
	v_exp_f32_e32 v17, v17
	v_cndmask_b32_e64 v38, 0, v38, s[0:1]
	v_readlane_b32 s0, v255, 38
	v_readlane_b32 s1, v255, 39
	v_mul_f32_e32 v64, 0x3fb8aa3b, v64
	v_exp_f32_e32 v64, v64
	v_cndmask_b32_e64 v39, 0, v27, s[0:1]
	v_sub_f32_e32 v27, v36, v2
	v_sub_f32_e32 v36, v37, v2
	v_mul_f32_e32 v36, 0x3fb8aa3b, v36
	v_exp_f32_e32 v36, v36
	v_mul_f32_e32 v27, 0x3fb8aa3b, v27
	v_exp_f32_e32 v27, v27
	v_readlane_b32 s0, v255, 44
	v_readlane_b32 s1, v255, 45
	v_cmp_lt_f32_e64 s[80:81], s31, v67
	v_add_f32_e32 v26, v66, v26
	v_cndmask_b32_e64 v36, 0, v36, s[0:1]
	v_readlane_b32 s0, v255, 42
	v_readlane_b32 s1, v255, 43
	v_mul_f32_e32 v58, 0x3fb8aa3b, v58
	v_cndmask_b32_e64 v17, 0, v17, s[80:81]
	v_cndmask_b32_e64 v37, 0, v27, s[0:1]
	v_sub_f32_e32 v27, v34, v2
	v_sub_f32_e32 v34, v35, v2
	v_mul_f32_e32 v34, 0x3fb8aa3b, v34
	v_exp_f32_e32 v34, v34
	v_mul_f32_e32 v27, 0x3fb8aa3b, v27
	v_exp_f32_e32 v27, v27
	v_readlane_b32 s0, v255, 48
	v_add_f32_e32 v26, v65, v26
	v_exp_f32_e32 v58, v58
	v_mul_f32_e32 v56, 0x3fb8aa3b, v56
	v_readlane_b32 s1, v255, 49
	v_cndmask_b32_e64 v64, 0, v64, s[76:77]
	v_add_f32_e32 v26, v17, v26
	v_exp_f32_e32 v56, v56
	v_cndmask_b32_e64 v34, 0, v34, s[0:1]
	v_readlane_b32 s0, v255, 46
	v_add_f32_e32 v26, v64, v26
	v_readlane_b32 s1, v255, 47
	v_add_f32_e32 v26, v59, v26
	v_mul_f32_e32 v54, 0x3fb8aa3b, v54
	v_cndmask_b32_e64 v35, 0, v27, s[0:1]
	v_sub_f32_e32 v27, v32, v2
	v_sub_f32_e32 v32, v33, v2
	v_cndmask_b32_e64 v58, 0, v58, s[72:73]
	v_add_f32_e32 v26, v57, v26
	v_exp_f32_e32 v54, v54
	v_mul_f32_e32 v52, 0x3fb8aa3b, v52
	v_mul_f32_e32 v32, 0x3fb8aa3b, v32
	v_cndmask_b32_e64 v56, 0, v56, s[68:69]
	v_add_f32_e32 v26, v58, v26
	v_exp_f32_e32 v52, v52
	v_exp_f32_e32 v32, v32
	v_add_f32_e32 v26, v56, v26
	v_mul_f32_e32 v27, 0x3fb8aa3b, v27
	v_add_f32_e32 v26, v55, v26
	v_mul_f32_e32 v50, 0x3fb8aa3b, v50
	v_exp_f32_e32 v27, v27
	v_readlane_b32 s0, v255, 52
	v_cndmask_b32_e64 v54, 0, v54, s[64:65]
	v_add_f32_e32 v26, v53, v26
	v_exp_f32_e32 v50, v50
	v_mul_f32_e32 v48, 0x3fb8aa3b, v48
	v_readlane_b32 s1, v255, 53
	v_cndmask_b32_e64 v52, 0, v52, s[60:61]
	v_add_f32_e32 v26, v54, v26
	v_exp_f32_e32 v48, v48
	v_cndmask_b32_e64 v67, 0, v32, s[0:1]
	v_readlane_b32 s0, v255, 50
	v_add_f32_e32 v26, v52, v26
	v_readlane_b32 s1, v255, 51
	v_add_f32_e32 v26, v51, v26
	v_mul_f32_e32 v46, 0x3fb8aa3b, v46
	v_cndmask_b32_e64 v68, 0, v27, s[0:1]
	v_sub_f32_e32 v27, v30, v2
	v_sub_f32_e32 v30, v31, v2
	v_cndmask_b32_e64 v50, 0, v50, s[58:59]
	v_add_f32_e32 v26, v49, v26
	v_exp_f32_e32 v46, v46
	v_mul_f32_e32 v44, 0x3fb8aa3b, v44
	v_mul_f32_e32 v30, 0x3fb8aa3b, v30
	v_cndmask_b32_e64 v48, 0, v48, s[52:53]
	v_add_f32_e32 v26, v50, v26
	v_exp_f32_e32 v44, v44
	v_exp_f32_e32 v30, v30
	v_add_f32_e32 v26, v48, v26
	v_mul_f32_e32 v27, 0x3fb8aa3b, v27
	v_add_f32_e32 v26, v47, v26
	v_mul_f32_e32 v42, 0x3fb8aa3b, v42
	v_exp_f32_e32 v27, v27
	v_readlane_b32 s0, v255, 24
	v_cndmask_b32_e64 v46, 0, v46, s[48:49]
	v_add_f32_e32 v26, v45, v26
	v_exp_f32_e32 v42, v42
	v_mul_f32_e32 v40, 0x3fb8aa3b, v40
	v_readlane_b32 s1, v255, 25
	v_cndmask_b32_e64 v44, 0, v44, s[44:45]
	v_add_f32_e32 v26, v46, v26
	v_exp_f32_e32 v40, v40
	v_cndmask_b32_e64 v69, 0, v30, s[0:1]
	v_readlane_b32 s0, v255, 22
	v_add_f32_e32 v26, v44, v26
	v_readlane_b32 s1, v255, 23
	v_add_f32_e32 v26, v43, v26
	v_cndmask_b32_e64 v42, 0, v42, s[40:41]
	v_cndmask_b32_e64 v70, 0, v27, s[0:1]
	v_sub_f32_e32 v27, v28, v2
	v_sub_f32_e32 v28, v29, v2
	v_add_f32_e32 v26, v41, v26
	v_mul_f32_e32 v28, 0x3fb8aa3b, v28
	v_cndmask_b32_e64 v40, 0, v40, s[36:37]
	v_add_f32_e32 v26, v42, v26
	v_exp_f32_e32 v28, v28
	v_add_f32_e32 v26, v40, v26
	v_mul_f32_e32 v27, 0x3fb8aa3b, v27
	v_add_f32_e32 v26, v39, v26
	v_exp_f32_e32 v27, v27
	v_readlane_b32 s0, v255, 28
	v_sub_f32_e32 v23, v23, v2
	v_add_f32_e32 v26, v37, v26
	v_readlane_b32 s1, v255, 29
	v_mul_f32_e32 v23, 0x3fb8aa3b, v23
	v_add_f32_e32 v26, v38, v26
	v_cndmask_b32_e64 v71, 0, v28, s[0:1]
	v_readlane_b32 s0, v255, 26
	v_sub_f32_e32 v22, v22, v2
	v_exp_f32_e32 v23, v23
	v_add_f32_e32 v26, v36, v26
	v_readlane_b32 s1, v255, 27
	v_mul_f32_e32 v22, 0x3fb8aa3b, v22
	v_add_f32_e32 v26, v35, v26
	v_cndmask_b32_e64 v72, 0, v27, s[0:1]
	v_exp_f32_e32 v22, v22
	v_readlane_b32 s0, v255, 32
	v_sub_f32_e32 v20, v20, v2
	v_sub_f32_e32 v2, v21, v2
	v_add_f32_e32 v26, v68, v26
	v_readlane_b32 s1, v255, 33
	v_mul_f32_e32 v2, 0x3fb8aa3b, v2
	v_add_f32_e32 v26, v34, v26
	v_cndmask_b32_e64 v73, 0, v23, s[0:1]
	v_readlane_b32 s0, v255, 30
	v_exp_f32_e32 v2, v2
	v_add_f32_e32 v26, v67, v26
	v_readlane_b32 s1, v255, 31
	v_mul_f32_e32 v20, 0x3fb8aa3b, v20
	v_add_f32_e32 v26, v70, v26
	v_cndmask_b32_e64 v74, 0, v22, s[0:1]
	v_exp_f32_e32 v20, v20
	v_readlane_b32 s0, v255, 36
	v_add_f32_e32 v26, v72, v26
	v_readlane_b32 s1, v255, 37
	v_add_f32_e32 v26, v69, v26
	v_add_f32_e32 v26, v71, v26
	v_cndmask_b32_e64 v2, 0, v2, s[0:1]
	v_readlane_b32 s0, v255, 34
	v_readlane_b32 s1, v255, 35
	v_add_f32_e32 v22, v74, v26
	v_bfe_u32 v23, v4, 16, 1
	v_cndmask_b32_e64 v75, 0, v20, s[0:1]
	v_add_f32_e32 v20, v75, v22
	v_add_f32_e32 v20, v73, v20
	v_add_f32_e32 v20, v2, v20
	ds_bpermute_b32 v21, v208, v20
	v_bfe_u32 v22, v3, 16, 1
	v_add3_u32 v3, v3, v22, s33
	v_bfe_u32 v22, v6, 16, 1
	v_add3_u32 v4, v4, v23, s33
	s_waitcnt lgkmcnt(0)
	v_add_f32_e32 v32, v20, v21
	v_bfe_u32 v21, v13, 16, 1
	v_add3_u32 v13, v13, v21, s33
	v_bfe_u32 v21, v0, 16, 1
	v_bfe_u32 v20, v7, 16, 1
	v_bfe_u32 v23, v5, 16, 1
	v_add3_u32 v6, v6, v22, s33
	v_add3_u32 v0, v0, v21, s33
	v_add3_u32 v7, v7, v20, s33
	v_bfe_u32 v20, v1, 16, 1
	v_add3_u32 v5, v5, v23, s33
	v_lshrrev_b32_e32 v0, 16, v0
	v_lshrrev_b32_e32 v6, 16, v6
	v_add3_u32 v1, v1, v20, s33
	v_lshrrev_b32_e32 v5, 16, v5
	v_and_or_b32 v30, v13, s34, v6
	v_and_or_b32 v29, v3, s34, v0
	v_bfe_u32 v0, v8, 16, 1
	v_bfe_u32 v6, v12, 16, 1
	v_lshrrev_b32_e32 v1, 16, v1
	v_and_or_b32 v31, v7, s34, v5
	v_bfe_u32 v3, v15, 16, 1
	v_add3_u32 v0, v8, v0, s33
	v_bfe_u32 v5, v14, 16, 1
	v_bfe_u32 v7, v11, 16, 1
	v_bfe_u32 v8, v10, 16, 1
	v_add3_u32 v6, v12, v6, s33
	v_and_or_b32 v28, v4, s34, v1
	v_bfe_u32 v1, v25, 16, 1
	v_bfe_u32 v4, v24, 16, 1
	v_add3_u32 v3, v15, v3, s33
	v_add3_u32 v8, v10, v8, s33
	v_add3_u32 v7, v11, v7, s33
	v_add3_u32 v5, v14, v5, s33
	v_lshrrev_b32_e32 v6, 16, v6
	v_add3_u32 v4, v24, v4, s33
	v_add3_u32 v1, v25, v1, s33
	v_lshrrev_b32_e32 v5, 16, v5
	v_lshrrev_b32_e32 v7, 16, v7
	v_lshrrev_b32_e32 v8, 16, v8
	v_and_or_b32 v25, v3, s34, v6
	v_bfe_u32 v6, v9, 16, 1
	v_and_or_b32 v27, v0, s34, v8
	v_and_or_b32 v26, v1, s34, v7
	v_and_or_b32 v24, v4, s34, v5
	v_bfe_u32 v3, v60, 16, 1
	v_bfe_u32 v5, v62, 16, 1
	v_bfe_u32 v7, v19, 16, 1
	v_bfe_u32 v8, v18, 16, 1
	v_add3_u32 v6, v9, v6, s33
	v_readlane_b32 s78, v255, 0
	v_bfe_u32 v0, v16, 16, 1
	v_bfe_u32 v1, v63, 16, 1
	v_bfe_u32 v4, v61, 16, 1
	v_add3_u32 v3, v60, v3, s33
	v_add3_u32 v8, v18, v8, s33
	v_add3_u32 v7, v19, v7, s33
	v_add3_u32 v5, v62, v5, s33
	v_lshrrev_b32_e32 v6, 16, v6
	v_readlane_b32 s79, v255, 1
	v_add3_u32 v4, v61, v4, s33
	v_add3_u32 v1, v63, v1, s33
	v_add3_u32 v0, v16, v0, s33
	v_lshrrev_b32_e32 v5, 16, v5
	v_lshrrev_b32_e32 v7, 16, v7
	v_lshrrev_b32_e32 v8, 16, v8
	v_and_or_b32 v21, v3, s34, v6
	v_bfe_u32 v6, v17, 16, 1
	s_load_dword s77, s[78:79], 0xb8
	v_and_or_b32 v23, v0, s34, v8
	v_and_or_b32 v22, v1, s34, v7
	v_and_or_b32 v20, v4, s34, v5
	v_bfe_u32 v3, v64, 16, 1
	v_bfe_u32 v5, v66, 16, 1
	v_bfe_u32 v7, v59, 16, 1
	v_bfe_u32 v8, v58, 16, 1
	v_add3_u32 v6, v17, v6, s33
	s_waitcnt vmcnt(0) lgkmcnt(0)
	s_mov_b32 s0, s35
	v_bfe_u32 v0, v56, 16, 1
	v_bfe_u32 v1, v57, 16, 1
	v_bfe_u32 v4, v65, 16, 1
	v_add3_u32 v3, v64, v3, s33
	v_add3_u32 v8, v58, v8, s33
	v_add3_u32 v7, v59, v7, s33
	v_add3_u32 v5, v66, v5, s33
	v_lshrrev_b32_e32 v6, 16, v6
	s_barrier
	s_ashr_i32 s1, s0, 31
	v_add3_u32 v4, v65, v4, s33
	v_add3_u32 v1, v57, v1, s33
	v_add3_u32 v0, v56, v0, s33
	v_lshrrev_b32_e32 v5, 16, v5
	v_lshrrev_b32_e32 v7, 16, v7
	v_lshrrev_b32_e32 v8, 16, v8
	v_and_or_b32 v17, v3, s34, v6
	v_bfe_u32 v6, v54, 16, 1
	s_lshr_b32 s2, s1, 28
	v_and_or_b32 v19, v0, s34, v8
	v_and_or_b32 v18, v1, s34, v7
	v_and_or_b32 v16, v4, s34, v5
	v_bfe_u32 v3, v52, 16, 1
	v_bfe_u32 v5, v55, 16, 1
	v_bfe_u32 v7, v51, 16, 1
	v_bfe_u32 v8, v50, 16, 1
	v_add3_u32 v6, v54, v6, s33
	s_add_i32 s2, s0, s2
	v_bfe_u32 v0, v48, 16, 1
	v_bfe_u32 v1, v49, 16, 1
	v_bfe_u32 v4, v53, 16, 1
	v_add3_u32 v3, v52, v3, s33
	v_add3_u32 v8, v50, v8, s33
	v_add3_u32 v7, v51, v7, s33
	v_add3_u32 v5, v55, v5, s33
	v_lshrrev_b32_e32 v6, 16, v6
	s_ashr_i32 s2, s2, 4
	v_add3_u32 v4, v53, v4, s33
	v_add3_u32 v1, v49, v1, s33
	v_add3_u32 v0, v48, v0, s33
	v_lshrrev_b32_e32 v5, 16, v5
	v_lshrrev_b32_e32 v7, 16, v7
	v_lshrrev_b32_e32 v8, 16, v8
	v_and_or_b32 v13, v3, s34, v6
	v_bfe_u32 v6, v46, 16, 1
	s_lshr_b32 s3, s2, 30
	v_and_or_b32 v15, v0, s34, v8
	v_and_or_b32 v14, v1, s34, v7
	v_and_or_b32 v12, v4, s34, v5
	v_bfe_u32 v3, v44, 16, 1
	v_bfe_u32 v5, v47, 16, 1
	v_bfe_u32 v7, v43, 16, 1
	v_bfe_u32 v8, v42, 16, 1
	v_add3_u32 v6, v46, v6, s33
	s_add_i32 s3, s2, s3
	v_bfe_u32 v0, v40, 16, 1
	v_bfe_u32 v1, v41, 16, 1
	v_bfe_u32 v4, v45, 16, 1
	v_add3_u32 v3, v44, v3, s33
	v_add3_u32 v8, v42, v8, s33
	v_add3_u32 v7, v43, v7, s33
	v_add3_u32 v5, v47, v5, s33
	v_lshrrev_b32_e32 v6, 16, v6
	s_and_b32 s3, s3, 0xfffffc
	s_lshr_b32 s1, s1, 26
	v_add3_u32 v4, v45, v4, s33
	v_add3_u32 v1, v41, v1, s33
	v_add3_u32 v0, v40, v0, s33
	v_lshrrev_b32_e32 v5, 16, v5
	v_lshrrev_b32_e32 v7, 16, v7
	v_lshrrev_b32_e32 v8, 16, v8
	v_and_or_b32 v9, v3, s34, v6
	v_bfe_u32 v3, v36, 16, 1
	s_sub_i32 s2, s2, s3
	s_add_i32 s3, s0, s1
	v_and_or_b32 v11, v0, s34, v8
	v_and_or_b32 v10, v1, s34, v7
	v_and_or_b32 v8, v4, s34, v5
	v_add3_u32 v3, v36, v3, s33
	v_bfe_u32 v5, v39, 16, 1
	v_bfe_u32 v6, v38, 16, 1
	v_bfe_u32 v7, v35, 16, 1
	v_bfe_u32 v36, v34, 16, 1
	s_lshl_b32 s0, s2, 8
	s_lshl_b32 s2, s3, 2
	v_bfe_u32 v0, v67, 16, 1
	v_add3_u32 v34, v34, v36, s33
	v_add3_u32 v7, v35, v7, s33
	v_add3_u32 v6, v38, v6, s33
	v_add3_u32 v5, v39, v5, s33
	s_and_b32 s2, s2, 0xffffff00
	v_bfe_u32 v4, v37, 16, 1
	v_add3_u32 v0, v67, v0, s33
	v_lshrrev_b32_e32 v35, 16, v5
	v_lshrrev_b32_e32 v5, 16, v6
	v_lshrrev_b32_e32 v6, 16, v7
	v_lshrrev_b32_e32 v7, 16, v34
	s_ashr_i32 s3, s2, 31
	v_bfe_u32 v1, v68, 16, 1
	v_add3_u32 v4, v37, v4, s33
	v_and_or_b32 v7, v0, s34, v7
	v_and_or_b32 v5, v3, s34, v5
	v_bfe_u32 v0, v2, 16, 1
	v_bfe_u32 v3, v71, 16, 1
	s_ashr_i32 s1, s0, 31
	s_lshl_b64 s[2:3], s[2:3], 13
	v_readlane_b32 s4, v255, 15
	v_add3_u32 v1, v68, v1, s33
	v_and_or_b32 v4, v4, s34, v35
	v_add3_u32 v35, v71, v3, s33
	v_add3_u32 v0, v2, v0, s33
	v_bfe_u32 v2, v70, 16, 1
	v_bfe_u32 v3, v69, 16, 1
	v_bfe_u32 v36, v74, 16, 1
	s_add_u32 s2, s4, s2
	v_readlane_b32 s4, v255, 16
	v_readlane_b32 s81, v255, 2
	v_and_or_b32 v6, v1, s34, v6
	v_bfe_u32 v1, v75, 16, 1
	v_bfe_u32 v37, v73, 16, 1
	v_add3_u32 v36, v74, v36, s33
	v_add3_u32 v3, v69, v3, s33
	v_add3_u32 v2, v70, v2, s33
	s_addc_u32 s3, s4, s3
	s_lshl_b64 s[0:1], s[0:1], 1
	v_bfe_u32 v34, v72, 16, 1
	v_add3_u32 v1, v75, v1, s33
	v_add3_u32 v37, v73, v37, s33
	v_lshrrev_b32_e32 v38, 16, v2
	v_lshrrev_b32_e32 v39, 16, v3
	v_lshrrev_b32_e32 v2, 16, v36
	s_add_u32 s0, s2, s0
	s_mov_b32 s2, s81
	v_add3_u32 v34, v72, v34, s33
	v_lshrrev_b32_e32 v3, 16, v37
	v_and_or_b32 v2, v1, s34, v2
	v_and_or_b32 v1, v35, s34, v39
	v_and_or_b32 v3, v0, s34, v3
	v_lshl_add_u32 v35, s2, 1, v108
	v_and_or_b32 v0, v34, s34, v38
	v_max_i32_e32 v34, 0, v35
	v_lshlrev_b32_e32 v35, 1, v35
	v_bitop3_b32 v36, v35, v109, 14 bitop3:0x6c
	v_mov_b32_e32 v35, v89
	s_addc_u32 s1, s3, s1
	v_lshlrev_b64 v[34:35], 13, v[34:35]
	v_lshl_add_u64 v[34:35], s[0:1], 0, v[34:35]
	v_lshlrev_b32_e32 v36, 4, v36
	v_mov_b32_e32 v37, v89
	v_lshl_add_u64 v[34:35], v[34:35], 0, v[36:37]
	s_mov_b64 s[4:5], 0x800
	s_lshl_b32 s3, s2, 10
	v_lshl_add_u64 v[34:35], v[34:35], 0, s[4:5]
	s_add_i32 m0, s3, 0
	s_add_i32 s3, s2, 8
	global_load_lds_dwordx4 v[34:35], off
	v_lshl_add_u32 v35, s3, 1, v108
	v_max_i32_e32 v34, 0, v35
	v_lshlrev_b32_e32 v35, 1, v35
	v_bitop3_b32 v36, v35, v109, 14 bitop3:0x6c
	v_mov_b32_e32 v35, v89
	v_lshlrev_b64 v[34:35], 13, v[34:35]
	v_lshl_add_u64 v[34:35], s[0:1], 0, v[34:35]
	v_lshlrev_b32_e32 v36, 4, v36
	v_lshl_add_u64 v[34:35], v[34:35], 0, v[36:37]
	s_lshl_b32 s3, s3, 10
	v_lshl_add_u64 v[34:35], v[34:35], 0, s[4:5]
	s_add_i32 m0, s3, 0
	s_add_i32 s3, s2, 16
	global_load_lds_dwordx4 v[34:35], off
	v_lshl_add_u32 v35, s3, 1, v108
	v_max_i32_e32 v34, 0, v35
	v_lshlrev_b32_e32 v35, 1, v35
	v_bitop3_b32 v36, v35, v109, 14 bitop3:0x6c
	v_mov_b32_e32 v35, v89
	v_lshlrev_b64 v[34:35], 13, v[34:35]
	v_lshl_add_u64 v[34:35], s[0:1], 0, v[34:35]
	v_lshlrev_b32_e32 v36, 4, v36
	v_lshl_add_u64 v[34:35], v[34:35], 0, v[36:37]
	s_lshl_b32 s3, s3, 10
	v_lshl_add_u64 v[34:35], v[34:35], 0, s[4:5]
	s_add_i32 m0, s3, 0
	s_add_i32 s3, s2, 24
	global_load_lds_dwordx4 v[34:35], off
	v_lshl_add_u32 v35, s3, 1, v108
	v_max_i32_e32 v34, 0, v35
	v_lshlrev_b32_e32 v35, 1, v35
	v_bitop3_b32 v36, v35, v109, 14 bitop3:0x6c
	v_mov_b32_e32 v35, v89
	v_lshlrev_b64 v[34:35], 13, v[34:35]
	v_lshl_add_u64 v[34:35], s[0:1], 0, v[34:35]
	v_lshlrev_b32_e32 v36, 4, v36
	v_lshl_add_u64 v[34:35], v[34:35], 0, v[36:37]
	s_lshl_b32 s3, s3, 10
	v_lshl_add_u64 v[34:35], v[34:35], 0, s[4:5]
	s_add_i32 m0, s3, 0
	s_add_i32 s3, s2, 32
	global_load_lds_dwordx4 v[34:35], off
	v_lshl_add_u32 v35, s3, 1, v108
	v_max_i32_e32 v34, 0, v35
	v_lshlrev_b32_e32 v35, 1, v35
	v_bitop3_b32 v36, v35, v109, 14 bitop3:0x6c
	v_mov_b32_e32 v35, v89
	v_lshlrev_b64 v[34:35], 13, v[34:35]
	v_lshl_add_u64 v[34:35], s[0:1], 0, v[34:35]
	v_lshlrev_b32_e32 v36, 4, v36
	v_lshl_add_u64 v[34:35], v[34:35], 0, v[36:37]
	s_lshl_b32 s3, s3, 10
	v_lshl_add_u64 v[34:35], v[34:35], 0, s[4:5]
	s_add_i32 m0, s3, 0
	s_add_i32 s3, s2, 40
	global_load_lds_dwordx4 v[34:35], off
	v_lshl_add_u32 v35, s3, 1, v108
	v_max_i32_e32 v34, 0, v35
	v_lshlrev_b32_e32 v35, 1, v35
	v_bitop3_b32 v36, v35, v109, 14 bitop3:0x6c
	v_mov_b32_e32 v35, v89
	v_lshlrev_b64 v[34:35], 13, v[34:35]
	v_lshl_add_u64 v[34:35], s[0:1], 0, v[34:35]
	v_lshlrev_b32_e32 v36, 4, v36
	v_lshl_add_u64 v[34:35], v[34:35], 0, v[36:37]
	s_lshl_b32 s3, s3, 10
	v_lshl_add_u64 v[34:35], v[34:35], 0, s[4:5]
	s_add_i32 m0, s3, 0
	s_add_i32 s3, s2, 48
	global_load_lds_dwordx4 v[34:35], off
	v_lshl_add_u32 v35, s3, 1, v108
	v_max_i32_e32 v34, 0, v35
	v_lshlrev_b32_e32 v35, 1, v35
	v_bitop3_b32 v36, v35, v109, 14 bitop3:0x6c
	v_mov_b32_e32 v35, v89
	v_lshlrev_b64 v[34:35], 13, v[34:35]
	v_lshl_add_u64 v[34:35], s[0:1], 0, v[34:35]
	v_lshlrev_b32_e32 v36, 4, v36
	v_lshl_add_u64 v[34:35], v[34:35], 0, v[36:37]
	s_lshl_b32 s3, s3, 10
	v_lshl_add_u64 v[34:35], v[34:35], 0, s[4:5]
	s_add_i32 m0, s3, 0
	s_add_i32 s3, s2, 56
	global_load_lds_dwordx4 v[34:35], off
	v_lshl_add_u32 v35, s3, 1, v108
	v_max_i32_e32 v34, 0, v35
	v_lshlrev_b32_e32 v35, 1, v35
	v_bitop3_b32 v36, v35, v109, 14 bitop3:0x6c
	v_mov_b32_e32 v35, v89
	v_lshlrev_b64 v[34:35], 13, v[34:35]
	v_lshl_add_u64 v[34:35], s[0:1], 0, v[34:35]
	v_lshlrev_b32_e32 v36, 4, v36
	v_lshl_add_u64 v[34:35], v[34:35], 0, v[36:37]
	s_lshl_b32 s3, s3, 10
	v_lshl_add_u64 v[34:35], v[34:35], 0, s[4:5]
	s_add_i32 m0, s3, 0
	s_add_i32 s3, s2, 64
	global_load_lds_dwordx4 v[34:35], off
	v_lshl_add_u32 v35, s3, 1, v108
	v_max_i32_e32 v34, 0, v35
	v_lshlrev_b32_e32 v35, 1, v35
	v_bitop3_b32 v36, v35, v109, 14 bitop3:0x6c
	v_mov_b32_e32 v35, v89
	v_lshlrev_b64 v[34:35], 13, v[34:35]
	v_lshl_add_u64 v[34:35], s[0:1], 0, v[34:35]
	v_lshlrev_b32_e32 v36, 4, v36
	v_lshl_add_u64 v[34:35], v[34:35], 0, v[36:37]
	s_lshl_b32 s3, s3, 10
	v_lshl_add_u64 v[34:35], v[34:35], 0, s[4:5]
	s_add_i32 m0, s3, 0
	s_add_i32 s3, s2, 0x48
	global_load_lds_dwordx4 v[34:35], off
	v_lshl_add_u32 v35, s3, 1, v108
	v_max_i32_e32 v34, 0, v35
	v_lshlrev_b32_e32 v35, 1, v35
	v_bitop3_b32 v36, v35, v109, 14 bitop3:0x6c
	v_mov_b32_e32 v35, v89
	v_lshlrev_b64 v[34:35], 13, v[34:35]
	v_lshl_add_u64 v[34:35], s[0:1], 0, v[34:35]
	v_lshlrev_b32_e32 v36, 4, v36
	v_lshl_add_u64 v[34:35], v[34:35], 0, v[36:37]
	s_lshl_b32 s3, s3, 10
	v_lshl_add_u64 v[34:35], v[34:35], 0, s[4:5]
	s_add_i32 m0, s3, 0
	s_add_i32 s3, s2, 0x50
	global_load_lds_dwordx4 v[34:35], off
	v_lshl_add_u32 v35, s3, 1, v108
	v_max_i32_e32 v34, 0, v35
	v_lshlrev_b32_e32 v35, 1, v35
	v_bitop3_b32 v36, v35, v109, 14 bitop3:0x6c
	v_mov_b32_e32 v35, v89
	v_lshlrev_b64 v[34:35], 13, v[34:35]
	v_lshl_add_u64 v[34:35], s[0:1], 0, v[34:35]
	v_lshlrev_b32_e32 v36, 4, v36
	v_lshl_add_u64 v[34:35], v[34:35], 0, v[36:37]
	s_lshl_b32 s3, s3, 10
	v_lshl_add_u64 v[34:35], v[34:35], 0, s[4:5]
	s_add_i32 m0, s3, 0
	s_add_i32 s3, s2, 0x58
	global_load_lds_dwordx4 v[34:35], off
	v_lshl_add_u32 v35, s3, 1, v108
	v_max_i32_e32 v34, 0, v35
	v_lshlrev_b32_e32 v35, 1, v35
	v_bitop3_b32 v36, v35, v109, 14 bitop3:0x6c
	v_mov_b32_e32 v35, v89
	v_lshlrev_b64 v[34:35], 13, v[34:35]
	v_lshl_add_u64 v[34:35], s[0:1], 0, v[34:35]
	v_lshlrev_b32_e32 v36, 4, v36
	v_lshl_add_u64 v[34:35], v[34:35], 0, v[36:37]
	s_lshl_b32 s3, s3, 10
	v_lshl_add_u64 v[34:35], v[34:35], 0, s[4:5]
	s_add_i32 m0, s3, 0
	s_add_i32 s3, s2, 0x60
	global_load_lds_dwordx4 v[34:35], off
	v_lshl_add_u32 v35, s3, 1, v108
	v_max_i32_e32 v34, 0, v35
	v_lshlrev_b32_e32 v35, 1, v35
	v_bitop3_b32 v36, v35, v109, 14 bitop3:0x6c
	v_mov_b32_e32 v35, v89
	v_lshlrev_b64 v[34:35], 13, v[34:35]
	v_lshl_add_u64 v[34:35], s[0:1], 0, v[34:35]
	v_lshlrev_b32_e32 v36, 4, v36
	v_lshl_add_u64 v[34:35], v[34:35], 0, v[36:37]
	s_lshl_b32 s3, s3, 10
	v_lshl_add_u64 v[34:35], v[34:35], 0, s[4:5]
	s_add_i32 m0, s3, 0
	s_add_i32 s3, s2, 0x68
	global_load_lds_dwordx4 v[34:35], off
	v_lshl_add_u32 v35, s3, 1, v108
	v_max_i32_e32 v34, 0, v35
	v_lshlrev_b32_e32 v35, 1, v35
	v_bitop3_b32 v36, v35, v109, 14 bitop3:0x6c
	v_mov_b32_e32 v35, v89
	v_lshlrev_b64 v[34:35], 13, v[34:35]
	v_lshl_add_u64 v[34:35], s[0:1], 0, v[34:35]
	v_lshlrev_b32_e32 v36, 4, v36
	v_lshl_add_u64 v[34:35], v[34:35], 0, v[36:37]
	s_lshl_b32 s3, s3, 10
	v_lshl_add_u64 v[34:35], v[34:35], 0, s[4:5]
	s_add_i32 m0, s3, 0
	s_add_i32 s3, s2, 0x70
	global_load_lds_dwordx4 v[34:35], off
	v_lshl_add_u32 v35, s3, 1, v108
	v_max_i32_e32 v34, 0, v35
	v_lshlrev_b32_e32 v35, 1, v35
	v_bitop3_b32 v36, v35, v109, 14 bitop3:0x6c
	v_mov_b32_e32 v35, v89
	v_lshlrev_b64 v[34:35], 13, v[34:35]
	v_lshl_add_u64 v[34:35], s[0:1], 0, v[34:35]
	v_lshlrev_b32_e32 v36, 4, v36
	v_lshl_add_u64 v[34:35], v[34:35], 0, v[36:37]
	s_lshl_b32 s3, s3, 10
	v_lshl_add_u64 v[34:35], v[34:35], 0, s[4:5]
	s_add_i32 m0, s3, 0
	s_addk_i32 s2, 0x78
	global_load_lds_dwordx4 v[34:35], off
	v_lshl_add_u32 v35, s2, 1, v108
	v_max_i32_e32 v34, 0, v35
	v_lshlrev_b32_e32 v35, 1, v35
	v_bitop3_b32 v36, v35, v109, 14 bitop3:0x6c
	v_mov_b32_e32 v35, v89
	v_lshlrev_b64 v[34:35], 13, v[34:35]
	v_lshl_add_u64 v[34:35], s[0:1], 0, v[34:35]
	v_lshlrev_b32_e32 v36, 4, v36
	v_lshl_add_u64 v[34:35], v[34:35], 0, v[36:37]
	s_lshl_b32 s0, s2, 10
	v_lshl_add_u64 v[34:35], v[34:35], 0, s[4:5]
	s_add_i32 m0, s0, 0
	s_mov_b32 s0, s35
	global_load_lds_dwordx4 v[34:35], off
	s_waitcnt vmcnt(0) lgkmcnt(0)
	s_barrier
	s_ashr_i32 s1, s0, 31
	s_lshr_b32 s2, s1, 28
	s_add_i32 s2, s0, s2
	ds_bpermute_b32 v33, v105, v32
	s_ashr_i32 s3, s2, 4
	s_lshr_b32 s4, s3, 30
	s_add_i32 s4, s3, s4
	s_and_b32 s4, s4, 0xfffffc
	s_sub_i32 s3, s3, s4
	s_mov_b32 s4, s81
	s_waitcnt lgkmcnt(0)
	v_add_f32_e32 v36, v32, v33
	ds_read_b64_tr_b16 v[32:33], v175 offset:0
	ds_read_b64_tr_b16 v[34:35], v175 offset:0x2000
	ds_read_b64_tr_b16 v[38:39], v176 offset:0
	ds_read_b64_tr_b16 v[40:41], v176 offset:0x2000
	ds_read_b64_tr_b16 v[42:43], v177 offset:0
	ds_read_b64_tr_b16 v[44:45], v177 offset:0x2000
	s_and_b32 s2, s2, 0x1fffff0
	s_lshr_b32 s1, s1, 26
	ds_read_b64_tr_b16 v[46:47], v178 offset:0
	s_sub_i32 s2, s0, s2
	s_add_i32 s0, s0, s1
	ds_read_b64_tr_b16 v[48:49], v178 offset:0x2000
	s_lshl_b32 s0, s0, 5
	s_waitcnt lgkmcnt(0)
	s_and_b32 s0, s0, 0xfffff800
	s_lshl_b32 s1, s2, 7
	s_add_i32 s0, s0, s1
	s_lshl_b32 s2, s3, 8
	s_ashr_i32 s1, s0, 31
	s_ashr_i32 s3, s2, 31
	ds_read_b64_tr_b16 v[50:51], v179 offset:0
	ds_read_b64_tr_b16 v[52:53], v179 offset:0x2000
	ds_read_b64_tr_b16 v[54:55], v180 offset:0
	ds_read_b64_tr_b16 v[56:57], v180 offset:0x2000
	ds_read_b64_tr_b16 v[58:59], v181 offset:0
	ds_read_b64_tr_b16 v[60:61], v181 offset:0x2000
	ds_read_b64_tr_b16 v[62:63], v182 offset:0
	ds_read_b64_tr_b16 v[64:65], v182 offset:0x2000
	s_waitcnt lgkmcnt(0)
	v_mfma_f32_16x16x32_bf16 v[32:35], v[32:35], v[28:31], 0
	v_mfma_f32_16x16x32_bf16 v[38:41], v[38:41], v[28:31], 0
	v_mfma_f32_16x16x32_bf16 v[42:45], v[42:45], v[28:31], 0
	v_mfma_f32_16x16x32_bf16 v[46:49], v[46:49], v[28:31], 0
	ds_read_b64_tr_b16 v[66:67], v183 offset:0
	ds_read_b64_tr_b16 v[68:69], v183 offset:0x2000
	ds_read_b64_tr_b16 v[70:71], v184 offset:0
	ds_read_b64_tr_b16 v[72:73], v184 offset:0x2000
	ds_read_b64_tr_b16 v[74:75], v185 offset:0
	ds_read_b64_tr_b16 v[76:77], v185 offset:0x2000
	ds_read_b64_tr_b16 v[78:79], v186 offset:0
	ds_read_b64_tr_b16 v[80:81], v186 offset:0x2000
	s_waitcnt lgkmcnt(0)
	v_mfma_f32_16x16x32_bf16 v[50:53], v[50:53], v[28:31], 0
	v_mfma_f32_16x16x32_bf16 v[54:57], v[54:57], v[28:31], 0
	v_mfma_f32_16x16x32_bf16 v[58:61], v[58:61], v[28:31], 0
	v_mfma_f32_16x16x32_bf16 v[62:65], v[62:65], v[28:31], 0
	ds_read_b64_tr_b16 v[82:83], v187 offset:0
	ds_read_b64_tr_b16 v[84:85], v187 offset:0x2000
	ds_read_b64_tr_b16 v[208:209], v188 offset:0
	ds_read_b64_tr_b16 v[210:211], v188 offset:0x2000
	ds_read_b64_tr_b16 v[212:213], v189 offset:0
	ds_read_b64_tr_b16 v[214:215], v189 offset:0x2000
	ds_read_b64_tr_b16 v[216:217], v190 offset:0
	ds_read_b64_tr_b16 v[218:219], v190 offset:0x2000
	s_waitcnt lgkmcnt(0)
	v_mfma_f32_16x16x32_bf16 v[66:69], v[66:69], v[28:31], 0
	v_mfma_f32_16x16x32_bf16 v[70:73], v[70:73], v[28:31], 0
	v_mfma_f32_16x16x32_bf16 v[74:77], v[74:77], v[28:31], 0
	v_mfma_f32_16x16x32_bf16 v[78:81], v[78:81], v[28:31], 0
	ds_read_b64_tr_b16 v[220:221], v175 offset:0x4000
	ds_read_b64_tr_b16 v[222:223], v175 offset:0x6000
	ds_read_b64_tr_b16 v[224:225], v176 offset:0x4000
	ds_read_b64_tr_b16 v[226:227], v176 offset:0x6000
	ds_read_b64_tr_b16 v[228:229], v177 offset:0x4000
	ds_read_b64_tr_b16 v[230:231], v177 offset:0x6000
	ds_read_b64_tr_b16 v[232:233], v178 offset:0x4000
	ds_read_b64_tr_b16 v[234:235], v178 offset:0x6000
	s_waitcnt lgkmcnt(0)
	v_mfma_f32_16x16x32_bf16 v[82:85], v[82:85], v[28:31], 0
	v_mfma_f32_16x16x32_bf16 v[208:211], v[208:211], v[28:31], 0
	v_mfma_f32_16x16x32_bf16 v[212:215], v[212:215], v[28:31], 0
	v_mfma_f32_16x16x32_bf16 v[28:31], v[216:219], v[28:31], 0
	ds_read_b64_tr_b16 v[216:217], v179 offset:0x4000
	ds_read_b64_tr_b16 v[218:219], v179 offset:0x6000
	v_mfma_f32_16x16x32_bf16 v[32:35], v[220:223], v[24:27], v[32:35]
	ds_read_b64_tr_b16 v[220:221], v180 offset:0x4000
	ds_read_b64_tr_b16 v[222:223], v180 offset:0x6000
	v_mfma_f32_16x16x32_bf16 v[38:41], v[224:227], v[24:27], v[38:41]
	ds_read_b64_tr_b16 v[224:225], v181 offset:0x4000
	ds_read_b64_tr_b16 v[226:227], v181 offset:0x6000
	v_mfma_f32_16x16x32_bf16 v[42:45], v[228:231], v[24:27], v[42:45]
	ds_read_b64_tr_b16 v[228:229], v182 offset:0x4000
	ds_read_b64_tr_b16 v[230:231], v182 offset:0x6000
	s_waitcnt lgkmcnt(0)
	v_mfma_f32_16x16x32_bf16 v[46:49], v[232:235], v[24:27], v[46:49]
	v_mfma_f32_16x16x32_bf16 v[50:53], v[216:219], v[24:27], v[50:53]
	ds_read_b64_tr_b16 v[216:217], v183 offset:0x4000
	ds_read_b64_tr_b16 v[218:219], v183 offset:0x6000
	v_mfma_f32_16x16x32_bf16 v[54:57], v[220:223], v[24:27], v[54:57]
	ds_read_b64_tr_b16 v[220:221], v184 offset:0x4000
	ds_read_b64_tr_b16 v[222:223], v184 offset:0x6000
	ds_read_b64_tr_b16 v[232:233], v185 offset:0x4000
	ds_read_b64_tr_b16 v[234:235], v185 offset:0x6000
	v_mfma_f32_16x16x32_bf16 v[58:61], v[224:227], v[24:27], v[58:61]
	ds_read_b64_tr_b16 v[224:225], v186 offset:0x4000
	ds_read_b64_tr_b16 v[226:227], v186 offset:0x6000
	s_waitcnt lgkmcnt(0)
	v_mfma_f32_16x16x32_bf16 v[62:65], v[228:231], v[24:27], v[62:65]
	v_mfma_f32_16x16x32_bf16 v[66:69], v[216:219], v[24:27], v[66:69]
	ds_read_b64_tr_b16 v[216:217], v187 offset:0x4000
	ds_read_b64_tr_b16 v[218:219], v187 offset:0x6000
	v_mfma_f32_16x16x32_bf16 v[70:73], v[220:223], v[24:27], v[70:73]
	ds_read_b64_tr_b16 v[220:221], v188 offset:0x4000
	ds_read_b64_tr_b16 v[222:223], v188 offset:0x6000
	ds_read_b64_tr_b16 v[228:229], v189 offset:0x4000
	ds_read_b64_tr_b16 v[230:231], v189 offset:0x6000
	v_mfma_f32_16x16x32_bf16 v[74:77], v[232:235], v[24:27], v[74:77]
	ds_read_b64_tr_b16 v[232:233], v190 offset:0x4000
	ds_read_b64_tr_b16 v[234:235], v190 offset:0x6000
	s_waitcnt lgkmcnt(0)
	v_mfma_f32_16x16x32_bf16 v[78:81], v[224:227], v[24:27], v[78:81]
	v_mfma_f32_16x16x32_bf16 v[82:85], v[216:219], v[24:27], v[82:85]
	ds_read_b64_tr_b16 v[216:217], v175 offset:0x8000
	ds_read_b64_tr_b16 v[218:219], v175 offset:0xa000
	v_mfma_f32_16x16x32_bf16 v[208:211], v[220:223], v[24:27], v[208:211]
	ds_read_b64_tr_b16 v[220:221], v176 offset:0x8000
	ds_read_b64_tr_b16 v[222:223], v176 offset:0xa000
	ds_read_b64_tr_b16 v[224:225], v177 offset:0x8000
	ds_read_b64_tr_b16 v[226:227], v177 offset:0xa000
	v_mfma_f32_16x16x32_bf16 v[212:215], v[228:231], v[24:27], v[212:215]
	ds_read_b64_tr_b16 v[228:229], v178 offset:0x8000
	ds_read_b64_tr_b16 v[230:231], v178 offset:0xa000
	s_waitcnt lgkmcnt(0)
	v_mfma_f32_16x16x32_bf16 v[24:27], v[232:235], v[24:27], v[28:31]
	v_mfma_f32_16x16x32_bf16 v[28:31], v[216:219], v[20:23], v[32:35]
	ds_read_b64_tr_b16 v[32:33], v179 offset:0x8000
	ds_read_b64_tr_b16 v[34:35], v179 offset:0xa000
	ds_read_b64_tr_b16 v[216:217], v180 offset:0x8000
	ds_read_b64_tr_b16 v[218:219], v180 offset:0xa000
	v_mfma_f32_16x16x32_bf16 v[38:41], v[220:223], v[20:23], v[38:41]
	ds_read_b64_tr_b16 v[220:221], v181 offset:0x8000
	ds_read_b64_tr_b16 v[222:223], v181 offset:0xa000
	v_mfma_f32_16x16x32_bf16 v[42:45], v[224:227], v[20:23], v[42:45]
	ds_read_b64_tr_b16 v[224:225], v182 offset:0x8000
	ds_read_b64_tr_b16 v[226:227], v182 offset:0xa000
	s_waitcnt lgkmcnt(0)
	v_mfma_f32_16x16x32_bf16 v[46:49], v[228:231], v[20:23], v[46:49]
	v_mfma_f32_16x16x32_bf16 v[32:35], v[32:35], v[20:23], v[50:53]
	ds_read_b64_tr_b16 v[50:51], v183 offset:0x8000
	ds_read_b64_tr_b16 v[52:53], v183 offset:0xa000
	v_mfma_f32_16x16x32_bf16 v[54:57], v[216:219], v[20:23], v[54:57]
	ds_read_b64_tr_b16 v[216:217], v184 offset:0x8000
	ds_read_b64_tr_b16 v[218:219], v184 offset:0xa000
	ds_read_b64_tr_b16 v[228:229], v185 offset:0x8000
	ds_read_b64_tr_b16 v[230:231], v185 offset:0xa000
	v_mfma_f32_16x16x32_bf16 v[58:61], v[220:223], v[20:23], v[58:61]
	ds_read_b64_tr_b16 v[220:221], v186 offset:0x8000
	ds_read_b64_tr_b16 v[222:223], v186 offset:0xa000
	s_waitcnt lgkmcnt(0)
	v_mfma_f32_16x16x32_bf16 v[62:65], v[224:227], v[20:23], v[62:65]
	v_mfma_f32_16x16x32_bf16 v[50:53], v[50:53], v[20:23], v[66:69]
	ds_read_b64_tr_b16 v[66:67], v187 offset:0x8000
	ds_read_b64_tr_b16 v[68:69], v187 offset:0xa000
	v_mfma_f32_16x16x32_bf16 v[70:73], v[216:219], v[20:23], v[70:73]
	ds_read_b64_tr_b16 v[216:217], v188 offset:0x8000
	ds_read_b64_tr_b16 v[218:219], v188 offset:0xa000
	ds_read_b64_tr_b16 v[224:225], v189 offset:0x8000
	ds_read_b64_tr_b16 v[226:227], v189 offset:0xa000
	v_mfma_f32_16x16x32_bf16 v[74:77], v[228:231], v[20:23], v[74:77]
	ds_read_b64_tr_b16 v[228:229], v190 offset:0x8000
	ds_read_b64_tr_b16 v[230:231], v190 offset:0xa000
	s_waitcnt lgkmcnt(0)
	v_mfma_f32_16x16x32_bf16 v[78:81], v[220:223], v[20:23], v[78:81]
	v_mfma_f32_16x16x32_bf16 v[66:69], v[66:69], v[20:23], v[82:85]
	ds_read_b64_tr_b16 v[82:83], v175 offset:0xc000
	ds_read_b64_tr_b16 v[84:85], v175 offset:0xe000
	v_mfma_f32_16x16x32_bf16 v[208:211], v[216:219], v[20:23], v[208:211]
	ds_read_b64_tr_b16 v[216:217], v176 offset:0xc000
	ds_read_b64_tr_b16 v[218:219], v176 offset:0xe000
	ds_read_b64_tr_b16 v[220:221], v177 offset:0xc000
	ds_read_b64_tr_b16 v[222:223], v177 offset:0xe000
	v_mfma_f32_16x16x32_bf16 v[212:215], v[224:227], v[20:23], v[212:215]
	ds_read_b64_tr_b16 v[224:225], v178 offset:0xc000
	ds_read_b64_tr_b16 v[226:227], v178 offset:0xe000
	s_waitcnt lgkmcnt(0)
	v_mfma_f32_16x16x32_bf16 v[20:23], v[228:231], v[20:23], v[24:27]
	v_mfma_f32_16x16x32_bf16 v[24:27], v[82:85], v[16:19], v[28:31]
	ds_read_b64_tr_b16 v[28:29], v179 offset:0xc000
	ds_read_b64_tr_b16 v[30:31], v179 offset:0xe000
	ds_read_b64_tr_b16 v[82:83], v180 offset:0xc000
	ds_read_b64_tr_b16 v[84:85], v180 offset:0xe000
	v_mfma_f32_16x16x32_bf16 v[38:41], v[216:219], v[16:19], v[38:41]
	ds_read_b64_tr_b16 v[216:217], v181 offset:0xc000
	ds_read_b64_tr_b16 v[218:219], v181 offset:0xe000
	v_mfma_f32_16x16x32_bf16 v[42:45], v[220:223], v[16:19], v[42:45]
	ds_read_b64_tr_b16 v[220:221], v182 offset:0xc000
	ds_read_b64_tr_b16 v[222:223], v182 offset:0xe000
	s_waitcnt lgkmcnt(0)
	v_mfma_f32_16x16x32_bf16 v[46:49], v[224:227], v[16:19], v[46:49]
	v_mfma_f32_16x16x32_bf16 v[28:31], v[28:31], v[16:19], v[32:35]
	ds_read_b64_tr_b16 v[32:33], v183 offset:0xc000
	ds_read_b64_tr_b16 v[34:35], v183 offset:0xe000
	v_mfma_f32_16x16x32_bf16 v[54:57], v[82:85], v[16:19], v[54:57]
	ds_read_b64_tr_b16 v[82:83], v184 offset:0xc000
	ds_read_b64_tr_b16 v[84:85], v184 offset:0xe000
	ds_read_b64_tr_b16 v[224:225], v185 offset:0xc000
	ds_read_b64_tr_b16 v[226:227], v185 offset:0xe000
	v_mfma_f32_16x16x32_bf16 v[58:61], v[216:219], v[16:19], v[58:61]
	ds_read_b64_tr_b16 v[216:217], v186 offset:0xc000
	ds_read_b64_tr_b16 v[218:219], v186 offset:0xe000
	s_waitcnt lgkmcnt(0)
	v_mfma_f32_16x16x32_bf16 v[62:65], v[220:223], v[16:19], v[62:65]
	v_mfma_f32_16x16x32_bf16 v[32:35], v[32:35], v[16:19], v[50:53]
	ds_read_b64_tr_b16 v[50:51], v187 offset:0xc000
	ds_read_b64_tr_b16 v[52:53], v187 offset:0xe000
	v_mfma_f32_16x16x32_bf16 v[70:73], v[82:85], v[16:19], v[70:73]
	ds_read_b64_tr_b16 v[82:83], v188 offset:0xc000
	ds_read_b64_tr_b16 v[84:85], v188 offset:0xe000
	ds_read_b64_tr_b16 v[220:221], v189 offset:0xc000
	ds_read_b64_tr_b16 v[222:223], v189 offset:0xe000
	v_mfma_f32_16x16x32_bf16 v[74:77], v[224:227], v[16:19], v[74:77]
	ds_read_b64_tr_b16 v[224:225], v190 offset:0xc000
	ds_read_b64_tr_b16 v[226:227], v190 offset:0xe000
	s_waitcnt lgkmcnt(0)
	v_mfma_f32_16x16x32_bf16 v[78:81], v[216:219], v[16:19], v[78:81]
	v_mfma_f32_16x16x32_bf16 v[50:53], v[50:53], v[16:19], v[66:69]
	ds_read_b64_tr_b16 v[66:67], v191 offset:0
	ds_read_b64_tr_b16 v[68:69], v191 offset:0x2000
	v_mfma_f32_16x16x32_bf16 v[82:85], v[82:85], v[16:19], v[208:211]
	ds_read_b64_tr_b16 v[208:209], v192 offset:0
	ds_read_b64_tr_b16 v[210:211], v192 offset:0x2000
	ds_read_b64_tr_b16 v[216:217], v193 offset:0
	ds_read_b64_tr_b16 v[218:219], v193 offset:0x2000
	v_mfma_f32_16x16x32_bf16 v[212:215], v[220:223], v[16:19], v[212:215]
	ds_read_b64_tr_b16 v[220:221], v194 offset:0
	ds_read_b64_tr_b16 v[222:223], v194 offset:0x2000
	s_waitcnt lgkmcnt(0)
	v_mfma_f32_16x16x32_bf16 v[16:19], v[224:227], v[16:19], v[20:23]
	v_mfma_f32_16x16x32_bf16 v[20:23], v[66:69], v[12:15], v[24:27]
	ds_read_b64_tr_b16 v[24:25], v195 offset:0
	ds_read_b64_tr_b16 v[26:27], v195 offset:0x2000
	ds_read_b64_tr_b16 v[66:67], v196 offset:0
	ds_read_b64_tr_b16 v[68:69], v196 offset:0x2000
	v_mfma_f32_16x16x32_bf16 v[38:41], v[208:211], v[12:15], v[38:41]
	ds_read_b64_tr_b16 v[208:209], v197 offset:0
	ds_read_b64_tr_b16 v[210:211], v197 offset:0x2000
	v_mfma_f32_16x16x32_bf16 v[42:45], v[216:219], v[12:15], v[42:45]
	ds_read_b64_tr_b16 v[216:217], v198 offset:0
	ds_read_b64_tr_b16 v[218:219], v198 offset:0x2000
	s_waitcnt lgkmcnt(0)
	v_mfma_f32_16x16x32_bf16 v[46:49], v[220:223], v[12:15], v[46:49]
	v_mfma_f32_16x16x32_bf16 v[24:27], v[24:27], v[12:15], v[28:31]
	ds_read_b64_tr_b16 v[28:29], v199 offset:0
	ds_read_b64_tr_b16 v[30:31], v199 offset:0x2000
	v_mfma_f32_16x16x32_bf16 v[54:57], v[66:69], v[12:15], v[54:57]
	ds_read_b64_tr_b16 v[66:67], v200 offset:0
	ds_read_b64_tr_b16 v[68:69], v200 offset:0x2000
	ds_read_b64_tr_b16 v[220:221], v201 offset:0
	ds_read_b64_tr_b16 v[222:223], v201 offset:0x2000
	v_mfma_f32_16x16x32_bf16 v[58:61], v[208:211], v[12:15], v[58:61]
	ds_read_b64_tr_b16 v[208:209], v202 offset:0
	ds_read_b64_tr_b16 v[210:211], v202 offset:0x2000
	s_waitcnt lgkmcnt(0)
	v_mfma_f32_16x16x32_bf16 v[62:65], v[216:219], v[12:15], v[62:65]
	v_mfma_f32_16x16x32_bf16 v[28:31], v[28:31], v[12:15], v[32:35]
	ds_read_b64_tr_b16 v[32:33], v203 offset:0
	ds_read_b64_tr_b16 v[34:35], v203 offset:0x2000
	v_mfma_f32_16x16x32_bf16 v[66:69], v[66:69], v[12:15], v[70:73]
	ds_read_b64_tr_b16 v[70:71], v204 offset:0
	ds_read_b64_tr_b16 v[72:73], v204 offset:0x2000
	ds_read_b64_tr_b16 v[216:217], v205 offset:0
	ds_read_b64_tr_b16 v[218:219], v205 offset:0x2000
	v_mfma_f32_16x16x32_bf16 v[74:77], v[220:223], v[12:15], v[74:77]
	ds_read_b64_tr_b16 v[220:221], v206 offset:0
	ds_read_b64_tr_b16 v[222:223], v206 offset:0x2000
	s_waitcnt lgkmcnt(0)
	v_mfma_f32_16x16x32_bf16 v[78:81], v[208:211], v[12:15], v[78:81]
	v_mfma_f32_16x16x32_bf16 v[32:35], v[32:35], v[12:15], v[50:53]
	ds_read_b64_tr_b16 v[50:51], v191 offset:0x4000
	ds_read_b64_tr_b16 v[52:53], v191 offset:0x6000
	v_mfma_f32_16x16x32_bf16 v[70:73], v[70:73], v[12:15], v[82:85]
	ds_read_b64_tr_b16 v[82:83], v192 offset:0x4000
	ds_read_b64_tr_b16 v[84:85], v192 offset:0x6000
	ds_read_b64_tr_b16 v[208:209], v193 offset:0x4000
	ds_read_b64_tr_b16 v[210:211], v193 offset:0x6000
	v_mfma_f32_16x16x32_bf16 v[212:215], v[216:219], v[12:15], v[212:215]
	ds_read_b64_tr_b16 v[216:217], v194 offset:0x4000
	ds_read_b64_tr_b16 v[218:219], v194 offset:0x6000
	s_waitcnt lgkmcnt(0)
	v_mfma_f32_16x16x32_bf16 v[12:15], v[220:223], v[12:15], v[16:19]
	v_mfma_f32_16x16x32_bf16 v[16:19], v[50:53], v[8:11], v[20:23]
	ds_read_b64_tr_b16 v[20:21], v195 offset:0x4000
	ds_read_b64_tr_b16 v[22:23], v195 offset:0x6000
	ds_read_b64_tr_b16 v[50:51], v196 offset:0x4000
	ds_read_b64_tr_b16 v[52:53], v196 offset:0x6000
	v_mfma_f32_16x16x32_bf16 v[38:41], v[82:85], v[8:11], v[38:41]
	ds_read_b64_tr_b16 v[82:83], v197 offset:0x4000
	ds_read_b64_tr_b16 v[84:85], v197 offset:0x6000
	v_mfma_f32_16x16x32_bf16 v[42:45], v[208:211], v[8:11], v[42:45]
	ds_read_b64_tr_b16 v[208:209], v198 offset:0x4000
	ds_read_b64_tr_b16 v[210:211], v198 offset:0x6000
	s_waitcnt lgkmcnt(0)
	v_mfma_f32_16x16x32_bf16 v[46:49], v[216:219], v[8:11], v[46:49]
	v_mfma_f32_16x16x32_bf16 v[20:23], v[20:23], v[8:11], v[24:27]
	ds_read_b64_tr_b16 v[24:25], v199 offset:0x4000
	ds_read_b64_tr_b16 v[26:27], v199 offset:0x6000
	v_mfma_f32_16x16x32_bf16 v[50:53], v[50:53], v[8:11], v[54:57]
	ds_read_b64_tr_b16 v[54:55], v200 offset:0x4000
	ds_read_b64_tr_b16 v[56:57], v200 offset:0x6000
	ds_read_b64_tr_b16 v[216:217], v201 offset:0x4000
	ds_read_b64_tr_b16 v[218:219], v201 offset:0x6000
	v_mfma_f32_16x16x32_bf16 v[58:61], v[82:85], v[8:11], v[58:61]
	ds_read_b64_tr_b16 v[82:83], v202 offset:0x4000
	ds_read_b64_tr_b16 v[84:85], v202 offset:0x6000
	s_waitcnt lgkmcnt(0)
	v_mfma_f32_16x16x32_bf16 v[62:65], v[208:211], v[8:11], v[62:65]
	v_mfma_f32_16x16x32_bf16 v[24:27], v[24:27], v[8:11], v[28:31]
	ds_read_b64_tr_b16 v[28:29], v203 offset:0x4000
	ds_read_b64_tr_b16 v[30:31], v203 offset:0x6000
	v_mfma_f32_16x16x32_bf16 v[54:57], v[54:57], v[8:11], v[66:69]
	ds_read_b64_tr_b16 v[66:67], v204 offset:0x4000
	ds_read_b64_tr_b16 v[68:69], v204 offset:0x6000
	ds_read_b64_tr_b16 v[208:209], v205 offset:0x4000
	ds_read_b64_tr_b16 v[210:211], v205 offset:0x6000
	v_mfma_f32_16x16x32_bf16 v[74:77], v[216:219], v[8:11], v[74:77]
	ds_read_b64_tr_b16 v[216:217], v206 offset:0x4000
	ds_read_b64_tr_b16 v[218:219], v206 offset:0x6000
	s_waitcnt lgkmcnt(0)
	v_mfma_f32_16x16x32_bf16 v[78:81], v[82:85], v[8:11], v[78:81]
	v_mfma_f32_16x16x32_bf16 v[28:31], v[28:31], v[8:11], v[32:35]
	ds_read_b64_tr_b16 v[32:33], v191 offset:0x8000
	ds_read_b64_tr_b16 v[34:35], v191 offset:0xa000
	v_mfma_f32_16x16x32_bf16 v[66:69], v[66:69], v[8:11], v[70:73]
	ds_read_b64_tr_b16 v[70:71], v192 offset:0x8000
	ds_read_b64_tr_b16 v[72:73], v192 offset:0xa000
	ds_read_b64_tr_b16 v[82:83], v193 offset:0x8000
	ds_read_b64_tr_b16 v[84:85], v193 offset:0xa000
	v_mfma_f32_16x16x32_bf16 v[208:211], v[208:211], v[8:11], v[212:215]
	ds_read_b64_tr_b16 v[212:213], v194 offset:0x8000
	ds_read_b64_tr_b16 v[214:215], v194 offset:0xa000
	s_waitcnt lgkmcnt(0)
	v_mfma_f32_16x16x32_bf16 v[8:11], v[216:219], v[8:11], v[12:15]
	v_mfma_f32_16x16x32_bf16 v[12:15], v[32:35], v[4:7], v[16:19]
	ds_read_b64_tr_b16 v[16:17], v195 offset:0x8000
	ds_read_b64_tr_b16 v[18:19], v195 offset:0xa000
	v_mfma_f32_16x16x32_bf16 v[32:35], v[70:73], v[4:7], v[38:41]
	ds_read_b64_tr_b16 v[38:39], v196 offset:0x8000
	ds_read_b64_tr_b16 v[40:41], v196 offset:0xa000
	ds_read_b64_tr_b16 v[70:71], v197 offset:0x8000
	ds_read_b64_tr_b16 v[72:73], v197 offset:0xa000
	v_mfma_f32_16x16x32_bf16 v[42:45], v[82:85], v[4:7], v[42:45]
	ds_read_b64_tr_b16 v[82:83], v198 offset:0x8000
	ds_read_b64_tr_b16 v[84:85], v198 offset:0xa000
	s_waitcnt lgkmcnt(0)
	v_mfma_f32_16x16x32_bf16 v[46:49], v[212:215], v[4:7], v[46:49]
	v_mfma_f32_16x16x32_bf16 v[16:19], v[16:19], v[4:7], v[20:23]
	ds_read_b64_tr_b16 v[20:21], v199 offset:0x8000
	ds_read_b64_tr_b16 v[22:23], v199 offset:0xa000
	v_mfma_f32_16x16x32_bf16 v[38:41], v[38:41], v[4:7], v[50:53]
	ds_read_b64_tr_b16 v[50:51], v200 offset:0x8000
	ds_read_b64_tr_b16 v[52:53], v200 offset:0xa000
	ds_read_b64_tr_b16 v[212:213], v201 offset:0x8000
	ds_read_b64_tr_b16 v[214:215], v201 offset:0xa000
	v_mfma_f32_16x16x32_bf16 v[58:61], v[70:73], v[4:7], v[58:61]
	ds_read_b64_tr_b16 v[70:71], v202 offset:0x8000
	ds_read_b64_tr_b16 v[72:73], v202 offset:0xa000
	s_waitcnt lgkmcnt(0)
	v_mfma_f32_16x16x32_bf16 v[62:65], v[82:85], v[4:7], v[62:65]
	v_mfma_f32_16x16x32_bf16 v[20:23], v[20:23], v[4:7], v[24:27]
	ds_read_b64_tr_b16 v[24:25], v203 offset:0x8000
	ds_read_b64_tr_b16 v[26:27], v203 offset:0xa000
	v_mfma_f32_16x16x32_bf16 v[50:53], v[50:53], v[4:7], v[54:57]
	ds_read_b64_tr_b16 v[54:55], v204 offset:0x8000
	ds_read_b64_tr_b16 v[56:57], v204 offset:0xa000
	ds_read_b64_tr_b16 v[82:83], v205 offset:0x8000
	ds_read_b64_tr_b16 v[84:85], v205 offset:0xa000
	v_mfma_f32_16x16x32_bf16 v[74:77], v[212:215], v[4:7], v[74:77]
	ds_read_b64_tr_b16 v[212:213], v206 offset:0x8000
	ds_read_b64_tr_b16 v[214:215], v206 offset:0xa000
	s_waitcnt lgkmcnt(0)
	v_mfma_f32_16x16x32_bf16 v[70:73], v[70:73], v[4:7], v[78:81]
	v_mfma_f32_16x16x32_bf16 v[78:81], v[24:27], v[4:7], v[28:31]
	ds_read_b64_tr_b16 v[24:25], v191 offset:0xc000
	ds_read_b64_tr_b16 v[26:27], v191 offset:0xe000
	ds_read_b64_tr_b16 v[28:29], v192 offset:0xc000
	ds_read_b64_tr_b16 v[30:31], v192 offset:0xe000
	v_mfma_f32_16x16x32_bf16 v[54:57], v[54:57], v[4:7], v[66:69]
	ds_read_b64_tr_b16 v[66:67], v193 offset:0xc000
	ds_read_b64_tr_b16 v[68:69], v193 offset:0xe000
	v_mfma_f32_16x16x32_bf16 v[82:85], v[82:85], v[4:7], v[208:211]
	ds_read_b64_tr_b16 v[208:209], v194 offset:0xc000
	ds_read_b64_tr_b16 v[210:211], v194 offset:0xe000
	s_waitcnt lgkmcnt(0)
	v_mfma_f32_16x16x32_bf16 v[212:215], v[212:215], v[4:7], v[8:11]
	ds_read_b64_tr_b16 v[4:5], v195 offset:0xc000
	ds_read_b64_tr_b16 v[6:7], v195 offset:0xe000
	ds_read_b64_tr_b16 v[8:9], v196 offset:0xc000
	ds_read_b64_tr_b16 v[10:11], v196 offset:0xe000
	v_mfma_f32_16x16x32_bf16 v[216:219], v[24:27], v[0:3], v[12:15]
	ds_read_b64_tr_b16 v[12:13], v197 offset:0xc000
	ds_read_b64_tr_b16 v[14:15], v197 offset:0xe000
	ds_read_b64_tr_b16 v[24:25], v198 offset:0xc000
	ds_read_b64_tr_b16 v[26:27], v198 offset:0xe000
	s_waitcnt lgkmcnt(0)
	v_mfma_f32_16x16x32_bf16 v[220:223], v[28:31], v[0:3], v[32:35]
	v_mfma_f32_16x16x32_bf16 v[42:45], v[66:69], v[0:3], v[42:45]
	v_mfma_f32_16x16x32_bf16 v[46:49], v[208:211], v[0:3], v[46:49]
	v_mfma_f32_16x16x32_bf16 v[66:69], v[4:7], v[0:3], v[16:19]
	ds_read_b64_tr_b16 v[4:5], v199 offset:0xc000
	ds_read_b64_tr_b16 v[6:7], v199 offset:0xe000
	v_mfma_f32_16x16x32_bf16 v[208:211], v[8:11], v[0:3], v[38:41]
	ds_read_b64_tr_b16 v[8:9], v200 offset:0xc000
	ds_read_b64_tr_b16 v[10:11], v200 offset:0xe000
	ds_read_b64_tr_b16 v[16:17], v201 offset:0xc000
	ds_read_b64_tr_b16 v[18:19], v201 offset:0xe000
	v_mfma_f32_16x16x32_bf16 v[58:61], v[12:15], v[0:3], v[58:61]
	ds_read_b64_tr_b16 v[12:13], v202 offset:0xc000
	ds_read_b64_tr_b16 v[14:15], v202 offset:0xe000
	s_waitcnt lgkmcnt(0)
	v_mfma_f32_16x16x32_bf16 v[32:35], v[24:27], v[0:3], v[62:65]
	v_mfma_f32_16x16x32_bf16 v[28:31], v[4:7], v[0:3], v[20:23]
	ds_read_b64_tr_b16 v[4:5], v203 offset:0xc000
	ds_read_b64_tr_b16 v[6:7], v203 offset:0xe000
	v_mfma_f32_16x16x32_bf16 v[24:27], v[8:11], v[0:3], v[50:53]
	ds_read_b64_tr_b16 v[8:9], v204 offset:0xc000
	ds_read_b64_tr_b16 v[10:11], v204 offset:0xe000
	ds_read_b64_tr_b16 v[38:39], v205 offset:0xc000
	ds_read_b64_tr_b16 v[40:41], v205 offset:0xe000
	ds_read_b64_tr_b16 v[50:51], v206 offset:0xc000
	ds_read_b64_tr_b16 v[52:53], v206 offset:0xe000
	s_waitcnt lgkmcnt(0)
	v_mfma_f32_16x16x32_bf16 v[20:23], v[16:19], v[0:3], v[74:77]
	v_mfma_f32_16x16x32_bf16 v[12:15], v[12:15], v[0:3], v[70:73]
	v_div_scale_f32 v37, s[4:5], v36, v36, 1.0
	v_rcp_f32_e32 v62, v37
	v_mfma_f32_16x16x32_bf16 v[16:19], v[4:7], v[0:3], v[78:81]
	s_lshl_b64 s[0:1], s[0:1], 13
	v_readlane_b32 s4, v255, 19
	v_fma_f32 v4, -v37, v62, 1.0
	v_fmac_f32_e32 v62, v4, v62
	v_mfma_f32_16x16x32_bf16 v[8:11], v[8:11], v[0:3], v[54:57]
	s_add_u32 s4, s4, s0
	v_readlane_b32 s0, v255, 20
	s_addc_u32 s5, s0, s1
	v_div_scale_f32 v54, vcc, 1.0, v36, 1.0
	v_mul_f32_e32 v55, v54, v62
	v_mfma_f32_16x16x32_bf16 v[4:7], v[38:41], v[0:3], v[82:85]
	v_fma_f32 v38, -v37, v55, v54
	v_fmac_f32_e32 v55, v38, v62
	v_fma_f32 v37, -v37, v55, v54
	v_div_fmas_f32 v37, v37, v62, v55
	v_div_fixup_f32 v38, v37, v36, 1.0
	v_mov_b32_e32 v40, v216
	v_mov_b32_e32 v41, v218
	v_pk_mul_f32 v[40:41], v[38:39], v[40:41] op_sel_hi:[0,1]
	v_mov_b32_e32 v218, v217
	v_mfma_f32_16x16x32_bf16 v[0:3], v[50:53], v[0:3], v[212:215]
	s_lshl_b64 s[0:1], s[2:3], 1
	v_pk_mul_f32 v[50:51], v[38:39], v[218:219] op_sel_hi:[0,1]
	v_and_b32_sdwa v39, v41, v106 dst_sel:DWORD dst_unused:UNUSED_PAD src0_sel:WORD_1 src1_sel:DWORD
	v_and_b32_sdwa v52, v40, v106 dst_sel:DWORD dst_unused:UNUSED_PAD src0_sel:WORD_1 src1_sel:DWORD
	s_add_u32 s0, s4, s0
	v_add3_u32 v40, v40, v52, s33
	v_add3_u32 v39, v41, v39, s33
	v_and_b32_sdwa v41, v51, v106 dst_sel:DWORD dst_unused:UNUSED_PAD src0_sel:WORD_1 src1_sel:DWORD
	v_and_b32_sdwa v52, v50, v106 dst_sel:DWORD dst_unused:UNUSED_PAD src0_sel:WORD_1 src1_sel:DWORD
	s_addc_u32 s1, s5, s1
	v_add3_u32 v41, v51, v41, s33
	v_add3_u32 v50, v50, v52, s33
	v_lshl_add_u64 v[36:37], s[0:1], 0, v[102:103]
	v_mov_b32_e32 v105, v89
	v_and_b32_e32 v41, 0xffff0000, v41
	v_and_b32_e32 v50, 0xffff0000, v50
	v_lshl_add_u64 v[36:37], v[36:37], 0, v[104:105]
	v_or_b32_sdwa v41, v41, v39 dst_sel:DWORD dst_unused:UNUSED_PAD src0_sel:DWORD src1_sel:WORD_1
	v_or_b32_sdwa v40, v50, v40 dst_sel:DWORD dst_unused:UNUSED_PAD src0_sel:DWORD src1_sel:WORD_1
	global_store_dwordx2 v[36:37], v[40:41], off
	v_mov_b32_e32 v40, v220
	v_mov_b32_e32 v41, v222
	v_pk_mul_f32 v[40:41], v[38:39], v[40:41] op_sel_hi:[0,1]
	v_mov_b32_e32 v222, v221
	v_pk_mul_f32 v[50:51], v[38:39], v[222:223] op_sel_hi:[0,1]
	v_and_b32_sdwa v39, v41, v106 dst_sel:DWORD dst_unused:UNUSED_PAD src0_sel:WORD_1 src1_sel:DWORD
	v_and_b32_sdwa v52, v40, v106 dst_sel:DWORD dst_unused:UNUSED_PAD src0_sel:WORD_1 src1_sel:DWORD
	v_add3_u32 v40, v40, v52, s33
	v_add3_u32 v39, v41, v39, s33
	v_and_b32_sdwa v41, v51, v106 dst_sel:DWORD dst_unused:UNUSED_PAD src0_sel:WORD_1 src1_sel:DWORD
	v_and_b32_sdwa v52, v50, v106 dst_sel:DWORD dst_unused:UNUSED_PAD src0_sel:WORD_1 src1_sel:DWORD
	v_add3_u32 v41, v51, v41, s33
	v_add3_u32 v50, v50, v52, s33
	v_and_b32_e32 v41, 0xffff0000, v41
	v_and_b32_e32 v50, 0xffff0000, v50
	v_or_b32_sdwa v41, v41, v39 dst_sel:DWORD dst_unused:UNUSED_PAD src0_sel:DWORD src1_sel:WORD_1
	v_or_b32_sdwa v40, v50, v40 dst_sel:DWORD dst_unused:UNUSED_PAD src0_sel:DWORD src1_sel:WORD_1
	global_store_dwordx2 v[36:37], v[40:41], off offset:32
	v_mov_b32_e32 v40, v42
	v_mov_b32_e32 v41, v44
	v_pk_mul_f32 v[40:41], v[38:39], v[40:41] op_sel_hi:[0,1]
	v_mov_b32_e32 v44, v43
	v_pk_mul_f32 v[42:43], v[38:39], v[44:45] op_sel_hi:[0,1]
	v_and_b32_sdwa v39, v41, v106 dst_sel:DWORD dst_unused:UNUSED_PAD src0_sel:WORD_1 src1_sel:DWORD
	v_and_b32_sdwa v44, v40, v106 dst_sel:DWORD dst_unused:UNUSED_PAD src0_sel:WORD_1 src1_sel:DWORD
	v_add3_u32 v40, v40, v44, s33
	v_add3_u32 v39, v41, v39, s33
	v_and_b32_sdwa v41, v43, v106 dst_sel:DWORD dst_unused:UNUSED_PAD src0_sel:WORD_1 src1_sel:DWORD
	v_and_b32_sdwa v44, v42, v106 dst_sel:DWORD dst_unused:UNUSED_PAD src0_sel:WORD_1 src1_sel:DWORD
	v_add3_u32 v41, v43, v41, s33
	v_add3_u32 v42, v42, v44, s33
	v_and_b32_e32 v41, 0xffff0000, v41
	v_and_b32_e32 v42, 0xffff0000, v42
	v_or_b32_sdwa v41, v41, v39 dst_sel:DWORD dst_unused:UNUSED_PAD src0_sel:DWORD src1_sel:WORD_1
	v_or_b32_sdwa v40, v42, v40 dst_sel:DWORD dst_unused:UNUSED_PAD src0_sel:DWORD src1_sel:WORD_1
	global_store_dwordx2 v[36:37], v[40:41], off offset:64
	v_mov_b32_e32 v40, v46
	v_mov_b32_e32 v41, v48
	v_pk_mul_f32 v[40:41], v[38:39], v[40:41] op_sel_hi:[0,1]
	v_mov_b32_e32 v48, v47
	v_pk_mul_f32 v[42:43], v[38:39], v[48:49] op_sel_hi:[0,1]
	v_and_b32_sdwa v39, v41, v106 dst_sel:DWORD dst_unused:UNUSED_PAD src0_sel:WORD_1 src1_sel:DWORD
	v_and_b32_sdwa v44, v40, v106 dst_sel:DWORD dst_unused:UNUSED_PAD src0_sel:WORD_1 src1_sel:DWORD
	v_add3_u32 v40, v40, v44, s33
	v_add3_u32 v39, v41, v39, s33
	v_and_b32_sdwa v41, v43, v106 dst_sel:DWORD dst_unused:UNUSED_PAD src0_sel:WORD_1 src1_sel:DWORD
	v_and_b32_sdwa v44, v42, v106 dst_sel:DWORD dst_unused:UNUSED_PAD src0_sel:WORD_1 src1_sel:DWORD
	v_add3_u32 v41, v43, v41, s33
	v_add3_u32 v42, v42, v44, s33
	v_and_b32_e32 v41, 0xffff0000, v41
	v_and_b32_e32 v42, 0xffff0000, v42
	v_or_b32_sdwa v41, v41, v39 dst_sel:DWORD dst_unused:UNUSED_PAD src0_sel:DWORD src1_sel:WORD_1
	v_or_b32_sdwa v40, v42, v40 dst_sel:DWORD dst_unused:UNUSED_PAD src0_sel:DWORD src1_sel:WORD_1
	global_store_dwordx2 v[36:37], v[40:41], off offset:96
	v_mov_b32_e32 v40, v66
	v_mov_b32_e32 v41, v68
	v_pk_mul_f32 v[40:41], v[38:39], v[40:41] op_sel_hi:[0,1]
	v_mov_b32_e32 v68, v67
	v_pk_mul_f32 v[42:43], v[38:39], v[68:69] op_sel_hi:[0,1]
	v_and_b32_sdwa v39, v41, v106 dst_sel:DWORD dst_unused:UNUSED_PAD src0_sel:WORD_1 src1_sel:DWORD
	v_and_b32_sdwa v44, v40, v106 dst_sel:DWORD dst_unused:UNUSED_PAD src0_sel:WORD_1 src1_sel:DWORD
	v_add3_u32 v40, v40, v44, s33
	v_add3_u32 v39, v41, v39, s33
	v_and_b32_sdwa v41, v43, v106 dst_sel:DWORD dst_unused:UNUSED_PAD src0_sel:WORD_1 src1_sel:DWORD
	v_and_b32_sdwa v44, v42, v106 dst_sel:DWORD dst_unused:UNUSED_PAD src0_sel:WORD_1 src1_sel:DWORD
	v_add3_u32 v41, v43, v41, s33
	v_add3_u32 v42, v42, v44, s33
	v_and_b32_e32 v41, 0xffff0000, v41
	v_and_b32_e32 v42, 0xffff0000, v42
	v_or_b32_sdwa v41, v41, v39 dst_sel:DWORD dst_unused:UNUSED_PAD src0_sel:DWORD src1_sel:WORD_1
	v_or_b32_sdwa v40, v42, v40 dst_sel:DWORD dst_unused:UNUSED_PAD src0_sel:DWORD src1_sel:WORD_1
	global_store_dwordx2 v[36:37], v[40:41], off offset:128
	v_mov_b32_e32 v40, v208
	v_mov_b32_e32 v41, v210
	v_pk_mul_f32 v[40:41], v[38:39], v[40:41] op_sel_hi:[0,1]
	v_mov_b32_e32 v210, v209
	v_pk_mul_f32 v[42:43], v[38:39], v[210:211] op_sel_hi:[0,1]
	v_and_b32_sdwa v39, v41, v106 dst_sel:DWORD dst_unused:UNUSED_PAD src0_sel:WORD_1 src1_sel:DWORD
	v_and_b32_sdwa v44, v40, v106 dst_sel:DWORD dst_unused:UNUSED_PAD src0_sel:WORD_1 src1_sel:DWORD
	v_add3_u32 v40, v40, v44, s33
	v_add3_u32 v39, v41, v39, s33
	v_and_b32_sdwa v41, v43, v106 dst_sel:DWORD dst_unused:UNUSED_PAD src0_sel:WORD_1 src1_sel:DWORD
	v_and_b32_sdwa v44, v42, v106 dst_sel:DWORD dst_unused:UNUSED_PAD src0_sel:WORD_1 src1_sel:DWORD
	v_add3_u32 v41, v43, v41, s33
	v_add3_u32 v42, v42, v44, s33
	v_and_b32_e32 v41, 0xffff0000, v41
	v_and_b32_e32 v42, 0xffff0000, v42
	v_or_b32_sdwa v41, v41, v39 dst_sel:DWORD dst_unused:UNUSED_PAD src0_sel:DWORD src1_sel:WORD_1
	v_or_b32_sdwa v40, v42, v40 dst_sel:DWORD dst_unused:UNUSED_PAD src0_sel:DWORD src1_sel:WORD_1
	global_store_dwordx2 v[36:37], v[40:41], off offset:160
	v_mov_b32_e32 v40, v58
	v_mov_b32_e32 v41, v60
	v_pk_mul_f32 v[40:41], v[38:39], v[40:41] op_sel_hi:[0,1]
	v_mov_b32_e32 v60, v59
	v_pk_mul_f32 v[42:43], v[38:39], v[60:61] op_sel_hi:[0,1]
	v_and_b32_sdwa v39, v41, v106 dst_sel:DWORD dst_unused:UNUSED_PAD src0_sel:WORD_1 src1_sel:DWORD
	v_and_b32_sdwa v44, v40, v106 dst_sel:DWORD dst_unused:UNUSED_PAD src0_sel:WORD_1 src1_sel:DWORD
	v_add3_u32 v40, v40, v44, s33
	v_add3_u32 v39, v41, v39, s33
	v_and_b32_sdwa v41, v43, v106 dst_sel:DWORD dst_unused:UNUSED_PAD src0_sel:WORD_1 src1_sel:DWORD
	v_and_b32_sdwa v44, v42, v106 dst_sel:DWORD dst_unused:UNUSED_PAD src0_sel:WORD_1 src1_sel:DWORD
	v_add3_u32 v41, v43, v41, s33
	v_add3_u32 v42, v42, v44, s33
	v_and_b32_e32 v41, 0xffff0000, v41
	v_and_b32_e32 v42, 0xffff0000, v42
	v_or_b32_sdwa v41, v41, v39 dst_sel:DWORD dst_unused:UNUSED_PAD src0_sel:DWORD src1_sel:WORD_1
	v_or_b32_sdwa v40, v42, v40 dst_sel:DWORD dst_unused:UNUSED_PAD src0_sel:DWORD src1_sel:WORD_1
	global_store_dwordx2 v[36:37], v[40:41], off offset:192
	v_mov_b32_e32 v40, v32
	v_mov_b32_e32 v41, v34
	v_pk_mul_f32 v[40:41], v[38:39], v[40:41] op_sel_hi:[0,1]
	v_mov_b32_e32 v34, v33
	v_pk_mul_f32 v[32:33], v[38:39], v[34:35] op_sel_hi:[0,1]
	v_and_b32_sdwa v35, v40, v106 dst_sel:DWORD dst_unused:UNUSED_PAD src0_sel:WORD_1 src1_sel:DWORD
	v_add3_u32 v35, v40, v35, s33
	v_and_b32_sdwa v39, v33, v106 dst_sel:DWORD dst_unused:UNUSED_PAD src0_sel:WORD_1 src1_sel:DWORD
	v_and_b32_sdwa v40, v32, v106 dst_sel:DWORD dst_unused:UNUSED_PAD src0_sel:WORD_1 src1_sel:DWORD
	v_and_b32_sdwa v34, v41, v106 dst_sel:DWORD dst_unused:UNUSED_PAD src0_sel:WORD_1 src1_sel:DWORD
	v_add3_u32 v33, v33, v39, s33
	v_add3_u32 v32, v32, v40, s33
	v_add3_u32 v34, v41, v34, s33
	v_and_b32_e32 v33, 0xffff0000, v33
	v_and_b32_e32 v32, 0xffff0000, v32
	v_or_b32_sdwa v33, v33, v34 dst_sel:DWORD dst_unused:UNUSED_PAD src0_sel:DWORD src1_sel:WORD_1
	v_or_b32_sdwa v32, v32, v35 dst_sel:DWORD dst_unused:UNUSED_PAD src0_sel:DWORD src1_sel:WORD_1
	global_store_dwordx2 v[36:37], v[32:33], off offset:224
	v_mov_b32_e32 v32, v28
	v_mov_b32_e32 v33, v30
	v_pk_mul_f32 v[32:33], v[38:39], v[32:33] op_sel_hi:[0,1]
	v_mov_b32_e32 v30, v29
	v_pk_mul_f32 v[28:29], v[38:39], v[30:31] op_sel_hi:[0,1]
	v_and_b32_sdwa v30, v33, v106 dst_sel:DWORD dst_unused:UNUSED_PAD src0_sel:WORD_1 src1_sel:DWORD
	v_and_b32_sdwa v31, v32, v106 dst_sel:DWORD dst_unused:UNUSED_PAD src0_sel:WORD_1 src1_sel:DWORD
	v_add3_u32 v31, v32, v31, s33
	v_add3_u32 v30, v33, v30, s33
	v_and_b32_sdwa v32, v29, v106 dst_sel:DWORD dst_unused:UNUSED_PAD src0_sel:WORD_1 src1_sel:DWORD
	v_and_b32_sdwa v33, v28, v106 dst_sel:DWORD dst_unused:UNUSED_PAD src0_sel:WORD_1 src1_sel:DWORD
	v_add3_u32 v29, v29, v32, s33
	v_add3_u32 v28, v28, v33, s33
	v_and_b32_e32 v29, 0xffff0000, v29
	v_and_b32_e32 v28, 0xffff0000, v28
	v_or_b32_sdwa v29, v29, v30 dst_sel:DWORD dst_unused:UNUSED_PAD src0_sel:DWORD src1_sel:WORD_1
	v_or_b32_sdwa v28, v28, v31 dst_sel:DWORD dst_unused:UNUSED_PAD src0_sel:DWORD src1_sel:WORD_1
	global_store_dwordx2 v[36:37], v[28:29], off offset:256
	v_mov_b32_e32 v28, v24
	v_mov_b32_e32 v29, v26
	v_pk_mul_f32 v[28:29], v[38:39], v[28:29] op_sel_hi:[0,1]
	v_mov_b32_e32 v26, v25
	v_pk_mul_f32 v[24:25], v[38:39], v[26:27] op_sel_hi:[0,1]
	v_and_b32_sdwa v26, v29, v106 dst_sel:DWORD dst_unused:UNUSED_PAD src0_sel:WORD_1 src1_sel:DWORD
	v_and_b32_sdwa v27, v28, v106 dst_sel:DWORD dst_unused:UNUSED_PAD src0_sel:WORD_1 src1_sel:DWORD
	v_add3_u32 v27, v28, v27, s33
	v_add3_u32 v26, v29, v26, s33
	v_and_b32_sdwa v28, v25, v106 dst_sel:DWORD dst_unused:UNUSED_PAD src0_sel:WORD_1 src1_sel:DWORD
	v_and_b32_sdwa v29, v24, v106 dst_sel:DWORD dst_unused:UNUSED_PAD src0_sel:WORD_1 src1_sel:DWORD
	v_add3_u32 v25, v25, v28, s33
	v_add3_u32 v24, v24, v29, s33
	v_and_b32_e32 v25, 0xffff0000, v25
	v_and_b32_e32 v24, 0xffff0000, v24
	v_or_b32_sdwa v25, v25, v26 dst_sel:DWORD dst_unused:UNUSED_PAD src0_sel:DWORD src1_sel:WORD_1
	v_or_b32_sdwa v24, v24, v27 dst_sel:DWORD dst_unused:UNUSED_PAD src0_sel:DWORD src1_sel:WORD_1
	global_store_dwordx2 v[36:37], v[24:25], off offset:288
	v_mov_b32_e32 v24, v20
	v_mov_b32_e32 v25, v22
	v_pk_mul_f32 v[24:25], v[38:39], v[24:25] op_sel_hi:[0,1]
	v_mov_b32_e32 v22, v21
	v_pk_mul_f32 v[20:21], v[38:39], v[22:23] op_sel_hi:[0,1]
	v_and_b32_sdwa v22, v25, v106 dst_sel:DWORD dst_unused:UNUSED_PAD src0_sel:WORD_1 src1_sel:DWORD
	v_and_b32_sdwa v23, v24, v106 dst_sel:DWORD dst_unused:UNUSED_PAD src0_sel:WORD_1 src1_sel:DWORD
	v_add3_u32 v23, v24, v23, s33
	v_add3_u32 v22, v25, v22, s33
	v_and_b32_sdwa v24, v21, v106 dst_sel:DWORD dst_unused:UNUSED_PAD src0_sel:WORD_1 src1_sel:DWORD
	v_and_b32_sdwa v25, v20, v106 dst_sel:DWORD dst_unused:UNUSED_PAD src0_sel:WORD_1 src1_sel:DWORD
	v_add3_u32 v21, v21, v24, s33
	v_add3_u32 v20, v20, v25, s33
	v_and_b32_e32 v21, 0xffff0000, v21
	v_and_b32_e32 v20, 0xffff0000, v20
	v_or_b32_sdwa v21, v21, v22 dst_sel:DWORD dst_unused:UNUSED_PAD src0_sel:DWORD src1_sel:WORD_1
	v_or_b32_sdwa v20, v20, v23 dst_sel:DWORD dst_unused:UNUSED_PAD src0_sel:DWORD src1_sel:WORD_1
	global_store_dwordx2 v[36:37], v[20:21], off offset:320
	v_mov_b32_e32 v20, v12
	v_mov_b32_e32 v21, v14
	v_pk_mul_f32 v[20:21], v[38:39], v[20:21] op_sel_hi:[0,1]
	v_mov_b32_e32 v14, v13
	v_pk_mul_f32 v[12:13], v[38:39], v[14:15] op_sel_hi:[0,1]
	v_and_b32_sdwa v14, v21, v106 dst_sel:DWORD dst_unused:UNUSED_PAD src0_sel:WORD_1 src1_sel:DWORD
	v_and_b32_sdwa v15, v20, v106 dst_sel:DWORD dst_unused:UNUSED_PAD src0_sel:WORD_1 src1_sel:DWORD
	v_add3_u32 v15, v20, v15, s33
	v_add3_u32 v14, v21, v14, s33
	v_and_b32_sdwa v20, v13, v106 dst_sel:DWORD dst_unused:UNUSED_PAD src0_sel:WORD_1 src1_sel:DWORD
	v_and_b32_sdwa v21, v12, v106 dst_sel:DWORD dst_unused:UNUSED_PAD src0_sel:WORD_1 src1_sel:DWORD
	v_add3_u32 v13, v13, v20, s33
	v_add3_u32 v12, v12, v21, s33
	v_and_b32_e32 v13, 0xffff0000, v13
	v_and_b32_e32 v12, 0xffff0000, v12
	v_or_b32_sdwa v13, v13, v14 dst_sel:DWORD dst_unused:UNUSED_PAD src0_sel:DWORD src1_sel:WORD_1
	v_or_b32_sdwa v12, v12, v15 dst_sel:DWORD dst_unused:UNUSED_PAD src0_sel:DWORD src1_sel:WORD_1
	global_store_dwordx2 v[36:37], v[12:13], off offset:352
	v_mov_b32_e32 v12, v16
	v_mov_b32_e32 v13, v18
	v_pk_mul_f32 v[12:13], v[38:39], v[12:13] op_sel_hi:[0,1]
	v_mov_b32_e32 v18, v17
	v_pk_mul_f32 v[14:15], v[38:39], v[18:19] op_sel_hi:[0,1]
	v_and_b32_sdwa v16, v13, v106 dst_sel:DWORD dst_unused:UNUSED_PAD src0_sel:WORD_1 src1_sel:DWORD
	v_and_b32_sdwa v17, v12, v106 dst_sel:DWORD dst_unused:UNUSED_PAD src0_sel:WORD_1 src1_sel:DWORD
	v_add3_u32 v12, v12, v17, s33
	v_add3_u32 v13, v13, v16, s33
	v_and_b32_sdwa v16, v15, v106 dst_sel:DWORD dst_unused:UNUSED_PAD src0_sel:WORD_1 src1_sel:DWORD
	v_and_b32_sdwa v17, v14, v106 dst_sel:DWORD dst_unused:UNUSED_PAD src0_sel:WORD_1 src1_sel:DWORD
	v_add3_u32 v15, v15, v16, s33
	v_add3_u32 v14, v14, v17, s33
	v_and_b32_e32 v15, 0xffff0000, v15
	v_and_b32_e32 v14, 0xffff0000, v14
	v_or_b32_sdwa v13, v15, v13 dst_sel:DWORD dst_unused:UNUSED_PAD src0_sel:DWORD src1_sel:WORD_1
	v_or_b32_sdwa v12, v14, v12 dst_sel:DWORD dst_unused:UNUSED_PAD src0_sel:DWORD src1_sel:WORD_1
	global_store_dwordx2 v[36:37], v[12:13], off offset:384
	v_mov_b32_e32 v12, v8
	v_mov_b32_e32 v13, v10
	v_pk_mul_f32 v[12:13], v[38:39], v[12:13] op_sel_hi:[0,1]
	v_mov_b32_e32 v10, v9
	v_pk_mul_f32 v[8:9], v[38:39], v[10:11] op_sel_hi:[0,1]
	v_and_b32_sdwa v10, v13, v106 dst_sel:DWORD dst_unused:UNUSED_PAD src0_sel:WORD_1 src1_sel:DWORD
	v_and_b32_sdwa v11, v12, v106 dst_sel:DWORD dst_unused:UNUSED_PAD src0_sel:WORD_1 src1_sel:DWORD
	v_add3_u32 v11, v12, v11, s33
	v_add3_u32 v10, v13, v10, s33
	v_and_b32_sdwa v12, v9, v106 dst_sel:DWORD dst_unused:UNUSED_PAD src0_sel:WORD_1 src1_sel:DWORD
	v_and_b32_sdwa v13, v8, v106 dst_sel:DWORD dst_unused:UNUSED_PAD src0_sel:WORD_1 src1_sel:DWORD
	v_add3_u32 v9, v9, v12, s33
	v_add3_u32 v8, v8, v13, s33
	v_and_b32_e32 v9, 0xffff0000, v9
	v_and_b32_e32 v8, 0xffff0000, v8
	v_or_b32_sdwa v9, v9, v10 dst_sel:DWORD dst_unused:UNUSED_PAD src0_sel:DWORD src1_sel:WORD_1
	v_or_b32_sdwa v8, v8, v11 dst_sel:DWORD dst_unused:UNUSED_PAD src0_sel:DWORD src1_sel:WORD_1
	global_store_dwordx2 v[36:37], v[8:9], off offset:416
	v_mov_b32_e32 v8, v4
	v_mov_b32_e32 v9, v6
	v_pk_mul_f32 v[8:9], v[38:39], v[8:9] op_sel_hi:[0,1]
	v_mov_b32_e32 v6, v5
	v_pk_mul_f32 v[4:5], v[38:39], v[6:7] op_sel_hi:[0,1]
	v_and_b32_sdwa v6, v9, v106 dst_sel:DWORD dst_unused:UNUSED_PAD src0_sel:WORD_1 src1_sel:DWORD
	v_and_b32_sdwa v7, v8, v106 dst_sel:DWORD dst_unused:UNUSED_PAD src0_sel:WORD_1 src1_sel:DWORD
	v_add3_u32 v7, v8, v7, s33
	v_add3_u32 v6, v9, v6, s33
	v_and_b32_sdwa v8, v5, v106 dst_sel:DWORD dst_unused:UNUSED_PAD src0_sel:WORD_1 src1_sel:DWORD
	v_and_b32_sdwa v9, v4, v106 dst_sel:DWORD dst_unused:UNUSED_PAD src0_sel:WORD_1 src1_sel:DWORD
	v_add3_u32 v5, v5, v8, s33
	v_add3_u32 v4, v4, v9, s33
	v_and_b32_e32 v5, 0xffff0000, v5
	v_and_b32_e32 v4, 0xffff0000, v4
	v_or_b32_sdwa v5, v5, v6 dst_sel:DWORD dst_unused:UNUSED_PAD src0_sel:DWORD src1_sel:WORD_1
	v_or_b32_sdwa v4, v4, v7 dst_sel:DWORD dst_unused:UNUSED_PAD src0_sel:DWORD src1_sel:WORD_1
	global_store_dwordx2 v[36:37], v[4:5], off offset:448
	v_mov_b32_e32 v4, v0
	v_mov_b32_e32 v5, v2
	v_pk_mul_f32 v[4:5], v[38:39], v[4:5] op_sel_hi:[0,1]
	v_mov_b32_e32 v2, v1
	v_pk_mul_f32 v[0:1], v[38:39], v[2:3] op_sel_hi:[0,1]
	v_and_b32_sdwa v2, v5, v106 dst_sel:DWORD dst_unused:UNUSED_PAD src0_sel:WORD_1 src1_sel:DWORD
	v_and_b32_sdwa v3, v4, v106 dst_sel:DWORD dst_unused:UNUSED_PAD src0_sel:WORD_1 src1_sel:DWORD
	v_add3_u32 v3, v4, v3, s33
	v_add3_u32 v2, v5, v2, s33
	v_and_b32_sdwa v4, v1, v106 dst_sel:DWORD dst_unused:UNUSED_PAD src0_sel:WORD_1 src1_sel:DWORD
	v_and_b32_sdwa v5, v0, v106 dst_sel:DWORD dst_unused:UNUSED_PAD src0_sel:WORD_1 src1_sel:DWORD
	v_add3_u32 v1, v1, v4, s33
	v_add3_u32 v0, v0, v5, s33
	v_and_b32_e32 v1, 0xffff0000, v1
	v_and_b32_e32 v0, 0xffff0000, v0
	v_or_b32_sdwa v1, v1, v2 dst_sel:DWORD dst_unused:UNUSED_PAD src0_sel:DWORD src1_sel:WORD_1
	v_or_b32_sdwa v0, v0, v3 dst_sel:DWORD dst_unused:UNUSED_PAD src0_sel:DWORD src1_sel:WORD_1
	global_store_dwordx2 v[36:37], v[0:1], off offset:480
	s_waitcnt vmcnt(0) lgkmcnt(0)
	s_barrier
	s_add_i32 s35, s35, s77
	s_cmpk_gt_i32 s35, 0x1ff
	s_cbranch_scc0 .LBB0_371
	s_waitcnt vmcnt(0) lgkmcnt(0)
	s_barrier
	v_readlane_b32 s82, v255, 13
	v_readlane_b32 s84, v255, 11
	v_readlane_b32 s88, v255, 8
	v_readlane_b32 s90, v255, 5
	v_readlane_b32 s80, v255, 21
	v_readlane_b32 s83, v255, 14
	v_readlane_b32 s85, v255, 12
	v_readlane_b32 s86, v255, 10
	v_readlane_b32 s89, v255, 9
	v_readlane_b32 s87, v255, 7
	v_readlane_b32 s91, v255, 6
	v_readlane_b32 s92, v255, 4
	v_readlane_b32 s93, v255, 3

.LBB0_1108:
	s_mov_b32 s0, s35
	s_ashr_i32 s1, s0, 31
	s_lshr_b32 s2, s1, 28
	s_add_i32 s2, s0, s2
	s_ashr_i32 s3, s2, 4
	s_lshr_b32 s4, s3, 30
	s_and_b32 s2, s2, 0x1fffff0
	s_add_i32 s4, s3, s4
	s_lshr_b32 s1, s1, 26
	s_sub_i32 s2, s0, s2
	s_and_b32 s4, s4, 0xfffffc
	s_add_i32 s0, s0, s1
	s_sub_i32 s3, s3, s4
	s_ashr_i32 s4, s0, 6
	s_lshl_b32 s0, s4, 11
	s_lshl_b32 s1, s2, 7
	s_lshl_b32 s2, s4, 8
	s_add_i32 s5, s0, s1
	s_lshl_b32 s0, s3, 8
	s_ashr_i32 s3, s2, 31
	s_ashr_i32 s1, s0, 31
	s_lshl_b64 s[2:3], s[2:3], 13
	v_readlane_b32 s4, v255, 15
	s_add_u32 s2, s4, s2
	v_readlane_b32 s4, v255, 16
	s_addc_u32 s3, s4, s3
	s_lshl_b64 s[0:1], s[0:1], 1
	s_mov_b32 s4, s81
	s_add_u32 s2, s2, s0
	s_addc_u32 s3, s3, s1
	s_lshl_b32 s4, s4, 10
	s_add_i32 s4, s4, 0
	v_lshl_add_u64 v[0:1], s[2:3], 0, v[92:93]
	v_lshl_add_u64 v[0:1], v[0:1], 0, v[104:105]
	s_mov_b32 m0, s4
	v_lshl_add_u64 v[2:3], s[2:3], 0, v[94:95]
	global_load_lds_dwordx4 v[0:1], off
	v_lshl_add_u64 v[2:3], v[2:3], 0, v[106:107]
	s_add_i32 m0, s4, 0x2000
	s_mov_b64 s[6:7], 0x80
	global_load_lds_dwordx4 v[2:3], off
	s_add_i32 m0, s4, 0x4000
	v_lshl_add_u64 v[4:5], v[0:1], 0, s[6:7]
	global_load_lds_dwordx4 v[4:5], off
	v_lshl_add_u64 v[4:5], v[2:3], 0, s[6:7]
	s_add_i32 m0, s4, 0x6000
	s_mov_b64 s[8:9], 0x100
	global_load_lds_dwordx4 v[4:5], off
	s_add_i32 m0, s4, 0x8000
	v_lshl_add_u64 v[4:5], v[0:1], 0, s[8:9]
	global_load_lds_dwordx4 v[4:5], off
	v_lshl_add_u64 v[4:5], v[2:3], 0, s[8:9]
	s_add_i32 m0, s4, 0xa000
	s_mov_b64 s[10:11], 0x180
	global_load_lds_dwordx4 v[4:5], off
	s_add_i32 m0, s4, 0xc000
	v_lshl_add_u64 v[0:1], v[0:1], 0, s[10:11]
	global_load_lds_dwordx4 v[0:1], off
	v_lshl_add_u64 v[0:1], v[2:3], 0, s[10:11]
	s_add_i32 m0, s4, 0xe000
	v_lshl_add_u64 v[2:3], s[2:3], 0, v[98:99]
	global_load_lds_dwordx4 v[0:1], off
	v_lshl_add_u64 v[0:1], s[2:3], 0, v[96:97]
	s_add_i32 m0, s4, 0x10000
	v_lshl_add_u64 v[0:1], v[0:1], 0, v[104:105]
	global_load_lds_dwordx4 v[0:1], off
	v_lshl_add_u64 v[2:3], v[2:3], 0, v[106:107]
	s_add_i32 m0, s4, 0x12000
	v_lshl_add_u64 v[4:5], v[0:1], 0, s[6:7]
	global_load_lds_dwordx4 v[2:3], off
	s_add_i32 m0, s4, 0x14000
	s_mul_hi_i32 s2, s5, 0x5000
	global_load_lds_dwordx4 v[4:5], off
	v_lshl_add_u64 v[4:5], v[2:3], 0, s[6:7]
	s_add_i32 m0, s4, 0x16000
	s_mulk_i32 s5, 0x5000
	global_load_lds_dwordx4 v[4:5], off
	s_add_i32 m0, s4, 0x18000
	v_lshl_add_u64 v[4:5], v[0:1], 0, s[8:9]
	global_load_lds_dwordx4 v[4:5], off
	v_lshl_add_u64 v[4:5], v[2:3], 0, s[8:9]
	s_add_i32 m0, s4, 0x1a000
	v_lshl_add_u64 v[0:1], v[0:1], 0, s[10:11]
	global_load_lds_dwordx4 v[4:5], off
	s_add_i32 m0, s4, 0x1c000
	v_readlane_b32 s3, v255, 17
	global_load_lds_dwordx4 v[0:1], off
	s_add_i32 m0, s4, 0x1e000
	s_add_u32 s3, s3, s5
	v_readlane_b32 s4, v255, 18
	s_addc_u32 s2, s4, s2
	s_add_u32 s0, s3, s0
	v_lshl_add_u64 v[0:1], v[2:3], 0, s[10:11]
	s_addc_u32 s1, s2, s1
	global_load_lds_dwordx4 v[0:1], off
	v_lshl_add_u64 v[0:1], s[0:1], 0, v[102:103]
	v_lshl_add_u64 v[0:1], v[0:1], 0, v[90:91]
	global_load_dwordx4 v[52:55], v[0:1], off
	global_load_dwordx4 v[48:51], v[0:1], off offset:64
	global_load_dwordx4 v[44:47], v[0:1], off offset:128
	global_load_dwordx4 v[40:43], v[0:1], off offset:192
	global_load_dwordx4 v[36:39], v[0:1], off offset:256
	global_load_dwordx4 v[32:35], v[0:1], off offset:320
	global_load_dwordx4 v[28:31], v[0:1], off offset:384
	global_load_dwordx4 v[20:23], v[0:1], off offset:448
	s_mov_b32 s0, s35
	s_waitcnt vmcnt(0) lgkmcnt(0)
	s_waitcnt vmcnt(0)
	s_barrier
	s_mov_b32 s0, s81
	ds_read_b128 v[220:223], v111
	ds_read_b128 v[224:227], v111 offset:1024
	ds_read_b128 v[228:231], v111 offset:16384
	ds_read_b128 v[232:235], v111 offset:17408
	ds_read_b128 v[236:239], v111 offset:32768
	ds_read_b128 v[240:243], v111 offset:33792
	ds_read_b128 v[244:247], v111 offset:49152
	ds_read_b128 v[248:251], v111 offset:50176
	s_waitcnt lgkmcnt(7)
	v_mfma_f32_16x16x32_bf16 v[0:3], v[220:223], v[52:55], 0
	ds_read_b128 v[220:223], v111 offset:2048
	s_waitcnt lgkmcnt(7)
	v_mfma_f32_16x16x32_bf16 v[0:3], v[224:227], v[48:51], v[0:3]
	ds_read_b128 v[224:227], v111 offset:3072
	s_waitcnt lgkmcnt(7)
	v_mfma_f32_16x16x32_bf16 v[0:3], v[228:231], v[44:47], v[0:3]
	ds_read_b128 v[228:231], v111 offset:18432
	s_waitcnt lgkmcnt(7)
	v_mfma_f32_16x16x32_bf16 v[0:3], v[232:235], v[40:43], v[0:3]
	ds_read_b128 v[232:235], v111 offset:19456
	s_waitcnt lgkmcnt(7)
	v_mfma_f32_16x16x32_bf16 v[0:3], v[236:239], v[36:39], v[0:3]
	ds_read_b128 v[236:239], v111 offset:34816
	s_waitcnt lgkmcnt(7)
	v_mfma_f32_16x16x32_bf16 v[0:3], v[240:243], v[32:35], v[0:3]
	ds_read_b128 v[240:243], v111 offset:35840
	s_waitcnt lgkmcnt(7)
	v_mfma_f32_16x16x32_bf16 v[0:3], v[244:247], v[28:31], v[0:3]
	ds_read_b128 v[244:247], v111 offset:51200
	s_waitcnt lgkmcnt(7)
	v_mfma_f32_16x16x32_bf16 v[0:3], v[248:251], v[20:23], v[0:3]
	ds_read_b128 v[248:251], v111 offset:52224
	s_waitcnt lgkmcnt(7)
	v_mfma_f32_16x16x32_bf16 v[4:7], v[220:223], v[52:55], 0
	ds_read_b128 v[220:223], v111 offset:4096
	s_waitcnt lgkmcnt(7)
	v_mfma_f32_16x16x32_bf16 v[4:7], v[224:227], v[48:51], v[4:7]
	ds_read_b128 v[224:227], v111 offset:5120
	s_waitcnt lgkmcnt(7)
	v_mfma_f32_16x16x32_bf16 v[4:7], v[228:231], v[44:47], v[4:7]
	ds_read_b128 v[228:231], v111 offset:20480
	s_waitcnt lgkmcnt(7)
	v_mfma_f32_16x16x32_bf16 v[4:7], v[232:235], v[40:43], v[4:7]
	ds_read_b128 v[232:235], v111 offset:21504
	s_waitcnt lgkmcnt(7)
	v_mfma_f32_16x16x32_bf16 v[4:7], v[236:239], v[36:39], v[4:7]
	ds_read_b128 v[236:239], v111 offset:36864
	s_waitcnt lgkmcnt(7)
	v_mfma_f32_16x16x32_bf16 v[4:7], v[240:243], v[32:35], v[4:7]
	ds_read_b128 v[240:243], v111 offset:37888
	s_waitcnt lgkmcnt(7)
	v_mfma_f32_16x16x32_bf16 v[4:7], v[244:247], v[28:31], v[4:7]
	ds_read_b128 v[244:247], v111 offset:53248
	s_waitcnt lgkmcnt(7)
	v_mfma_f32_16x16x32_bf16 v[4:7], v[248:251], v[20:23], v[4:7]
	ds_read_b128 v[248:251], v111 offset:54272
	s_waitcnt lgkmcnt(7)
	v_mfma_f32_16x16x32_bf16 v[8:11], v[220:223], v[52:55], 0
	ds_read_b128 v[220:223], v111 offset:6144
	s_waitcnt lgkmcnt(7)
	v_mfma_f32_16x16x32_bf16 v[8:11], v[224:227], v[48:51], v[8:11]
	ds_read_b128 v[224:227], v111 offset:7168
	s_waitcnt lgkmcnt(7)
	v_mfma_f32_16x16x32_bf16 v[8:11], v[228:231], v[44:47], v[8:11]
	ds_read_b128 v[228:231], v111 offset:22528
	s_waitcnt lgkmcnt(7)
	v_mfma_f32_16x16x32_bf16 v[8:11], v[232:235], v[40:43], v[8:11]
	ds_read_b128 v[232:235], v111 offset:23552
	s_waitcnt lgkmcnt(7)
	v_mfma_f32_16x16x32_bf16 v[8:11], v[236:239], v[36:39], v[8:11]
	ds_read_b128 v[236:239], v111 offset:38912
	s_waitcnt lgkmcnt(7)
	v_mfma_f32_16x16x32_bf16 v[8:11], v[240:243], v[32:35], v[8:11]
	ds_read_b128 v[240:243], v111 offset:39936
	s_waitcnt lgkmcnt(7)
	v_mfma_f32_16x16x32_bf16 v[8:11], v[244:247], v[28:31], v[8:11]
	ds_read_b128 v[244:247], v111 offset:55296
	s_waitcnt lgkmcnt(7)
	v_mfma_f32_16x16x32_bf16 v[8:11], v[248:251], v[20:23], v[8:11]
	ds_read_b128 v[248:251], v111 offset:56320
	s_waitcnt lgkmcnt(7)
	v_mfma_f32_16x16x32_bf16 v[12:15], v[220:223], v[52:55], 0
	ds_read_b128 v[220:223], v111 offset:8192
	s_waitcnt lgkmcnt(7)
	v_mfma_f32_16x16x32_bf16 v[12:15], v[224:227], v[48:51], v[12:15]
	ds_read_b128 v[224:227], v111 offset:9216
	s_waitcnt lgkmcnt(7)
	v_mfma_f32_16x16x32_bf16 v[12:15], v[228:231], v[44:47], v[12:15]
	ds_read_b128 v[228:231], v111 offset:24576
	s_waitcnt lgkmcnt(7)
	v_mfma_f32_16x16x32_bf16 v[12:15], v[232:235], v[40:43], v[12:15]
	ds_read_b128 v[232:235], v111 offset:25600
	s_waitcnt lgkmcnt(7)
	v_mfma_f32_16x16x32_bf16 v[12:15], v[236:239], v[36:39], v[12:15]
	ds_read_b128 v[236:239], v111 offset:40960
	s_waitcnt lgkmcnt(7)
	v_mfma_f32_16x16x32_bf16 v[12:15], v[240:243], v[32:35], v[12:15]
	ds_read_b128 v[240:243], v111 offset:41984
	s_waitcnt lgkmcnt(7)
	v_mfma_f32_16x16x32_bf16 v[12:15], v[244:247], v[28:31], v[12:15]
	ds_read_b128 v[244:247], v111 offset:57344
	s_waitcnt lgkmcnt(7)
	v_mfma_f32_16x16x32_bf16 v[12:15], v[248:251], v[20:23], v[12:15]
	ds_read_b128 v[248:251], v111 offset:58368
	s_waitcnt lgkmcnt(7)
	v_mfma_f32_16x16x32_bf16 v[16:19], v[220:223], v[52:55], 0
	ds_read_b128 v[220:223], v111 offset:10240
	s_waitcnt lgkmcnt(7)
	v_mfma_f32_16x16x32_bf16 v[16:19], v[224:227], v[48:51], v[16:19]
	ds_read_b128 v[224:227], v111 offset:11264
	s_waitcnt lgkmcnt(7)
	v_mfma_f32_16x16x32_bf16 v[16:19], v[228:231], v[44:47], v[16:19]
	ds_read_b128 v[228:231], v111 offset:26624
	s_waitcnt lgkmcnt(7)
	v_mfma_f32_16x16x32_bf16 v[16:19], v[232:235], v[40:43], v[16:19]
	ds_read_b128 v[232:235], v111 offset:27648
	s_waitcnt lgkmcnt(7)
	v_mfma_f32_16x16x32_bf16 v[16:19], v[236:239], v[36:39], v[16:19]
	ds_read_b128 v[236:239], v111 offset:43008
	s_waitcnt lgkmcnt(7)
	v_mfma_f32_16x16x32_bf16 v[16:19], v[240:243], v[32:35], v[16:19]
	ds_read_b128 v[240:243], v111 offset:44032
	s_waitcnt lgkmcnt(7)
	v_mfma_f32_16x16x32_bf16 v[16:19], v[244:247], v[28:31], v[16:19]
	ds_read_b128 v[244:247], v111 offset:59392
	s_waitcnt lgkmcnt(7)
	v_mfma_f32_16x16x32_bf16 v[16:19], v[248:251], v[20:23], v[16:19]
	ds_read_b128 v[248:251], v111 offset:60416
	s_waitcnt lgkmcnt(7)
	v_mfma_f32_16x16x32_bf16 v[24:27], v[220:223], v[52:55], 0
	ds_read_b128 v[220:223], v111 offset:12288
	s_waitcnt lgkmcnt(7)
	v_mfma_f32_16x16x32_bf16 v[24:27], v[224:227], v[48:51], v[24:27]
	ds_read_b128 v[224:227], v111 offset:13312
	s_waitcnt lgkmcnt(7)
	v_mfma_f32_16x16x32_bf16 v[24:27], v[228:231], v[44:47], v[24:27]
	ds_read_b128 v[228:231], v111 offset:28672
	s_waitcnt lgkmcnt(7)
	v_mfma_f32_16x16x32_bf16 v[24:27], v[232:235], v[40:43], v[24:27]
	ds_read_b128 v[232:235], v111 offset:29696
	s_waitcnt lgkmcnt(7)
	v_mfma_f32_16x16x32_bf16 v[24:27], v[236:239], v[36:39], v[24:27]
	ds_read_b128 v[236:239], v111 offset:45056
	s_waitcnt lgkmcnt(7)
	v_mfma_f32_16x16x32_bf16 v[24:27], v[240:243], v[32:35], v[24:27]
	ds_read_b128 v[240:243], v111 offset:46080
	s_waitcnt lgkmcnt(7)
	v_mfma_f32_16x16x32_bf16 v[24:27], v[244:247], v[28:31], v[24:27]
	ds_read_b128 v[244:247], v111 offset:61440
	s_waitcnt lgkmcnt(7)
	v_mfma_f32_16x16x32_bf16 v[24:27], v[248:251], v[20:23], v[24:27]
	ds_read_b128 v[248:251], v111 offset:62464
	s_waitcnt lgkmcnt(7)
	v_mfma_f32_16x16x32_bf16 v[56:59], v[220:223], v[52:55], 0
	ds_read_b128 v[220:223], v111 offset:14336
	s_waitcnt lgkmcnt(7)
	v_mfma_f32_16x16x32_bf16 v[56:59], v[224:227], v[48:51], v[56:59]
	ds_read_b128 v[224:227], v111 offset:15360
	s_waitcnt lgkmcnt(7)
	v_mfma_f32_16x16x32_bf16 v[56:59], v[228:231], v[44:47], v[56:59]
	ds_read_b128 v[228:231], v111 offset:30720
	s_waitcnt lgkmcnt(7)
	v_mfma_f32_16x16x32_bf16 v[56:59], v[232:235], v[40:43], v[56:59]
	ds_read_b128 v[232:235], v111 offset:31744
	s_waitcnt lgkmcnt(7)
	v_mfma_f32_16x16x32_bf16 v[56:59], v[236:239], v[36:39], v[56:59]
	ds_read_b128 v[236:239], v111 offset:47104
	s_waitcnt lgkmcnt(7)
	v_mfma_f32_16x16x32_bf16 v[56:59], v[240:243], v[32:35], v[56:59]
	ds_read_b128 v[240:243], v111 offset:48128
	s_waitcnt lgkmcnt(7)
	v_mfma_f32_16x16x32_bf16 v[56:59], v[244:247], v[28:31], v[56:59]
	ds_read_b128 v[244:247], v111 offset:63488
	s_waitcnt lgkmcnt(7)
	v_mfma_f32_16x16x32_bf16 v[56:59], v[248:251], v[20:23], v[56:59]
	ds_read_b128 v[248:251], v111 offset:64512
	s_waitcnt lgkmcnt(7)
	v_mfma_f32_16x16x32_bf16 v[60:63], v[220:223], v[52:55], 0
	ds_read_b128 v[220:223], v112
	s_waitcnt lgkmcnt(7)
	v_mfma_f32_16x16x32_bf16 v[60:63], v[224:227], v[48:51], v[60:63]
	ds_read_b128 v[224:227], v113
	s_waitcnt lgkmcnt(7)
	v_mfma_f32_16x16x32_bf16 v[60:63], v[228:231], v[44:47], v[60:63]
	ds_read_b128 v[228:231], v114
	s_waitcnt lgkmcnt(7)
	v_mfma_f32_16x16x32_bf16 v[60:63], v[232:235], v[40:43], v[60:63]
	ds_read_b128 v[232:235], v115
	s_waitcnt lgkmcnt(7)
	v_mfma_f32_16x16x32_bf16 v[60:63], v[236:239], v[36:39], v[60:63]
	ds_read_b128 v[236:239], v116
	s_waitcnt lgkmcnt(7)
	v_mfma_f32_16x16x32_bf16 v[60:63], v[240:243], v[32:35], v[60:63]
	ds_read_b128 v[240:243], v117
	s_waitcnt lgkmcnt(7)
	v_mfma_f32_16x16x32_bf16 v[60:63], v[244:247], v[28:31], v[60:63]
	ds_read_b128 v[244:247], v118
	s_waitcnt lgkmcnt(7)
	v_mfma_f32_16x16x32_bf16 v[60:63], v[248:251], v[20:23], v[60:63]
	ds_read_b128 v[248:251], v119
	s_waitcnt lgkmcnt(7)
	v_mfma_f32_16x16x32_bf16 v[64:67], v[220:223], v[52:55], 0
	ds_read_b128 v[220:223], v120
	s_waitcnt lgkmcnt(7)
	v_mfma_f32_16x16x32_bf16 v[64:67], v[224:227], v[48:51], v[64:67]
	ds_read_b128 v[224:227], v121
	s_waitcnt lgkmcnt(7)
	v_mfma_f32_16x16x32_bf16 v[64:67], v[228:231], v[44:47], v[64:67]
	ds_read_b128 v[228:231], v122
	s_waitcnt lgkmcnt(7)
	v_mfma_f32_16x16x32_bf16 v[64:67], v[232:235], v[40:43], v[64:67]
	ds_read_b128 v[232:235], v123
	s_waitcnt lgkmcnt(7)
	v_mfma_f32_16x16x32_bf16 v[64:67], v[236:239], v[36:39], v[64:67]
	ds_read_b128 v[236:239], v124
	s_waitcnt lgkmcnt(7)
	v_mfma_f32_16x16x32_bf16 v[64:67], v[240:243], v[32:35], v[64:67]
	ds_read_b128 v[240:243], v125
	s_waitcnt lgkmcnt(7)
	v_mfma_f32_16x16x32_bf16 v[64:67], v[244:247], v[28:31], v[64:67]
	ds_read_b128 v[244:247], v126
	s_waitcnt lgkmcnt(7)
	v_mfma_f32_16x16x32_bf16 v[64:67], v[248:251], v[20:23], v[64:67]
	ds_read_b128 v[248:251], v127
	s_waitcnt lgkmcnt(7)
	v_mfma_f32_16x16x32_bf16 v[68:71], v[220:223], v[52:55], 0
	ds_read_b128 v[220:223], v128
	s_waitcnt lgkmcnt(7)
	v_mfma_f32_16x16x32_bf16 v[68:71], v[224:227], v[48:51], v[68:71]
	ds_read_b128 v[224:227], v129
	s_waitcnt lgkmcnt(7)
	v_mfma_f32_16x16x32_bf16 v[68:71], v[228:231], v[44:47], v[68:71]
	ds_read_b128 v[228:231], v130
	s_waitcnt lgkmcnt(7)
	v_mfma_f32_16x16x32_bf16 v[68:71], v[232:235], v[40:43], v[68:71]
	ds_read_b128 v[232:235], v131
	s_waitcnt lgkmcnt(7)
	v_mfma_f32_16x16x32_bf16 v[68:71], v[236:239], v[36:39], v[68:71]
	ds_read_b128 v[236:239], v132
	s_waitcnt lgkmcnt(7)
	v_mfma_f32_16x16x32_bf16 v[68:71], v[240:243], v[32:35], v[68:71]
	ds_read_b128 v[240:243], v133
	s_waitcnt lgkmcnt(7)
	v_mfma_f32_16x16x32_bf16 v[68:71], v[244:247], v[28:31], v[68:71]
	ds_read_b128 v[244:247], v134
	s_waitcnt lgkmcnt(7)
	v_mfma_f32_16x16x32_bf16 v[68:71], v[248:251], v[20:23], v[68:71]
	ds_read_b128 v[248:251], v135
	s_waitcnt lgkmcnt(7)
	v_mfma_f32_16x16x32_bf16 v[72:75], v[220:223], v[52:55], 0
	ds_read_b128 v[220:223], v136
	s_waitcnt lgkmcnt(7)
	v_mfma_f32_16x16x32_bf16 v[72:75], v[224:227], v[48:51], v[72:75]
	ds_read_b128 v[224:227], v137
	s_waitcnt lgkmcnt(7)
	v_mfma_f32_16x16x32_bf16 v[72:75], v[228:231], v[44:47], v[72:75]
	ds_read_b128 v[228:231], v138
	s_waitcnt lgkmcnt(7)
	v_mfma_f32_16x16x32_bf16 v[72:75], v[232:235], v[40:43], v[72:75]
	ds_read_b128 v[232:235], v139
	s_waitcnt lgkmcnt(7)
	v_mfma_f32_16x16x32_bf16 v[72:75], v[236:239], v[36:39], v[72:75]
	ds_read_b128 v[236:239], v140
	s_waitcnt lgkmcnt(7)
	v_mfma_f32_16x16x32_bf16 v[72:75], v[240:243], v[32:35], v[72:75]
	ds_read_b128 v[240:243], v141
	s_waitcnt lgkmcnt(7)
	v_mfma_f32_16x16x32_bf16 v[72:75], v[244:247], v[28:31], v[72:75]
	ds_read_b128 v[244:247], v142
	s_waitcnt lgkmcnt(7)
	v_mfma_f32_16x16x32_bf16 v[72:75], v[248:251], v[20:23], v[72:75]
	ds_read_b128 v[248:251], v143
	s_waitcnt lgkmcnt(7)
	v_mfma_f32_16x16x32_bf16 v[76:79], v[220:223], v[52:55], 0
	ds_read_b128 v[220:223], v144
	s_waitcnt lgkmcnt(7)
	v_mfma_f32_16x16x32_bf16 v[76:79], v[224:227], v[48:51], v[76:79]
	ds_read_b128 v[224:227], v145
	s_waitcnt lgkmcnt(7)
	v_mfma_f32_16x16x32_bf16 v[76:79], v[228:231], v[44:47], v[76:79]
	ds_read_b128 v[228:231], v146
	s_waitcnt lgkmcnt(7)
	v_mfma_f32_16x16x32_bf16 v[76:79], v[232:235], v[40:43], v[76:79]
	ds_read_b128 v[232:235], v147
	s_waitcnt lgkmcnt(7)
	v_mfma_f32_16x16x32_bf16 v[76:79], v[236:239], v[36:39], v[76:79]
	ds_read_b128 v[236:239], v148
	s_waitcnt lgkmcnt(7)
	v_mfma_f32_16x16x32_bf16 v[76:79], v[240:243], v[32:35], v[76:79]
	ds_read_b128 v[240:243], v149
	s_waitcnt lgkmcnt(7)
	v_mfma_f32_16x16x32_bf16 v[76:79], v[244:247], v[28:31], v[76:79]
	ds_read_b128 v[244:247], v150
	s_waitcnt lgkmcnt(7)
	v_mfma_f32_16x16x32_bf16 v[76:79], v[248:251], v[20:23], v[76:79]
	ds_read_b128 v[248:251], v151
	s_waitcnt lgkmcnt(7)
	v_mfma_f32_16x16x32_bf16 v[80:83], v[220:223], v[52:55], 0
	ds_read_b128 v[220:223], v152
	s_waitcnt lgkmcnt(7)
	v_mfma_f32_16x16x32_bf16 v[80:83], v[224:227], v[48:51], v[80:83]
	ds_read_b128 v[224:227], v153
	s_waitcnt lgkmcnt(7)
	v_mfma_f32_16x16x32_bf16 v[80:83], v[228:231], v[44:47], v[80:83]
	ds_read_b128 v[228:231], v154
	s_waitcnt lgkmcnt(7)
	v_mfma_f32_16x16x32_bf16 v[80:83], v[232:235], v[40:43], v[80:83]
	ds_read_b128 v[232:235], v155
	s_waitcnt lgkmcnt(7)
	v_mfma_f32_16x16x32_bf16 v[80:83], v[236:239], v[36:39], v[80:83]
	ds_read_b128 v[236:239], v156
	s_waitcnt lgkmcnt(7)
	v_mfma_f32_16x16x32_bf16 v[80:83], v[240:243], v[32:35], v[80:83]
	ds_read_b128 v[240:243], v157
	s_waitcnt lgkmcnt(7)
	v_mfma_f32_16x16x32_bf16 v[80:83], v[244:247], v[28:31], v[80:83]
	ds_read_b128 v[244:247], v158
	s_waitcnt lgkmcnt(7)
	v_mfma_f32_16x16x32_bf16 v[80:83], v[248:251], v[20:23], v[80:83]
	ds_read_b128 v[248:251], v159
	s_waitcnt lgkmcnt(7)
	v_mfma_f32_16x16x32_bf16 v[84:87], v[220:223], v[52:55], 0
	ds_read_b128 v[220:223], v160
	s_waitcnt lgkmcnt(7)
	v_mfma_f32_16x16x32_bf16 v[84:87], v[224:227], v[48:51], v[84:87]
	ds_read_b128 v[224:227], v161
	s_waitcnt lgkmcnt(7)
	v_mfma_f32_16x16x32_bf16 v[84:87], v[228:231], v[44:47], v[84:87]
	ds_read_b128 v[228:231], v162
	s_waitcnt lgkmcnt(7)
	v_mfma_f32_16x16x32_bf16 v[84:87], v[232:235], v[40:43], v[84:87]
	ds_read_b128 v[232:235], v163
	s_waitcnt lgkmcnt(7)
	v_mfma_f32_16x16x32_bf16 v[84:87], v[236:239], v[36:39], v[84:87]
	ds_read_b128 v[236:239], v164
	s_waitcnt lgkmcnt(7)
	v_mfma_f32_16x16x32_bf16 v[84:87], v[240:243], v[32:35], v[84:87]
	ds_read_b128 v[240:243], v165
	s_waitcnt lgkmcnt(7)
	v_mfma_f32_16x16x32_bf16 v[84:87], v[244:247], v[28:31], v[84:87]
	ds_read_b128 v[244:247], v166
	s_waitcnt lgkmcnt(7)
	v_mfma_f32_16x16x32_bf16 v[84:87], v[248:251], v[20:23], v[84:87]
	ds_read_b128 v[248:251], v167
	s_waitcnt lgkmcnt(7)
	v_mfma_f32_16x16x32_bf16 v[210:213], v[220:223], v[52:55], 0
	s_waitcnt lgkmcnt(6)
	v_mfma_f32_16x16x32_bf16 v[210:213], v[224:227], v[48:51], v[210:213]
	s_waitcnt lgkmcnt(5)
	v_mfma_f32_16x16x32_bf16 v[210:213], v[228:231], v[44:47], v[210:213]
	s_waitcnt lgkmcnt(4)
	v_mfma_f32_16x16x32_bf16 v[210:213], v[232:235], v[40:43], v[210:213]
	s_waitcnt lgkmcnt(3)
	v_mfma_f32_16x16x32_bf16 v[210:213], v[236:239], v[36:39], v[210:213]
	s_waitcnt lgkmcnt(2)
	v_mfma_f32_16x16x32_bf16 v[210:213], v[240:243], v[32:35], v[210:213]
	s_waitcnt lgkmcnt(1)
	v_mfma_f32_16x16x32_bf16 v[210:213], v[244:247], v[28:31], v[210:213]
	s_waitcnt lgkmcnt(0)
	v_mfma_f32_16x16x32_bf16 v[212:215], v[248:251], v[20:23], v[210:213]
	ds_read_b128 v[216:219], v168
	s_waitcnt lgkmcnt(0)
	v_mfma_f32_16x16x32_bf16 v[52:55], v[216:219], v[52:55], 0
	ds_read_b128 v[216:219], v169
	s_waitcnt lgkmcnt(0)
	v_mfma_f32_16x16x32_bf16 v[48:51], v[216:219], v[48:51], v[52:55]
	s_nop 4
	ds_read_b128 v[52:55], v170
	s_waitcnt lgkmcnt(0)
	v_mfma_f32_16x16x32_bf16 v[44:47], v[52:55], v[44:47], v[48:51]
	s_nop 2
	ds_read_b128 v[48:51], v171
	s_waitcnt lgkmcnt(0)
	v_mfma_f32_16x16x32_bf16 v[40:43], v[48:51], v[40:43], v[44:47]
	s_nop 2
	ds_read_b128 v[44:47], v172
	v_mov_b32_e32 v48, v64
	v_mov_b32_e32 v49, v66
	s_waitcnt lgkmcnt(0)
	v_mfma_f32_16x16x32_bf16 v[36:39], v[44:47], v[36:39], v[40:43]
	s_nop 2
	ds_read_b128 v[40:43], v173
	v_mov_b32_e32 v66, v65
	v_mov_b32_e32 v64, v56
	s_waitcnt lgkmcnt(0)
	v_mfma_f32_16x16x32_bf16 v[32:35], v[40:43], v[32:35], v[36:39]
	s_nop 2
	ds_read_b128 v[36:39], v174
	v_mov_b32_e32 v40, v72
	v_mov_b32_e32 v41, v74
	s_waitcnt lgkmcnt(0)
	v_mfma_f32_16x16x32_bf16 v[28:31], v[36:39], v[28:31], v[32:35]
	s_nop 2
	ds_read_b128 v[32:35], v175
	v_pk_mul_f32 v[46:47], v[40:41], s[30:31] op_sel_hi:[1,0]
	v_mov_b32_e32 v40, v76
	s_waitcnt lgkmcnt(0)
	v_mfma_f32_16x16x32_bf16 v[32:35], v[32:35], v[20:23], v[28:31]
	v_lshl_or_b32 v20, s0, 4, v108
	v_and_b32_e32 v21, 64, v208
	v_xor_b32_e32 v20, 16, v208
	v_add_u32_e32 v21, 64, v21
	v_cmp_lt_i32_e32 vcc, v20, v21
	v_mov_b32_e32 v41, v78
	v_mov_b32_e32 v78, v77
	v_cndmask_b32_e32 v20, v208, v20, vcc
	v_lshlrev_b32_e32 v210, 2, v20
	v_xor_b32_e32 v20, 32, v208
	v_cmp_lt_i32_e32 vcc, v20, v21
	v_mov_b32_e32 v21, v214
	v_mov_b32_e32 v214, v213
	v_cndmask_b32_e32 v20, v208, v20, vcc
	v_lshlrev_b32_e32 v209, 2, v20
	v_mov_b32_e32 v20, v212
	v_pk_mul_f32 v[30:31], v[20:21], s[30:31] op_sel_hi:[1,0]
	v_pk_mul_f32 v[28:29], v[214:215], s[30:31] op_sel_hi:[1,0]
	v_cmp_lt_f32_e64 s[0:1], s31, v30
	v_mov_b32_e32 v20, v32
	v_mov_b32_e32 v21, v34
	v_writelane_b32 v255, s0, 22
	v_pk_mul_f32 v[22:23], v[20:21], s[30:31] op_sel_hi:[1,0]
	v_mov_b32_e32 v34, v33
	v_writelane_b32 v255, s1, 23
	v_cmp_lt_f32_e64 s[0:1], s31, v31
	v_pk_mul_f32 v[20:21], v[34:35], s[30:31] op_sel_hi:[1,0]
	v_mov_b32_e32 v32, v80
	v_writelane_b32 v255, s0, 24
	v_mov_b32_e32 v33, v82
	v_pk_mul_f32 v[38:39], v[32:33], s[30:31] op_sel_hi:[1,0]
	v_writelane_b32 v255, s1, 25
	v_cmp_lt_f32_e64 s[0:1], s31, v28
	v_mov_b32_e32 v82, v81
	v_pk_mul_f32 v[36:37], v[82:83], s[30:31] op_sel_hi:[1,0]
	v_writelane_b32 v255, s0, 26
	v_mov_b32_e32 v32, v84
	v_mov_b32_e32 v33, v86
	v_writelane_b32 v255, s1, 27
	v_cmp_lt_f32_e64 s[0:1], s31, v29
	v_pk_mul_f32 v[34:35], v[32:33], s[30:31] op_sel_hi:[1,0]
	v_mov_b32_e32 v86, v85
	v_writelane_b32 v255, s0, 28
	v_pk_mul_f32 v[32:33], v[86:87], s[30:31] op_sel_hi:[1,0]
	v_pk_mul_f32 v[42:43], v[40:41], s[30:31] op_sel_hi:[1,0]
	v_writelane_b32 v255, s1, 29
	v_cmp_lt_f32_e64 s[0:1], s31, v22
	v_pk_mul_f32 v[40:41], v[78:79], s[30:31] op_sel_hi:[1,0]
	v_mov_b32_e32 v65, v58
	v_writelane_b32 v255, s0, 30
	v_mov_b32_e32 v58, v57
	v_mov_b32_e32 v56, v60
	v_writelane_b32 v255, s1, 31
	v_cmp_lt_f32_e64 s[0:1], s31, v23
	v_mov_b32_e32 v57, v62
	v_mov_b32_e32 v62, v61
	v_writelane_b32 v255, s0, 32
	v_mov_b32_e32 v60, v16
	v_mov_b32_e32 v61, v18
	v_writelane_b32 v255, s1, 33
	v_cmp_lt_f32_e64 s[0:1], s31, v20
	v_mov_b32_e32 v18, v17
	v_mov_b32_e32 v16, v24
	v_writelane_b32 v255, s0, 34
	v_mov_b32_e32 v17, v26
	v_mov_b32_e32 v26, v25
	v_writelane_b32 v255, s1, 35
	v_cmp_lt_f32_e64 s[0:1], s31, v21
	v_mov_b32_e32 v24, v8
	v_mov_b32_e32 v25, v10
	v_writelane_b32 v255, s0, 36
	v_mov_b32_e32 v10, v9
	v_mov_b32_e32 v8, v12
	v_writelane_b32 v255, s1, 37
	v_cmp_lt_f32_e64 s[0:1], s31, v38
	v_mov_b32_e32 v9, v14
	v_mov_b32_e32 v14, v13
	v_writelane_b32 v255, s0, 38
	v_mov_b32_e32 v12, v0
	v_mov_b32_e32 v13, v2
	v_writelane_b32 v255, s1, 39
	v_cmp_lt_f32_e64 s[0:1], s31, v39
	v_mov_b32_e32 v2, v1
	v_pk_mul_f32 v[52:53], v[66:67], s[30:31] op_sel_hi:[1,0]
	v_writelane_b32 v255, s0, 40
	v_pk_mul_f32 v[66:67], v[64:65], s[30:31] op_sel_hi:[1,0]
	v_pk_mul_f32 v[64:65], v[58:59], s[30:31] op_sel_hi:[1,0]
	v_writelane_b32 v255, s1, 41
	v_cmp_lt_f32_e64 s[0:1], s31, v36
	v_pk_mul_f32 v[58:59], v[56:57], s[30:31] op_sel_hi:[1,0]
	v_pk_mul_f32 v[56:57], v[62:63], s[30:31] op_sel_hi:[1,0]
	v_writelane_b32 v255, s0, 42
	v_pk_mul_f32 v[62:63], v[60:61], s[30:31] op_sel_hi:[1,0]
	v_pk_mul_f32 v[60:61], v[18:19], s[30:31] op_sel_hi:[1,0]
	v_writelane_b32 v255, s1, 43
	v_cmp_lt_f32_e64 s[0:1], s31, v37
	v_pk_mul_f32 v[18:19], v[16:17], s[30:31] op_sel_hi:[1,0]
	v_pk_mul_f32 v[16:17], v[26:27], s[30:31] op_sel_hi:[1,0]
	v_writelane_b32 v255, s0, 44
	v_pk_mul_f32 v[26:27], v[24:25], s[30:31] op_sel_hi:[1,0]
	v_pk_mul_f32 v[24:25], v[10:11], s[30:31] op_sel_hi:[1,0]
	v_writelane_b32 v255, s1, 45
	v_cmp_lt_f32_e64 s[0:1], s31, v34
	v_pk_mul_f32 v[10:11], v[8:9], s[30:31] op_sel_hi:[1,0]
	v_pk_mul_f32 v[8:9], v[14:15], s[30:31] op_sel_hi:[1,0]
	v_writelane_b32 v255, s0, 46
	v_pk_mul_f32 v[12:13], v[12:13], s[30:31] op_sel_hi:[1,0]
	v_pk_mul_f32 v[14:15], v[2:3], s[30:31] op_sel_hi:[1,0]
	v_writelane_b32 v255, s1, 47
	v_cmp_lt_f32_e64 s[0:1], s31, v35
	v_pk_mul_f32 v[54:55], v[48:49], s[30:31] op_sel_hi:[1,0]
	v_mov_b32_e32 v48, v68
	v_writelane_b32 v255, s0, 48
	v_mov_b32_e32 v49, v70
	v_mov_b32_e32 v70, v69
	v_writelane_b32 v255, s1, 49
	v_cmp_lt_f32_e64 s[0:1], s31, v32
	v_mov_b32_e32 v1, v6
	v_mov_b32_e32 v6, v5
	v_writelane_b32 v255, s0, 50
	v_pk_mul_f32 v[50:51], v[48:49], s[30:31] op_sel_hi:[1,0]
	v_pk_mul_f32 v[48:49], v[70:71], s[30:31] op_sel_hi:[1,0]
	v_writelane_b32 v255, s1, 51
	v_cmp_lt_f32_e64 s[0:1], s31, v33
	v_pk_mul_f32 v[70:71], v[6:7], s[30:31] op_sel_hi:[1,0]
	v_mov_b32_e32 v74, v73
	v_writelane_b32 v255, s0, 52
	v_pk_mul_f32 v[44:45], v[74:75], s[30:31] op_sel_hi:[1,0]
	v_cmp_lt_f32_e64 s[4:5], s31, v14
	v_writelane_b32 v255, s1, 53
	v_cmp_lt_f32_e64 s[0:1], s31, v40
	v_cmp_lt_f32_e32 vcc, s31, v13
	v_cmp_lt_f32_e64 s[2:3], s31, v15
	v_writelane_b32 v255, s0, 54
	v_cmp_lt_f32_e64 s[12:13], s31, v70
	v_cmp_lt_f32_e64 s[10:11], s31, v71
	v_writelane_b32 v255, s1, 55
	s_mov_b32 s0, 0xff61b1e6
	v_max3_f32 v0, v12, s0, v14
	v_max3_f32 v2, v0, v13, v15
	v_mov_b32_e32 v0, v4
	v_pk_mul_f32 v[68:69], v[0:1], s[30:31] op_sel_hi:[1,0]
	v_cmp_lt_f32_e64 s[0:1], s31, v12
	v_max3_f32 v0, v2, v68, v70
	v_max3_f32 v0, v0, v69, v71
	v_max3_f32 v0, v0, v26, v24
	v_max3_f32 v0, v0, v27, v25
	v_max3_f32 v0, v0, v10, v8
	v_max3_f32 v0, v0, v11, v9
	v_max3_f32 v0, v0, v62, v60
	v_max3_f32 v0, v0, v63, v61
	v_max3_f32 v0, v0, v18, v16
	v_max3_f32 v0, v0, v19, v17
	v_max3_f32 v0, v0, v66, v64
	v_max3_f32 v0, v0, v67, v65
	v_max3_f32 v0, v0, v58, v56
	v_max3_f32 v0, v0, v59, v57
	v_max3_f32 v0, v0, v54, v52
	v_max3_f32 v0, v0, v55, v53
	v_max3_f32 v0, v0, v50, v48
	v_max3_f32 v0, v0, v51, v49
	v_max3_f32 v0, v0, v46, v44
	v_max3_f32 v0, v0, v47, v45
	v_max3_f32 v0, v0, v42, v40
	v_max3_f32 v0, v0, v43, v41
	v_max3_f32 v0, v0, v38, v36
	v_max3_f32 v0, v0, v39, v37
	v_max3_f32 v0, v0, v34, v32
	v_max3_f32 v0, v0, v35, v33
	v_max3_f32 v0, v0, v30, v28
	v_max3_f32 v0, v0, v31, v29
	v_max3_f32 v0, v0, v22, v20
	v_max3_f32 v0, v0, v23, v21
	ds_bpermute_b32 v1, v210, v0
	v_cmp_lt_f32_e64 s[8:9], s31, v68
	v_cmp_lt_f32_e64 s[6:7], s31, v69
	v_cmp_lt_f32_e64 s[16:17], s31, v26
	v_cmp_lt_f32_e64 s[22:23], s31, v24
	s_waitcnt lgkmcnt(0)
	v_max_f32_e32 v1, v1, v1
	v_max_f32_e32 v0, v0, v1
	ds_bpermute_b32 v1, v209, v0
	v_cmp_lt_f32_e64 s[24:25], s31, v10
	v_cmp_lt_f32_e64 s[18:19], s31, v25
	v_cmp_lt_f32_e64 s[14:15], s31, v27
	v_cmp_lt_f32_e64 s[28:29], s31, v8
	s_waitcnt lgkmcnt(0)
	v_max_f32_e32 v1, v1, v1
	v_max_f32_e32 v2, v0, v1
	v_sub_f32_e32 v0, v12, v2
	v_mul_f32_e32 v0, 0x3fb8aa3b, v0
	v_sub_f32_e32 v3, v14, v2
	v_exp_f32_e32 v1, v0
	v_sub_f32_e32 v0, v13, v2
	v_mul_f32_e32 v3, 0x3fb8aa3b, v3
	v_mul_f32_e32 v0, 0x3fb8aa3b, v0
	v_exp_f32_e32 v4, v3
	v_sub_f32_e32 v3, v15, v2
	v_exp_f32_e32 v0, v0
	v_mul_f32_e32 v3, 0x3fb8aa3b, v3
	v_exp_f32_e32 v3, v3
	v_cndmask_b32_e64 v1, 0, v1, s[0:1]
	v_add_f32_e32 v5, 0, v1
	v_cndmask_b32_e64 v4, 0, v4, s[4:5]
	v_cndmask_b32_e32 v0, 0, v0, vcc
	v_add_f32_e32 v5, v4, v5
	v_cndmask_b32_e64 v3, 0, v3, s[2:3]
	v_add_f32_e32 v5, v0, v5
	v_add_f32_e32 v7, v3, v5
	v_sub_f32_e32 v5, v68, v2
	v_mul_f32_e32 v5, 0x3fb8aa3b, v5
	v_exp_f32_e32 v6, v5
	v_sub_f32_e32 v5, v69, v2
	v_mul_f32_e32 v5, 0x3fb8aa3b, v5
	v_exp_f32_e32 v5, v5
	v_cndmask_b32_e64 v6, 0, v6, s[8:9]
	v_add_f32_e32 v12, v6, v7
	v_sub_f32_e32 v7, v70, v2
	v_mul_f32_e32 v7, 0x3fb8aa3b, v7
	v_exp_f32_e32 v13, v7
	v_sub_f32_e32 v7, v71, v2
	v_mul_f32_e32 v7, 0x3fb8aa3b, v7
	v_exp_f32_e32 v7, v7
	v_cndmask_b32_e64 v13, 0, v13, s[12:13]
	v_cndmask_b32_e64 v5, 0, v5, s[6:7]
	v_add_f32_e32 v12, v13, v12
	v_cndmask_b32_e64 v7, 0, v7, s[10:11]
	v_add_f32_e32 v12, v5, v12
	v_add_f32_e32 v15, v7, v12
	v_sub_f32_e32 v12, v26, v2
	v_mul_f32_e32 v12, 0x3fb8aa3b, v12
	v_exp_f32_e32 v14, v12
	v_sub_f32_e32 v12, v27, v2
	v_mul_f32_e32 v12, 0x3fb8aa3b, v12
	v_exp_f32_e32 v12, v12
	v_cndmask_b32_e64 v14, 0, v14, s[16:17]
	v_add_f32_e32 v26, v14, v15
	v_sub_f32_e32 v15, v24, v2
	v_mul_f32_e32 v15, 0x3fb8aa3b, v15
	v_exp_f32_e32 v24, v15
	v_sub_f32_e32 v15, v25, v2
	v_mul_f32_e32 v15, 0x3fb8aa3b, v15
	v_sub_f32_e32 v10, v10, v2
	v_exp_f32_e32 v15, v15
	v_cndmask_b32_e64 v24, 0, v24, s[22:23]
	v_mul_f32_e32 v10, 0x3fb8aa3b, v10
	v_add_f32_e32 v25, v24, v26
	v_exp_f32_e32 v26, v10
	v_cndmask_b32_e64 v12, 0, v12, s[14:15]
	v_cndmask_b32_e64 v15, 0, v15, s[18:19]
	v_add_f32_e32 v25, v12, v25
	v_sub_f32_e32 v8, v8, v2
	v_cmp_lt_f32_e64 s[20:21], s31, v11
	v_add_f32_e32 v25, v15, v25
	v_sub_f32_e32 v10, v11, v2
	v_cndmask_b32_e64 v11, 0, v26, s[24:25]
	v_mul_f32_e32 v8, 0x3fb8aa3b, v8
	v_mul_f32_e32 v10, 0x3fb8aa3b, v10
	v_add_f32_e32 v26, v11, v25
	v_exp_f32_e32 v25, v8
	v_sub_f32_e32 v8, v9, v2
	v_exp_f32_e32 v10, v10
	v_mul_f32_e32 v8, 0x3fb8aa3b, v8
	v_exp_f32_e32 v8, v8
	v_cndmask_b32_e64 v25, 0, v25, s[28:29]
	v_cmp_lt_f32_e64 s[26:27], s31, v9
	v_cndmask_b32_e64 v10, 0, v10, s[20:21]
	v_add_f32_e32 v9, v25, v26
	v_cndmask_b32_e64 v8, 0, v8, s[26:27]
	v_add_f32_e32 v9, v10, v9
	v_add_f32_e32 v26, v8, v9
	v_sub_f32_e32 v9, v62, v2
	v_mul_f32_e32 v9, 0x3fb8aa3b, v9
	v_exp_f32_e32 v27, v9
	v_cmp_lt_f32_e64 s[94:95], s31, v62
	v_cmp_lt_f32_e64 s[86:87], s31, v18
	v_sub_f32_e32 v18, v18, v2
	v_cndmask_b32_e64 v62, 0, v27, s[94:95]
	v_sub_f32_e32 v27, v60, v2
	v_mul_f32_e32 v27, 0x3fb8aa3b, v27
	v_exp_f32_e32 v27, v27
	v_cmp_lt_f32_e64 s[88:89], s31, v60
	v_sub_f32_e32 v9, v63, v2
	v_mul_f32_e32 v18, 0x3fb8aa3b, v18
	v_cmp_lt_f32_e64 s[92:93], s31, v61
	v_mul_f32_e32 v9, 0x3fb8aa3b, v9
	v_sub_f32_e32 v60, v61, v2
	v_cndmask_b32_e64 v61, 0, v27, s[88:89]
	v_exp_f32_e32 v27, v18
	v_exp_f32_e32 v9, v9
	v_mul_f32_e32 v60, 0x3fb8aa3b, v60
	v_cmp_lt_f32_e64 s[82:83], s31, v16
	v_exp_f32_e32 v60, v60
	v_sub_f32_e32 v16, v16, v2
	v_sub_f32_e32 v18, v19, v2
	v_mul_f32_e32 v16, 0x3fb8aa3b, v16
	v_cmp_lt_f32_e64 s[96:97], s31, v63
	v_cmp_lt_f32_e64 s[90:91], s31, v19
	v_add_f32_e32 v26, v62, v26
	v_mul_f32_e32 v18, 0x3fb8aa3b, v18
	v_cndmask_b32_e64 v19, 0, v27, s[86:87]
	v_exp_f32_e32 v27, v16
	v_sub_f32_e32 v16, v17, v2
	v_cndmask_b32_e64 v9, 0, v9, s[96:97]
	v_add_f32_e32 v26, v61, v26
	v_exp_f32_e32 v18, v18
	v_mul_f32_e32 v16, 0x3fb8aa3b, v16
	v_cndmask_b32_e64 v60, 0, v60, s[92:93]
	v_add_f32_e32 v26, v9, v26
	v_exp_f32_e32 v16, v16
	v_add_f32_e32 v26, v60, v26
	v_add_f32_e32 v26, v19, v26
	v_cndmask_b32_e64 v63, 0, v27, s[82:83]
	v_cmp_lt_f32_e64 s[84:85], s31, v17
	v_cndmask_b32_e64 v18, 0, v18, s[90:91]
	v_add_f32_e32 v17, v63, v26
	v_cndmask_b32_e64 v16, 0, v16, s[84:85]
	v_add_f32_e32 v17, v18, v17
	v_add_f32_e32 v26, v16, v17
	v_sub_f32_e32 v17, v66, v2
	v_mul_f32_e32 v17, 0x3fb8aa3b, v17
	v_exp_f32_e32 v27, v17
	v_cmp_lt_f32_e64 s[78:79], s31, v66
	v_cmp_lt_f32_e64 s[74:75], s31, v64
	v_cmp_lt_f32_e64 s[76:77], s31, v65
	v_cndmask_b32_e64 v66, 0, v27, s[78:79]
	v_sub_f32_e32 v27, v64, v2
	v_mul_f32_e32 v27, 0x3fb8aa3b, v27
	v_exp_f32_e32 v27, v27
	v_sub_f32_e32 v64, v65, v2
	v_cmp_lt_f32_e64 s[70:71], s31, v58
	v_cmp_lt_f32_e64 s[72:73], s31, v59
	v_cndmask_b32_e64 v65, 0, v27, s[74:75]
	v_sub_f32_e32 v27, v58, v2
	v_mul_f32_e32 v27, 0x3fb8aa3b, v27
	v_exp_f32_e32 v27, v27
	v_sub_f32_e32 v58, v59, v2
	v_cmp_lt_f32_e64 s[66:67], s31, v56
	v_cmp_lt_f32_e64 s[68:69], s31, v57
	v_cndmask_b32_e64 v59, 0, v27, s[70:71]
	v_sub_f32_e32 v27, v56, v2
	v_mul_f32_e32 v27, 0x3fb8aa3b, v27
	v_exp_f32_e32 v27, v27
	v_sub_f32_e32 v56, v57, v2
	v_cmp_lt_f32_e64 s[62:63], s31, v54
	v_cmp_lt_f32_e64 s[64:65], s31, v55
	v_cndmask_b32_e64 v57, 0, v27, s[66:67]
	v_sub_f32_e32 v27, v54, v2
	v_mul_f32_e32 v27, 0x3fb8aa3b, v27
	v_exp_f32_e32 v27, v27
	v_sub_f32_e32 v54, v55, v2
	v_cmp_lt_f32_e64 s[54:55], s31, v52
	v_cmp_lt_f32_e64 s[60:61], s31, v53
	v_cndmask_b32_e64 v55, 0, v27, s[62:63]
	v_sub_f32_e32 v27, v52, v2
	v_mul_f32_e32 v27, 0x3fb8aa3b, v27
	v_exp_f32_e32 v27, v27
	v_sub_f32_e32 v52, v53, v2
	v_cmp_lt_f32_e64 s[56:57], s31, v50
	v_cmp_lt_f32_e64 s[58:59], s31, v51
	v_cndmask_b32_e64 v53, 0, v27, s[54:55]
	v_sub_f32_e32 v27, v50, v2
	v_mul_f32_e32 v27, 0x3fb8aa3b, v27
	v_exp_f32_e32 v27, v27
	v_sub_f32_e32 v50, v51, v2
	v_cmp_lt_f32_e64 s[50:51], s31, v48
	v_cmp_lt_f32_e64 s[52:53], s31, v49
	v_cndmask_b32_e64 v51, 0, v27, s[56:57]
	v_sub_f32_e32 v27, v48, v2
	v_mul_f32_e32 v27, 0x3fb8aa3b, v27
	v_exp_f32_e32 v27, v27
	v_sub_f32_e32 v48, v49, v2
	v_cmp_lt_f32_e64 s[46:47], s31, v46
	v_cmp_lt_f32_e64 s[48:49], s31, v47
	v_cndmask_b32_e64 v49, 0, v27, s[50:51]
	v_sub_f32_e32 v27, v46, v2
	v_mul_f32_e32 v27, 0x3fb8aa3b, v27
	v_exp_f32_e32 v27, v27
	v_sub_f32_e32 v46, v47, v2
	v_cmp_lt_f32_e64 s[42:43], s31, v44
	v_cmp_lt_f32_e64 s[44:45], s31, v45
	v_cndmask_b32_e64 v47, 0, v27, s[46:47]
	v_sub_f32_e32 v27, v44, v2
	v_mul_f32_e32 v27, 0x3fb8aa3b, v27
	v_exp_f32_e32 v27, v27
	v_sub_f32_e32 v44, v45, v2
	v_cmp_lt_f32_e64 s[38:39], s31, v42
	v_cmp_lt_f32_e64 s[40:41], s31, v43
	v_cndmask_b32_e64 v45, 0, v27, s[42:43]
	v_sub_f32_e32 v27, v42, v2
	v_mul_f32_e32 v27, 0x3fb8aa3b, v27
	v_exp_f32_e32 v27, v27
	v_sub_f32_e32 v42, v43, v2
	v_readlane_b32 s0, v255, 54
	v_readlane_b32 s1, v255, 55
	v_cndmask_b32_e64 v43, 0, v27, s[38:39]
	v_sub_f32_e32 v27, v40, v2
	v_mul_f32_e32 v27, 0x3fb8aa3b, v27
	v_exp_f32_e32 v27, v27
	v_cmp_lt_f32_e64 s[36:37], s31, v41
	v_sub_f32_e32 v40, v41, v2
	v_sub_f32_e32 v17, v67, v2
	v_cndmask_b32_e64 v41, 0, v27, s[0:1]
	v_sub_f32_e32 v27, v38, v2
	v_sub_f32_e32 v38, v39, v2
	v_mul_f32_e32 v38, 0x3fb8aa3b, v38
	v_exp_f32_e32 v38, v38
	v_mul_f32_e32 v27, 0x3fb8aa3b, v27
	v_exp_f32_e32 v27, v27
	v_readlane_b32 s0, v255, 40
	v_readlane_b32 s1, v255, 41
	v_mul_f32_e32 v17, 0x3fb8aa3b, v17
	v_exp_f32_e32 v17, v17
	v_cndmask_b32_e64 v38, 0, v38, s[0:1]
	v_readlane_b32 s0, v255, 38
	v_readlane_b32 s1, v255, 39
	v_mul_f32_e32 v64, 0x3fb8aa3b, v64
	v_exp_f32_e32 v64, v64
	v_cndmask_b32_e64 v39, 0, v27, s[0:1]
	v_sub_f32_e32 v27, v36, v2
	v_sub_f32_e32 v36, v37, v2
	v_mul_f32_e32 v36, 0x3fb8aa3b, v36
	v_exp_f32_e32 v36, v36
	v_mul_f32_e32 v27, 0x3fb8aa3b, v27
	v_exp_f32_e32 v27, v27
	v_readlane_b32 s0, v255, 44
	v_readlane_b32 s1, v255, 45
	v_cmp_lt_f32_e64 s[80:81], s31, v67
	v_add_f32_e32 v26, v66, v26
	v_cndmask_b32_e64 v36, 0, v36, s[0:1]
	v_readlane_b32 s0, v255, 42
	v_readlane_b32 s1, v255, 43
	v_mul_f32_e32 v58, 0x3fb8aa3b, v58
	v_cndmask_b32_e64 v17, 0, v17, s[80:81]
	v_cndmask_b32_e64 v37, 0, v27, s[0:1]
	v_sub_f32_e32 v27, v34, v2
	v_sub_f32_e32 v34, v35, v2
	v_mul_f32_e32 v34, 0x3fb8aa3b, v34
	v_exp_f32_e32 v34, v34
	v_mul_f32_e32 v27, 0x3fb8aa3b, v27
	v_exp_f32_e32 v27, v27
	v_readlane_b32 s0, v255, 48
	v_add_f32_e32 v26, v65, v26
	v_exp_f32_e32 v58, v58
	v_mul_f32_e32 v56, 0x3fb8aa3b, v56
	v_readlane_b32 s1, v255, 49
	v_cndmask_b32_e64 v64, 0, v64, s[76:77]
	v_add_f32_e32 v26, v17, v26
	v_exp_f32_e32 v56, v56
	v_cndmask_b32_e64 v34, 0, v34, s[0:1]
	v_readlane_b32 s0, v255, 46
	v_add_f32_e32 v26, v64, v26
	v_readlane_b32 s1, v255, 47
	v_add_f32_e32 v26, v59, v26
	v_mul_f32_e32 v54, 0x3fb8aa3b, v54
	v_cndmask_b32_e64 v35, 0, v27, s[0:1]
	v_sub_f32_e32 v27, v32, v2
	v_sub_f32_e32 v32, v33, v2
	v_cndmask_b32_e64 v58, 0, v58, s[72:73]
	v_add_f32_e32 v26, v57, v26
	v_exp_f32_e32 v54, v54
	v_mul_f32_e32 v52, 0x3fb8aa3b, v52
	v_mul_f32_e32 v32, 0x3fb8aa3b, v32
	v_cndmask_b32_e64 v56, 0, v56, s[68:69]
	v_add_f32_e32 v26, v58, v26
	v_exp_f32_e32 v52, v52
	v_exp_f32_e32 v32, v32
	v_add_f32_e32 v26, v56, v26
	v_mul_f32_e32 v27, 0x3fb8aa3b, v27
	v_add_f32_e32 v26, v55, v26
	v_mul_f32_e32 v50, 0x3fb8aa3b, v50
	v_exp_f32_e32 v27, v27
	v_readlane_b32 s0, v255, 52
	v_cndmask_b32_e64 v54, 0, v54, s[64:65]
	v_add_f32_e32 v26, v53, v26
	v_exp_f32_e32 v50, v50
	v_mul_f32_e32 v48, 0x3fb8aa3b, v48
	v_readlane_b32 s1, v255, 53
	v_cndmask_b32_e64 v52, 0, v52, s[60:61]
	v_add_f32_e32 v26, v54, v26
	v_exp_f32_e32 v48, v48
	v_cndmask_b32_e64 v67, 0, v32, s[0:1]
	v_readlane_b32 s0, v255, 50
	v_add_f32_e32 v26, v52, v26
	v_readlane_b32 s1, v255, 51
	v_add_f32_e32 v26, v51, v26
	v_mul_f32_e32 v46, 0x3fb8aa3b, v46
	v_cndmask_b32_e64 v68, 0, v27, s[0:1]
	v_sub_f32_e32 v27, v30, v2
	v_sub_f32_e32 v30, v31, v2
	v_cndmask_b32_e64 v50, 0, v50, s[58:59]
	v_add_f32_e32 v26, v49, v26
	v_exp_f32_e32 v46, v46
	v_mul_f32_e32 v44, 0x3fb8aa3b, v44
	v_mul_f32_e32 v30, 0x3fb8aa3b, v30
	v_cndmask_b32_e64 v48, 0, v48, s[52:53]
	v_add_f32_e32 v26, v50, v26
	v_exp_f32_e32 v44, v44
	v_exp_f32_e32 v30, v30
	v_add_f32_e32 v26, v48, v26
	v_mul_f32_e32 v27, 0x3fb8aa3b, v27
	v_add_f32_e32 v26, v47, v26
	v_mul_f32_e32 v42, 0x3fb8aa3b, v42
	v_exp_f32_e32 v27, v27
	v_readlane_b32 s0, v255, 24
	v_cndmask_b32_e64 v46, 0, v46, s[48:49]
	v_add_f32_e32 v26, v45, v26
	v_exp_f32_e32 v42, v42
	v_mul_f32_e32 v40, 0x3fb8aa3b, v40
	v_readlane_b32 s1, v255, 25
	v_cndmask_b32_e64 v44, 0, v44, s[44:45]
	v_add_f32_e32 v26, v46, v26
	v_exp_f32_e32 v40, v40
	v_cndmask_b32_e64 v69, 0, v30, s[0:1]
	v_readlane_b32 s0, v255, 22
	v_add_f32_e32 v26, v44, v26
	v_readlane_b32 s1, v255, 23
	v_add_f32_e32 v26, v43, v26
	v_cndmask_b32_e64 v42, 0, v42, s[40:41]
	v_cndmask_b32_e64 v70, 0, v27, s[0:1]
	v_sub_f32_e32 v27, v28, v2
	v_sub_f32_e32 v28, v29, v2
	v_add_f32_e32 v26, v41, v26
	v_mul_f32_e32 v28, 0x3fb8aa3b, v28
	v_cndmask_b32_e64 v40, 0, v40, s[36:37]
	v_add_f32_e32 v26, v42, v26
	v_exp_f32_e32 v28, v28
	v_add_f32_e32 v26, v40, v26
	v_mul_f32_e32 v27, 0x3fb8aa3b, v27
	v_add_f32_e32 v26, v39, v26
	v_exp_f32_e32 v27, v27
	v_readlane_b32 s0, v255, 28
	v_sub_f32_e32 v23, v23, v2
	v_add_f32_e32 v26, v37, v26
	v_readlane_b32 s1, v255, 29
	v_mul_f32_e32 v23, 0x3fb8aa3b, v23
	v_add_f32_e32 v26, v38, v26
	v_cndmask_b32_e64 v71, 0, v28, s[0:1]
	v_readlane_b32 s0, v255, 26
	v_sub_f32_e32 v22, v22, v2
	v_exp_f32_e32 v23, v23
	v_add_f32_e32 v26, v36, v26
	v_readlane_b32 s1, v255, 27
	v_mul_f32_e32 v22, 0x3fb8aa3b, v22
	v_add_f32_e32 v26, v35, v26
	v_cndmask_b32_e64 v72, 0, v27, s[0:1]
	v_exp_f32_e32 v22, v22
	v_readlane_b32 s0, v255, 32
	v_sub_f32_e32 v20, v20, v2
	v_sub_f32_e32 v2, v21, v2
	v_add_f32_e32 v26, v68, v26
	v_readlane_b32 s1, v255, 33
	v_mul_f32_e32 v2, 0x3fb8aa3b, v2
	v_add_f32_e32 v26, v34, v26
	v_cndmask_b32_e64 v73, 0, v23, s[0:1]
	v_readlane_b32 s0, v255, 30
	v_exp_f32_e32 v2, v2
	v_add_f32_e32 v26, v67, v26
	v_readlane_b32 s1, v255, 31
	v_mul_f32_e32 v20, 0x3fb8aa3b, v20
	v_add_f32_e32 v26, v70, v26
	v_cndmask_b32_e64 v74, 0, v22, s[0:1]
	v_exp_f32_e32 v20, v20
	v_readlane_b32 s0, v255, 36
	v_add_f32_e32 v26, v72, v26
	v_readlane_b32 s1, v255, 37
	v_add_f32_e32 v26, v69, v26
	v_add_f32_e32 v26, v71, v26
	v_cndmask_b32_e64 v2, 0, v2, s[0:1]
	v_readlane_b32 s0, v255, 34
	v_readlane_b32 s1, v255, 35
	v_add_f32_e32 v22, v74, v26
	v_bfe_u32 v23, v4, 16, 1
	v_cndmask_b32_e64 v75, 0, v20, s[0:1]
	v_add_f32_e32 v20, v75, v22
	v_add_f32_e32 v20, v73, v20
	v_add_f32_e32 v20, v2, v20
	ds_bpermute_b32 v21, v210, v20
	v_bfe_u32 v22, v3, 16, 1
	v_add3_u32 v3, v3, v22, s33
	v_bfe_u32 v22, v6, 16, 1
	v_add3_u32 v4, v4, v23, s33
	s_waitcnt lgkmcnt(0)
	v_add_f32_e32 v32, v20, v21
	v_bfe_u32 v21, v13, 16, 1
	v_add3_u32 v13, v13, v21, s33
	v_bfe_u32 v21, v0, 16, 1
	v_bfe_u32 v20, v7, 16, 1
	v_bfe_u32 v23, v5, 16, 1
	v_add3_u32 v6, v6, v22, s33
	v_add3_u32 v0, v0, v21, s33
	v_add3_u32 v7, v7, v20, s33
	v_bfe_u32 v20, v1, 16, 1
	v_add3_u32 v5, v5, v23, s33
	v_lshrrev_b32_e32 v0, 16, v0
	v_lshrrev_b32_e32 v6, 16, v6
	v_add3_u32 v1, v1, v20, s33
	v_lshrrev_b32_e32 v5, 16, v5
	v_and_or_b32 v30, v13, s34, v6
	v_and_or_b32 v29, v3, s34, v0
	v_bfe_u32 v0, v8, 16, 1
	v_bfe_u32 v6, v12, 16, 1
	v_lshrrev_b32_e32 v1, 16, v1
	v_and_or_b32 v31, v7, s34, v5
	v_bfe_u32 v3, v15, 16, 1
	v_add3_u32 v0, v8, v0, s33
	v_bfe_u32 v5, v14, 16, 1
	v_bfe_u32 v7, v11, 16, 1
	v_bfe_u32 v8, v10, 16, 1
	v_add3_u32 v6, v12, v6, s33
	v_and_or_b32 v28, v4, s34, v1
	v_bfe_u32 v1, v25, 16, 1
	v_bfe_u32 v4, v24, 16, 1
	v_add3_u32 v3, v15, v3, s33
	v_add3_u32 v8, v10, v8, s33
	v_add3_u32 v7, v11, v7, s33
	v_add3_u32 v5, v14, v5, s33
	v_lshrrev_b32_e32 v6, 16, v6
	v_add3_u32 v4, v24, v4, s33
	v_add3_u32 v1, v25, v1, s33
	v_lshrrev_b32_e32 v5, 16, v5
	v_lshrrev_b32_e32 v7, 16, v7
	v_lshrrev_b32_e32 v8, 16, v8
	v_and_or_b32 v25, v3, s34, v6
	v_bfe_u32 v6, v9, 16, 1
	v_and_or_b32 v27, v0, s34, v8
	v_and_or_b32 v26, v1, s34, v7
	v_and_or_b32 v24, v4, s34, v5
	v_bfe_u32 v3, v60, 16, 1
	v_bfe_u32 v5, v62, 16, 1
	v_bfe_u32 v7, v19, 16, 1
	v_bfe_u32 v8, v18, 16, 1
	v_add3_u32 v6, v9, v6, s33
	v_readlane_b32 s78, v255, 0
	v_bfe_u32 v0, v16, 16, 1
	v_bfe_u32 v1, v63, 16, 1
	v_bfe_u32 v4, v61, 16, 1
	v_add3_u32 v3, v60, v3, s33
	v_add3_u32 v8, v18, v8, s33
	v_add3_u32 v7, v19, v7, s33
	v_add3_u32 v5, v62, v5, s33
	v_lshrrev_b32_e32 v6, 16, v6
	v_readlane_b32 s79, v255, 1
	v_add3_u32 v4, v61, v4, s33
	v_add3_u32 v1, v63, v1, s33
	v_add3_u32 v0, v16, v0, s33
	v_lshrrev_b32_e32 v5, 16, v5
	v_lshrrev_b32_e32 v7, 16, v7
	v_lshrrev_b32_e32 v8, 16, v8
	v_and_or_b32 v21, v3, s34, v6
	v_bfe_u32 v6, v17, 16, 1
	s_load_dword s77, s[78:79], 0xb8
	v_and_or_b32 v23, v0, s34, v8
	v_and_or_b32 v22, v1, s34, v7
	v_and_or_b32 v20, v4, s34, v5
	v_bfe_u32 v3, v64, 16, 1
	v_bfe_u32 v5, v66, 16, 1
	v_bfe_u32 v7, v59, 16, 1
	v_bfe_u32 v8, v58, 16, 1
	v_add3_u32 v6, v17, v6, s33
	s_waitcnt vmcnt(0) lgkmcnt(0)
	s_mov_b32 s0, s35
	v_bfe_u32 v0, v56, 16, 1
	v_bfe_u32 v1, v57, 16, 1
	v_bfe_u32 v4, v65, 16, 1
	v_add3_u32 v3, v64, v3, s33
	v_add3_u32 v8, v58, v8, s33
	v_add3_u32 v7, v59, v7, s33
	v_add3_u32 v5, v66, v5, s33
	v_lshrrev_b32_e32 v6, 16, v6
	s_barrier
	s_ashr_i32 s1, s0, 31
	v_add3_u32 v4, v65, v4, s33
	v_add3_u32 v1, v57, v1, s33
	v_add3_u32 v0, v56, v0, s33
	v_lshrrev_b32_e32 v5, 16, v5
	v_lshrrev_b32_e32 v7, 16, v7
	v_lshrrev_b32_e32 v8, 16, v8
	v_and_or_b32 v17, v3, s34, v6
	v_bfe_u32 v6, v54, 16, 1
	s_lshr_b32 s2, s1, 28
	v_and_or_b32 v19, v0, s34, v8
	v_and_or_b32 v18, v1, s34, v7
	v_and_or_b32 v16, v4, s34, v5
	v_bfe_u32 v3, v52, 16, 1
	v_bfe_u32 v5, v55, 16, 1
	v_bfe_u32 v7, v51, 16, 1
	v_bfe_u32 v8, v50, 16, 1
	v_add3_u32 v6, v54, v6, s33
	s_add_i32 s2, s0, s2
	v_bfe_u32 v0, v48, 16, 1
	v_bfe_u32 v1, v49, 16, 1
	v_bfe_u32 v4, v53, 16, 1
	v_add3_u32 v3, v52, v3, s33
	v_add3_u32 v8, v50, v8, s33
	v_add3_u32 v7, v51, v7, s33
	v_add3_u32 v5, v55, v5, s33
	v_lshrrev_b32_e32 v6, 16, v6
	s_ashr_i32 s2, s2, 4
	v_add3_u32 v4, v53, v4, s33
	v_add3_u32 v1, v49, v1, s33
	v_add3_u32 v0, v48, v0, s33
	v_lshrrev_b32_e32 v5, 16, v5
	v_lshrrev_b32_e32 v7, 16, v7
	v_lshrrev_b32_e32 v8, 16, v8
	v_and_or_b32 v13, v3, s34, v6
	v_bfe_u32 v6, v46, 16, 1
	s_lshr_b32 s3, s2, 30
	v_and_or_b32 v15, v0, s34, v8
	v_and_or_b32 v14, v1, s34, v7
	v_and_or_b32 v12, v4, s34, v5
	v_bfe_u32 v3, v44, 16, 1
	v_bfe_u32 v5, v47, 16, 1
	v_bfe_u32 v7, v43, 16, 1
	v_bfe_u32 v8, v42, 16, 1
	v_add3_u32 v6, v46, v6, s33
	s_add_i32 s3, s2, s3
	v_bfe_u32 v0, v40, 16, 1
	v_bfe_u32 v1, v41, 16, 1
	v_bfe_u32 v4, v45, 16, 1
	v_add3_u32 v3, v44, v3, s33
	v_add3_u32 v8, v42, v8, s33
	v_add3_u32 v7, v43, v7, s33
	v_add3_u32 v5, v47, v5, s33
	v_lshrrev_b32_e32 v6, 16, v6
	s_and_b32 s3, s3, 0xfffffc
	s_lshr_b32 s1, s1, 26
	v_add3_u32 v4, v45, v4, s33
	v_add3_u32 v1, v41, v1, s33
	v_add3_u32 v0, v40, v0, s33
	v_lshrrev_b32_e32 v5, 16, v5
	v_lshrrev_b32_e32 v7, 16, v7
	v_lshrrev_b32_e32 v8, 16, v8
	v_and_or_b32 v9, v3, s34, v6
	v_bfe_u32 v3, v36, 16, 1
	s_sub_i32 s2, s2, s3
	s_add_i32 s3, s0, s1
	v_and_or_b32 v11, v0, s34, v8
	v_and_or_b32 v10, v1, s34, v7
	v_and_or_b32 v8, v4, s34, v5
	v_add3_u32 v3, v36, v3, s33
	v_bfe_u32 v5, v39, 16, 1
	v_bfe_u32 v6, v38, 16, 1
	v_bfe_u32 v7, v35, 16, 1
	v_bfe_u32 v36, v34, 16, 1
	s_lshl_b32 s0, s2, 8
	s_lshl_b32 s2, s3, 2
	v_bfe_u32 v0, v67, 16, 1
	v_add3_u32 v34, v34, v36, s33
	v_add3_u32 v7, v35, v7, s33
	v_add3_u32 v6, v38, v6, s33
	v_add3_u32 v5, v39, v5, s33
	s_and_b32 s2, s2, 0xffffff00
	v_bfe_u32 v4, v37, 16, 1
	v_add3_u32 v0, v67, v0, s33
	v_lshrrev_b32_e32 v35, 16, v5
	v_lshrrev_b32_e32 v5, 16, v6
	v_lshrrev_b32_e32 v6, 16, v7
	v_lshrrev_b32_e32 v7, 16, v34
	s_ashr_i32 s3, s2, 31
	v_bfe_u32 v1, v68, 16, 1
	v_add3_u32 v4, v37, v4, s33
	v_and_or_b32 v7, v0, s34, v7
	v_and_or_b32 v5, v3, s34, v5
	v_bfe_u32 v0, v2, 16, 1
	v_bfe_u32 v3, v71, 16, 1
	s_ashr_i32 s1, s0, 31
	s_lshl_b64 s[2:3], s[2:3], 13
	v_readlane_b32 s4, v255, 15
	v_add3_u32 v1, v68, v1, s33
	v_and_or_b32 v4, v4, s34, v35
	v_add3_u32 v35, v71, v3, s33
	v_add3_u32 v0, v2, v0, s33
	v_bfe_u32 v2, v70, 16, 1
	v_bfe_u32 v3, v69, 16, 1
	v_bfe_u32 v36, v74, 16, 1
	s_add_u32 s2, s4, s2
	v_readlane_b32 s4, v255, 16
	v_readlane_b32 s81, v255, 2
	v_and_or_b32 v6, v1, s34, v6
	v_bfe_u32 v1, v75, 16, 1
	v_bfe_u32 v37, v73, 16, 1
	v_add3_u32 v36, v74, v36, s33
	v_add3_u32 v3, v69, v3, s33
	v_add3_u32 v2, v70, v2, s33
	s_addc_u32 s3, s4, s3
	s_lshl_b64 s[0:1], s[0:1], 1
	v_bfe_u32 v34, v72, 16, 1
	v_add3_u32 v1, v75, v1, s33
	v_add3_u32 v37, v73, v37, s33
	v_lshrrev_b32_e32 v38, 16, v2
	v_lshrrev_b32_e32 v39, 16, v3
	v_lshrrev_b32_e32 v2, 16, v36
	s_add_u32 s0, s2, s0
	s_mov_b32 s2, s81
	v_add3_u32 v34, v72, v34, s33
	v_lshrrev_b32_e32 v3, 16, v37
	v_and_or_b32 v2, v1, s34, v2
	v_and_or_b32 v1, v35, s34, v39
	v_and_or_b32 v3, v0, s34, v3
	v_lshl_add_u32 v35, s2, 1, v109
	v_and_or_b32 v0, v34, s34, v38
	v_max_i32_e32 v34, 0, v35
	v_lshlrev_b32_e32 v35, 1, v35
	v_bitop3_b32 v36, v35, v110, 14 bitop3:0x6c
	v_mov_b32_e32 v35, v91
	s_addc_u32 s1, s3, s1
	v_lshlrev_b64 v[34:35], 13, v[34:35]
	v_lshl_add_u64 v[34:35], s[0:1], 0, v[34:35]
	v_lshlrev_b32_e32 v36, 4, v36
	v_mov_b32_e32 v37, v91
	v_lshl_add_u64 v[34:35], v[34:35], 0, v[36:37]
	s_mov_b64 s[4:5], 0x800
	s_lshl_b32 s3, s2, 10
	v_lshl_add_u64 v[34:35], v[34:35], 0, s[4:5]
	s_add_i32 m0, s3, 0
	s_add_i32 s3, s2, 8
	global_load_lds_dwordx4 v[34:35], off
	v_lshl_add_u32 v35, s3, 1, v109
	v_max_i32_e32 v34, 0, v35
	v_lshlrev_b32_e32 v35, 1, v35
	v_bitop3_b32 v36, v35, v110, 14 bitop3:0x6c
	v_mov_b32_e32 v35, v91
	v_lshlrev_b64 v[34:35], 13, v[34:35]
	v_lshl_add_u64 v[34:35], s[0:1], 0, v[34:35]
	v_lshlrev_b32_e32 v36, 4, v36
	v_lshl_add_u64 v[34:35], v[34:35], 0, v[36:37]
	s_lshl_b32 s3, s3, 10
	v_lshl_add_u64 v[34:35], v[34:35], 0, s[4:5]
	s_add_i32 m0, s3, 0
	s_add_i32 s3, s2, 16
	global_load_lds_dwordx4 v[34:35], off
	v_lshl_add_u32 v35, s3, 1, v109
	v_max_i32_e32 v34, 0, v35
	v_lshlrev_b32_e32 v35, 1, v35
	v_bitop3_b32 v36, v35, v110, 14 bitop3:0x6c
	v_mov_b32_e32 v35, v91
	v_lshlrev_b64 v[34:35], 13, v[34:35]
	v_lshl_add_u64 v[34:35], s[0:1], 0, v[34:35]
	v_lshlrev_b32_e32 v36, 4, v36
	v_lshl_add_u64 v[34:35], v[34:35], 0, v[36:37]
	s_lshl_b32 s3, s3, 10
	v_lshl_add_u64 v[34:35], v[34:35], 0, s[4:5]
	s_add_i32 m0, s3, 0
	s_add_i32 s3, s2, 24
	global_load_lds_dwordx4 v[34:35], off
	v_lshl_add_u32 v35, s3, 1, v109
	v_max_i32_e32 v34, 0, v35
	v_lshlrev_b32_e32 v35, 1, v35
	v_bitop3_b32 v36, v35, v110, 14 bitop3:0x6c
	v_mov_b32_e32 v35, v91
	v_lshlrev_b64 v[34:35], 13, v[34:35]
	v_lshl_add_u64 v[34:35], s[0:1], 0, v[34:35]
	v_lshlrev_b32_e32 v36, 4, v36
	v_lshl_add_u64 v[34:35], v[34:35], 0, v[36:37]
	s_lshl_b32 s3, s3, 10
	v_lshl_add_u64 v[34:35], v[34:35], 0, s[4:5]
	s_add_i32 m0, s3, 0
	s_add_i32 s3, s2, 32
	global_load_lds_dwordx4 v[34:35], off
	v_lshl_add_u32 v35, s3, 1, v109
	v_max_i32_e32 v34, 0, v35
	v_lshlrev_b32_e32 v35, 1, v35
	v_bitop3_b32 v36, v35, v110, 14 bitop3:0x6c
	v_mov_b32_e32 v35, v91
	v_lshlrev_b64 v[34:35], 13, v[34:35]
	v_lshl_add_u64 v[34:35], s[0:1], 0, v[34:35]
	v_lshlrev_b32_e32 v36, 4, v36
	v_lshl_add_u64 v[34:35], v[34:35], 0, v[36:37]
	s_lshl_b32 s3, s3, 10
	v_lshl_add_u64 v[34:35], v[34:35], 0, s[4:5]
	s_add_i32 m0, s3, 0
	s_add_i32 s3, s2, 40
	global_load_lds_dwordx4 v[34:35], off
	v_lshl_add_u32 v35, s3, 1, v109
	v_max_i32_e32 v34, 0, v35
	v_lshlrev_b32_e32 v35, 1, v35
	v_bitop3_b32 v36, v35, v110, 14 bitop3:0x6c
	v_mov_b32_e32 v35, v91
	v_lshlrev_b64 v[34:35], 13, v[34:35]
	v_lshl_add_u64 v[34:35], s[0:1], 0, v[34:35]
	v_lshlrev_b32_e32 v36, 4, v36
	v_lshl_add_u64 v[34:35], v[34:35], 0, v[36:37]
	s_lshl_b32 s3, s3, 10
	v_lshl_add_u64 v[34:35], v[34:35], 0, s[4:5]
	s_add_i32 m0, s3, 0
	s_add_i32 s3, s2, 48
	global_load_lds_dwordx4 v[34:35], off
	v_lshl_add_u32 v35, s3, 1, v109
	v_max_i32_e32 v34, 0, v35
	v_lshlrev_b32_e32 v35, 1, v35
	v_bitop3_b32 v36, v35, v110, 14 bitop3:0x6c
	v_mov_b32_e32 v35, v91
	v_lshlrev_b64 v[34:35], 13, v[34:35]
	v_lshl_add_u64 v[34:35], s[0:1], 0, v[34:35]
	v_lshlrev_b32_e32 v36, 4, v36
	v_lshl_add_u64 v[34:35], v[34:35], 0, v[36:37]
	s_lshl_b32 s3, s3, 10
	v_lshl_add_u64 v[34:35], v[34:35], 0, s[4:5]
	s_add_i32 m0, s3, 0
	s_add_i32 s3, s2, 56
	global_load_lds_dwordx4 v[34:35], off
	v_lshl_add_u32 v35, s3, 1, v109
	v_max_i32_e32 v34, 0, v35
	v_lshlrev_b32_e32 v35, 1, v35
	v_bitop3_b32 v36, v35, v110, 14 bitop3:0x6c
	v_mov_b32_e32 v35, v91
	v_lshlrev_b64 v[34:35], 13, v[34:35]
	v_lshl_add_u64 v[34:35], s[0:1], 0, v[34:35]
	v_lshlrev_b32_e32 v36, 4, v36
	v_lshl_add_u64 v[34:35], v[34:35], 0, v[36:37]
	s_lshl_b32 s3, s3, 10
	v_lshl_add_u64 v[34:35], v[34:35], 0, s[4:5]
	s_add_i32 m0, s3, 0
	s_add_i32 s3, s2, 64
	global_load_lds_dwordx4 v[34:35], off
	v_lshl_add_u32 v35, s3, 1, v109
	v_max_i32_e32 v34, 0, v35
	v_lshlrev_b32_e32 v35, 1, v35
	v_bitop3_b32 v36, v35, v110, 14 bitop3:0x6c
	v_mov_b32_e32 v35, v91
	v_lshlrev_b64 v[34:35], 13, v[34:35]
	v_lshl_add_u64 v[34:35], s[0:1], 0, v[34:35]
	v_lshlrev_b32_e32 v36, 4, v36
	v_lshl_add_u64 v[34:35], v[34:35], 0, v[36:37]
	s_lshl_b32 s3, s3, 10
	v_lshl_add_u64 v[34:35], v[34:35], 0, s[4:5]
	s_add_i32 m0, s3, 0
	s_add_i32 s3, s2, 0x48
	global_load_lds_dwordx4 v[34:35], off
	v_lshl_add_u32 v35, s3, 1, v109
	v_max_i32_e32 v34, 0, v35
	v_lshlrev_b32_e32 v35, 1, v35
	v_bitop3_b32 v36, v35, v110, 14 bitop3:0x6c
	v_mov_b32_e32 v35, v91
	v_lshlrev_b64 v[34:35], 13, v[34:35]
	v_lshl_add_u64 v[34:35], s[0:1], 0, v[34:35]
	v_lshlrev_b32_e32 v36, 4, v36
	v_lshl_add_u64 v[34:35], v[34:35], 0, v[36:37]
	s_lshl_b32 s3, s3, 10
	v_lshl_add_u64 v[34:35], v[34:35], 0, s[4:5]
	s_add_i32 m0, s3, 0
	s_add_i32 s3, s2, 0x50
	global_load_lds_dwordx4 v[34:35], off
	v_lshl_add_u32 v35, s3, 1, v109
	v_max_i32_e32 v34, 0, v35
	v_lshlrev_b32_e32 v35, 1, v35
	v_bitop3_b32 v36, v35, v110, 14 bitop3:0x6c
	v_mov_b32_e32 v35, v91
	v_lshlrev_b64 v[34:35], 13, v[34:35]
	v_lshl_add_u64 v[34:35], s[0:1], 0, v[34:35]
	v_lshlrev_b32_e32 v36, 4, v36
	v_lshl_add_u64 v[34:35], v[34:35], 0, v[36:37]
	s_lshl_b32 s3, s3, 10
	v_lshl_add_u64 v[34:35], v[34:35], 0, s[4:5]
	s_add_i32 m0, s3, 0
	s_add_i32 s3, s2, 0x58
	global_load_lds_dwordx4 v[34:35], off
	v_lshl_add_u32 v35, s3, 1, v109
	v_max_i32_e32 v34, 0, v35
	v_lshlrev_b32_e32 v35, 1, v35
	v_bitop3_b32 v36, v35, v110, 14 bitop3:0x6c
	v_mov_b32_e32 v35, v91
	v_lshlrev_b64 v[34:35], 13, v[34:35]
	v_lshl_add_u64 v[34:35], s[0:1], 0, v[34:35]
	v_lshlrev_b32_e32 v36, 4, v36
	v_lshl_add_u64 v[34:35], v[34:35], 0, v[36:37]
	s_lshl_b32 s3, s3, 10
	v_lshl_add_u64 v[34:35], v[34:35], 0, s[4:5]
	s_add_i32 m0, s3, 0
	s_add_i32 s3, s2, 0x60
	global_load_lds_dwordx4 v[34:35], off
	v_lshl_add_u32 v35, s3, 1, v109
	v_max_i32_e32 v34, 0, v35
	v_lshlrev_b32_e32 v35, 1, v35
	v_bitop3_b32 v36, v35, v110, 14 bitop3:0x6c
	v_mov_b32_e32 v35, v91
	v_lshlrev_b64 v[34:35], 13, v[34:35]
	v_lshl_add_u64 v[34:35], s[0:1], 0, v[34:35]
	v_lshlrev_b32_e32 v36, 4, v36
	v_lshl_add_u64 v[34:35], v[34:35], 0, v[36:37]
	s_lshl_b32 s3, s3, 10
	v_lshl_add_u64 v[34:35], v[34:35], 0, s[4:5]
	s_add_i32 m0, s3, 0
	s_add_i32 s3, s2, 0x68
	global_load_lds_dwordx4 v[34:35], off
	v_lshl_add_u32 v35, s3, 1, v109
	v_max_i32_e32 v34, 0, v35
	v_lshlrev_b32_e32 v35, 1, v35
	v_bitop3_b32 v36, v35, v110, 14 bitop3:0x6c
	v_mov_b32_e32 v35, v91
	v_lshlrev_b64 v[34:35], 13, v[34:35]
	v_lshl_add_u64 v[34:35], s[0:1], 0, v[34:35]
	v_lshlrev_b32_e32 v36, 4, v36
	v_lshl_add_u64 v[34:35], v[34:35], 0, v[36:37]
	s_lshl_b32 s3, s3, 10
	v_lshl_add_u64 v[34:35], v[34:35], 0, s[4:5]
	s_add_i32 m0, s3, 0
	s_add_i32 s3, s2, 0x70
	global_load_lds_dwordx4 v[34:35], off
	v_lshl_add_u32 v35, s3, 1, v109
	v_max_i32_e32 v34, 0, v35
	v_lshlrev_b32_e32 v35, 1, v35
	v_bitop3_b32 v36, v35, v110, 14 bitop3:0x6c
	v_mov_b32_e32 v35, v91
	v_lshlrev_b64 v[34:35], 13, v[34:35]
	v_lshl_add_u64 v[34:35], s[0:1], 0, v[34:35]
	v_lshlrev_b32_e32 v36, 4, v36
	v_lshl_add_u64 v[34:35], v[34:35], 0, v[36:37]
	s_lshl_b32 s3, s3, 10
	v_lshl_add_u64 v[34:35], v[34:35], 0, s[4:5]
	s_add_i32 m0, s3, 0
	s_addk_i32 s2, 0x78
	global_load_lds_dwordx4 v[34:35], off
	v_lshl_add_u32 v35, s2, 1, v109
	v_max_i32_e32 v34, 0, v35
	v_lshlrev_b32_e32 v35, 1, v35
	v_bitop3_b32 v36, v35, v110, 14 bitop3:0x6c
	v_mov_b32_e32 v35, v91
	v_lshlrev_b64 v[34:35], 13, v[34:35]
	v_lshl_add_u64 v[34:35], s[0:1], 0, v[34:35]
	v_lshlrev_b32_e32 v36, 4, v36
	v_lshl_add_u64 v[34:35], v[34:35], 0, v[36:37]
	s_lshl_b32 s0, s2, 10
	v_lshl_add_u64 v[34:35], v[34:35], 0, s[4:5]
	s_add_i32 m0, s0, 0
	s_mov_b32 s0, s35
	global_load_lds_dwordx4 v[34:35], off
	s_waitcnt vmcnt(0) lgkmcnt(0)
	s_barrier
	s_ashr_i32 s1, s0, 31
	s_lshr_b32 s2, s1, 28
	s_add_i32 s2, s0, s2
	s_ashr_i32 s3, s2, 4
	s_lshr_b32 s4, s3, 30
	s_add_i32 s4, s3, s4
	s_and_b32 s4, s4, 0xfffffc
	s_sub_i32 s3, s3, s4
	s_mov_b32 s4, s81
	ds_read_b64_tr_b16 v[34:35], v176 offset:0
	ds_read_b64_tr_b16 v[36:37], v176 offset:0x2000
	ds_read_b64_tr_b16 v[38:39], v177 offset:0
	ds_read_b64_tr_b16 v[40:41], v177 offset:0x2000
	ds_read_b64_tr_b16 v[42:43], v178 offset:0
	s_and_b32 s2, s2, 0x1fffff0
	s_lshr_b32 s1, s1, 26
	ds_read_b64_tr_b16 v[44:45], v178 offset:0x2000
	ds_bpermute_b32 v33, v209, v32
	s_sub_i32 s2, s0, s2
	s_add_i32 s0, s0, s1
	ds_read_b64_tr_b16 v[46:47], v179 offset:0
	s_lshl_b32 s0, s0, 5
	ds_read_b64_tr_b16 v[48:49], v179 offset:0x2000
	s_and_b32 s0, s0, 0xfffff800
	s_lshl_b32 s1, s2, 7
	s_waitcnt lgkmcnt(0)
	s_add_i32 s0, s0, s1
	s_ashr_i32 s1, s0, 31
	s_lshl_b32 s2, s3, 8
	s_ashr_i32 s3, s2, 31
	s_lshl_b64 s[0:1], s[0:1], 11
	s_waitcnt lgkmcnt(0)
	v_add_f32_e32 v32, v32, v33
	ds_read_b64_tr_b16 v[50:51], v180 offset:0
	ds_read_b64_tr_b16 v[52:53], v180 offset:0x2000
	ds_read_b64_tr_b16 v[54:55], v181 offset:0
	ds_read_b64_tr_b16 v[56:57], v181 offset:0x2000
	ds_read_b64_tr_b16 v[58:59], v182 offset:0
	ds_read_b64_tr_b16 v[60:61], v182 offset:0x2000
	ds_read_b64_tr_b16 v[62:63], v183 offset:0
	ds_read_b64_tr_b16 v[64:65], v183 offset:0x2000
	s_waitcnt lgkmcnt(0)
	v_mfma_f32_16x16x32_bf16 v[34:37], v[34:37], v[28:31], 0
	v_mfma_f32_16x16x32_bf16 v[38:41], v[38:41], v[28:31], 0
	v_mfma_f32_16x16x32_bf16 v[42:45], v[42:45], v[28:31], 0
	v_mfma_f32_16x16x32_bf16 v[46:49], v[46:49], v[28:31], 0
	ds_read_b64_tr_b16 v[66:67], v184 offset:0
	ds_read_b64_tr_b16 v[68:69], v184 offset:0x2000
	ds_read_b64_tr_b16 v[70:71], v185 offset:0
	ds_read_b64_tr_b16 v[72:73], v185 offset:0x2000
	ds_read_b64_tr_b16 v[74:75], v186 offset:0
	ds_read_b64_tr_b16 v[76:77], v186 offset:0x2000
	ds_read_b64_tr_b16 v[78:79], v187 offset:0
	ds_read_b64_tr_b16 v[80:81], v187 offset:0x2000
	s_waitcnt lgkmcnt(0)
	v_mfma_f32_16x16x32_bf16 v[50:53], v[50:53], v[28:31], 0
	v_mfma_f32_16x16x32_bf16 v[54:57], v[54:57], v[28:31], 0
	v_mfma_f32_16x16x32_bf16 v[58:61], v[58:61], v[28:31], 0
	v_mfma_f32_16x16x32_bf16 v[62:65], v[62:65], v[28:31], 0
	ds_read_b64_tr_b16 v[82:83], v188 offset:0
	ds_read_b64_tr_b16 v[84:85], v188 offset:0x2000
	ds_read_b64_tr_b16 v[210:211], v189 offset:0
	ds_read_b64_tr_b16 v[212:213], v189 offset:0x2000
	ds_read_b64_tr_b16 v[214:215], v190 offset:0
	ds_read_b64_tr_b16 v[216:217], v190 offset:0x2000
	ds_read_b64_tr_b16 v[218:219], v191 offset:0
	ds_read_b64_tr_b16 v[220:221], v191 offset:0x2000
	s_waitcnt lgkmcnt(0)
	v_mfma_f32_16x16x32_bf16 v[66:69], v[66:69], v[28:31], 0
	v_mfma_f32_16x16x32_bf16 v[70:73], v[70:73], v[28:31], 0
	v_mfma_f32_16x16x32_bf16 v[74:77], v[74:77], v[28:31], 0
	v_mfma_f32_16x16x32_bf16 v[78:81], v[78:81], v[28:31], 0
	ds_read_b64_tr_b16 v[222:223], v176 offset:0x4000
	ds_read_b64_tr_b16 v[224:225], v176 offset:0x6000
	ds_read_b64_tr_b16 v[226:227], v177 offset:0x4000
	ds_read_b64_tr_b16 v[228:229], v177 offset:0x6000
	ds_read_b64_tr_b16 v[230:231], v178 offset:0x4000
	ds_read_b64_tr_b16 v[232:233], v178 offset:0x6000
	ds_read_b64_tr_b16 v[234:235], v179 offset:0x4000
	ds_read_b64_tr_b16 v[236:237], v179 offset:0x6000
	s_waitcnt lgkmcnt(0)
	v_mfma_f32_16x16x32_bf16 v[82:85], v[82:85], v[28:31], 0
	v_mfma_f32_16x16x32_bf16 v[210:213], v[210:213], v[28:31], 0
	v_mfma_f32_16x16x32_bf16 v[214:217], v[214:217], v[28:31], 0
	v_mfma_f32_16x16x32_bf16 v[28:31], v[218:221], v[28:31], 0
	ds_read_b64_tr_b16 v[218:219], v180 offset:0x4000
	ds_read_b64_tr_b16 v[220:221], v180 offset:0x6000
	v_mfma_f32_16x16x32_bf16 v[34:37], v[222:225], v[24:27], v[34:37]
	ds_read_b64_tr_b16 v[222:223], v181 offset:0x4000
	ds_read_b64_tr_b16 v[224:225], v181 offset:0x6000
	v_mfma_f32_16x16x32_bf16 v[38:41], v[226:229], v[24:27], v[38:41]
	ds_read_b64_tr_b16 v[226:227], v182 offset:0x4000
	ds_read_b64_tr_b16 v[228:229], v182 offset:0x6000
	v_mfma_f32_16x16x32_bf16 v[42:45], v[230:233], v[24:27], v[42:45]
	ds_read_b64_tr_b16 v[230:231], v183 offset:0x4000
	ds_read_b64_tr_b16 v[232:233], v183 offset:0x6000
	s_waitcnt lgkmcnt(0)
	v_mfma_f32_16x16x32_bf16 v[46:49], v[234:237], v[24:27], v[46:49]
	v_mfma_f32_16x16x32_bf16 v[50:53], v[218:221], v[24:27], v[50:53]
	ds_read_b64_tr_b16 v[218:219], v184 offset:0x4000
	ds_read_b64_tr_b16 v[220:221], v184 offset:0x6000
	v_mfma_f32_16x16x32_bf16 v[54:57], v[222:225], v[24:27], v[54:57]
	ds_read_b64_tr_b16 v[222:223], v185 offset:0x4000
	ds_read_b64_tr_b16 v[224:225], v185 offset:0x6000
	ds_read_b64_tr_b16 v[234:235], v186 offset:0x4000
	ds_read_b64_tr_b16 v[236:237], v186 offset:0x6000
	v_mfma_f32_16x16x32_bf16 v[58:61], v[226:229], v[24:27], v[58:61]
	ds_read_b64_tr_b16 v[226:227], v187 offset:0x4000
	ds_read_b64_tr_b16 v[228:229], v187 offset:0x6000
	s_waitcnt lgkmcnt(0)
	v_mfma_f32_16x16x32_bf16 v[62:65], v[230:233], v[24:27], v[62:65]
	v_mfma_f32_16x16x32_bf16 v[66:69], v[218:221], v[24:27], v[66:69]
	ds_read_b64_tr_b16 v[218:219], v188 offset:0x4000
	ds_read_b64_tr_b16 v[220:221], v188 offset:0x6000
	v_mfma_f32_16x16x32_bf16 v[70:73], v[222:225], v[24:27], v[70:73]
	ds_read_b64_tr_b16 v[222:223], v189 offset:0x4000
	ds_read_b64_tr_b16 v[224:225], v189 offset:0x6000
	ds_read_b64_tr_b16 v[230:231], v190 offset:0x4000
	ds_read_b64_tr_b16 v[232:233], v190 offset:0x6000
	v_mfma_f32_16x16x32_bf16 v[74:77], v[234:237], v[24:27], v[74:77]
	ds_read_b64_tr_b16 v[234:235], v191 offset:0x4000
	ds_read_b64_tr_b16 v[236:237], v191 offset:0x6000
	s_waitcnt lgkmcnt(0)
	v_mfma_f32_16x16x32_bf16 v[78:81], v[226:229], v[24:27], v[78:81]
	v_mfma_f32_16x16x32_bf16 v[82:85], v[218:221], v[24:27], v[82:85]
	ds_read_b64_tr_b16 v[218:219], v176 offset:0x8000
	ds_read_b64_tr_b16 v[220:221], v176 offset:0xa000
	v_mfma_f32_16x16x32_bf16 v[210:213], v[222:225], v[24:27], v[210:213]
	ds_read_b64_tr_b16 v[222:223], v177 offset:0x8000
	ds_read_b64_tr_b16 v[224:225], v177 offset:0xa000
	ds_read_b64_tr_b16 v[226:227], v178 offset:0x8000
	ds_read_b64_tr_b16 v[228:229], v178 offset:0xa000
	v_mfma_f32_16x16x32_bf16 v[214:217], v[230:233], v[24:27], v[214:217]
	ds_read_b64_tr_b16 v[230:231], v179 offset:0x8000
	ds_read_b64_tr_b16 v[232:233], v179 offset:0xa000
	s_waitcnt lgkmcnt(0)
	v_mfma_f32_16x16x32_bf16 v[24:27], v[234:237], v[24:27], v[28:31]
	v_mfma_f32_16x16x32_bf16 v[28:31], v[218:221], v[20:23], v[34:37]
	ds_read_b64_tr_b16 v[34:35], v180 offset:0x8000
	ds_read_b64_tr_b16 v[36:37], v180 offset:0xa000
	ds_read_b64_tr_b16 v[218:219], v181 offset:0x8000
	ds_read_b64_tr_b16 v[220:221], v181 offset:0xa000
	v_mfma_f32_16x16x32_bf16 v[38:41], v[222:225], v[20:23], v[38:41]
	ds_read_b64_tr_b16 v[222:223], v182 offset:0x8000
	ds_read_b64_tr_b16 v[224:225], v182 offset:0xa000
	v_mfma_f32_16x16x32_bf16 v[42:45], v[226:229], v[20:23], v[42:45]
	ds_read_b64_tr_b16 v[226:227], v183 offset:0x8000
	ds_read_b64_tr_b16 v[228:229], v183 offset:0xa000
	s_waitcnt lgkmcnt(0)
	v_mfma_f32_16x16x32_bf16 v[46:49], v[230:233], v[20:23], v[46:49]
	v_mfma_f32_16x16x32_bf16 v[34:37], v[34:37], v[20:23], v[50:53]
	ds_read_b64_tr_b16 v[50:51], v184 offset:0x8000
	ds_read_b64_tr_b16 v[52:53], v184 offset:0xa000
	v_mfma_f32_16x16x32_bf16 v[54:57], v[218:221], v[20:23], v[54:57]
	ds_read_b64_tr_b16 v[218:219], v185 offset:0x8000
	ds_read_b64_tr_b16 v[220:221], v185 offset:0xa000
	ds_read_b64_tr_b16 v[230:231], v186 offset:0x8000
	ds_read_b64_tr_b16 v[232:233], v186 offset:0xa000
	v_mfma_f32_16x16x32_bf16 v[58:61], v[222:225], v[20:23], v[58:61]
	ds_read_b64_tr_b16 v[222:223], v187 offset:0x8000
	ds_read_b64_tr_b16 v[224:225], v187 offset:0xa000
	s_waitcnt lgkmcnt(0)
	v_mfma_f32_16x16x32_bf16 v[62:65], v[226:229], v[20:23], v[62:65]
	v_mfma_f32_16x16x32_bf16 v[50:53], v[50:53], v[20:23], v[66:69]
	ds_read_b64_tr_b16 v[66:67], v188 offset:0x8000
	ds_read_b64_tr_b16 v[68:69], v188 offset:0xa000
	v_mfma_f32_16x16x32_bf16 v[70:73], v[218:221], v[20:23], v[70:73]
	ds_read_b64_tr_b16 v[218:219], v189 offset:0x8000
	ds_read_b64_tr_b16 v[220:221], v189 offset:0xa000
	ds_read_b64_tr_b16 v[226:227], v190 offset:0x8000
	ds_read_b64_tr_b16 v[228:229], v190 offset:0xa000
	v_mfma_f32_16x16x32_bf16 v[74:77], v[230:233], v[20:23], v[74:77]
	ds_read_b64_tr_b16 v[230:231], v191 offset:0x8000
	ds_read_b64_tr_b16 v[232:233], v191 offset:0xa000
	s_waitcnt lgkmcnt(0)
	v_mfma_f32_16x16x32_bf16 v[78:81], v[222:225], v[20:23], v[78:81]
	v_mfma_f32_16x16x32_bf16 v[66:69], v[66:69], v[20:23], v[82:85]
	ds_read_b64_tr_b16 v[82:83], v176 offset:0xc000
	ds_read_b64_tr_b16 v[84:85], v176 offset:0xe000
	v_mfma_f32_16x16x32_bf16 v[210:213], v[218:221], v[20:23], v[210:213]
	ds_read_b64_tr_b16 v[218:219], v177 offset:0xc000
	ds_read_b64_tr_b16 v[220:221], v177 offset:0xe000
	ds_read_b64_tr_b16 v[222:223], v178 offset:0xc000
	ds_read_b64_tr_b16 v[224:225], v178 offset:0xe000
	v_mfma_f32_16x16x32_bf16 v[214:217], v[226:229], v[20:23], v[214:217]
	ds_read_b64_tr_b16 v[226:227], v179 offset:0xc000
	ds_read_b64_tr_b16 v[228:229], v179 offset:0xe000
	s_waitcnt lgkmcnt(0)
	v_mfma_f32_16x16x32_bf16 v[20:23], v[230:233], v[20:23], v[24:27]
	v_mfma_f32_16x16x32_bf16 v[24:27], v[82:85], v[16:19], v[28:31]
	ds_read_b64_tr_b16 v[28:29], v180 offset:0xc000
	ds_read_b64_tr_b16 v[30:31], v180 offset:0xe000
	ds_read_b64_tr_b16 v[82:83], v181 offset:0xc000
	ds_read_b64_tr_b16 v[84:85], v181 offset:0xe000
	v_mfma_f32_16x16x32_bf16 v[38:41], v[218:221], v[16:19], v[38:41]
	ds_read_b64_tr_b16 v[218:219], v182 offset:0xc000
	ds_read_b64_tr_b16 v[220:221], v182 offset:0xe000
	v_mfma_f32_16x16x32_bf16 v[42:45], v[222:225], v[16:19], v[42:45]
	ds_read_b64_tr_b16 v[222:223], v183 offset:0xc000
	ds_read_b64_tr_b16 v[224:225], v183 offset:0xe000
	s_waitcnt lgkmcnt(0)
	v_mfma_f32_16x16x32_bf16 v[46:49], v[226:229], v[16:19], v[46:49]
	v_mfma_f32_16x16x32_bf16 v[28:31], v[28:31], v[16:19], v[34:37]
	ds_read_b64_tr_b16 v[34:35], v184 offset:0xc000
	ds_read_b64_tr_b16 v[36:37], v184 offset:0xe000
	v_mfma_f32_16x16x32_bf16 v[54:57], v[82:85], v[16:19], v[54:57]
	ds_read_b64_tr_b16 v[82:83], v185 offset:0xc000
	ds_read_b64_tr_b16 v[84:85], v185 offset:0xe000
	ds_read_b64_tr_b16 v[226:227], v186 offset:0xc000
	ds_read_b64_tr_b16 v[228:229], v186 offset:0xe000
	v_mfma_f32_16x16x32_bf16 v[58:61], v[218:221], v[16:19], v[58:61]
	ds_read_b64_tr_b16 v[218:219], v187 offset:0xc000
	ds_read_b64_tr_b16 v[220:221], v187 offset:0xe000
	s_waitcnt lgkmcnt(0)
	v_mfma_f32_16x16x32_bf16 v[62:65], v[222:225], v[16:19], v[62:65]
	v_mfma_f32_16x16x32_bf16 v[34:37], v[34:37], v[16:19], v[50:53]
	ds_read_b64_tr_b16 v[50:51], v188 offset:0xc000
	ds_read_b64_tr_b16 v[52:53], v188 offset:0xe000
	v_mfma_f32_16x16x32_bf16 v[70:73], v[82:85], v[16:19], v[70:73]
	ds_read_b64_tr_b16 v[82:83], v189 offset:0xc000
	ds_read_b64_tr_b16 v[84:85], v189 offset:0xe000
	ds_read_b64_tr_b16 v[222:223], v190 offset:0xc000
	ds_read_b64_tr_b16 v[224:225], v190 offset:0xe000
	v_mfma_f32_16x16x32_bf16 v[74:77], v[226:229], v[16:19], v[74:77]
	ds_read_b64_tr_b16 v[226:227], v191 offset:0xc000
	ds_read_b64_tr_b16 v[228:229], v191 offset:0xe000
	s_waitcnt lgkmcnt(0)
	v_mfma_f32_16x16x32_bf16 v[78:81], v[218:221], v[16:19], v[78:81]
	v_mfma_f32_16x16x32_bf16 v[50:53], v[50:53], v[16:19], v[66:69]
	ds_read_b64_tr_b16 v[66:67], v192 offset:0
	ds_read_b64_tr_b16 v[68:69], v192 offset:0x2000
	v_mfma_f32_16x16x32_bf16 v[82:85], v[82:85], v[16:19], v[210:213]
	ds_read_b64_tr_b16 v[210:211], v193 offset:0
	ds_read_b64_tr_b16 v[212:213], v193 offset:0x2000
	ds_read_b64_tr_b16 v[218:219], v194 offset:0
	ds_read_b64_tr_b16 v[220:221], v194 offset:0x2000
	v_mfma_f32_16x16x32_bf16 v[214:217], v[222:225], v[16:19], v[214:217]
	ds_read_b64_tr_b16 v[222:223], v195 offset:0
	ds_read_b64_tr_b16 v[224:225], v195 offset:0x2000
	s_waitcnt lgkmcnt(0)
	v_mfma_f32_16x16x32_bf16 v[16:19], v[226:229], v[16:19], v[20:23]
	v_mfma_f32_16x16x32_bf16 v[20:23], v[66:69], v[12:15], v[24:27]
	ds_read_b64_tr_b16 v[24:25], v196 offset:0
	ds_read_b64_tr_b16 v[26:27], v196 offset:0x2000
	ds_read_b64_tr_b16 v[66:67], v197 offset:0
	ds_read_b64_tr_b16 v[68:69], v197 offset:0x2000
	v_mfma_f32_16x16x32_bf16 v[38:41], v[210:213], v[12:15], v[38:41]
	ds_read_b64_tr_b16 v[210:211], v198 offset:0
	ds_read_b64_tr_b16 v[212:213], v198 offset:0x2000
	v_mfma_f32_16x16x32_bf16 v[42:45], v[218:221], v[12:15], v[42:45]
	ds_read_b64_tr_b16 v[218:219], v199 offset:0
	ds_read_b64_tr_b16 v[220:221], v199 offset:0x2000
	s_waitcnt lgkmcnt(0)
	v_mfma_f32_16x16x32_bf16 v[46:49], v[222:225], v[12:15], v[46:49]
	v_mfma_f32_16x16x32_bf16 v[24:27], v[24:27], v[12:15], v[28:31]
	ds_read_b64_tr_b16 v[28:29], v200 offset:0
	ds_read_b64_tr_b16 v[30:31], v200 offset:0x2000
	v_mfma_f32_16x16x32_bf16 v[54:57], v[66:69], v[12:15], v[54:57]
	ds_read_b64_tr_b16 v[66:67], v201 offset:0
	ds_read_b64_tr_b16 v[68:69], v201 offset:0x2000
	ds_read_b64_tr_b16 v[222:223], v202 offset:0
	ds_read_b64_tr_b16 v[224:225], v202 offset:0x2000
	v_mfma_f32_16x16x32_bf16 v[58:61], v[210:213], v[12:15], v[58:61]
	ds_read_b64_tr_b16 v[210:211], v203 offset:0
	ds_read_b64_tr_b16 v[212:213], v203 offset:0x2000
	s_waitcnt lgkmcnt(0)
	v_mfma_f32_16x16x32_bf16 v[62:65], v[218:221], v[12:15], v[62:65]
	v_mfma_f32_16x16x32_bf16 v[28:31], v[28:31], v[12:15], v[34:37]
	ds_read_b64_tr_b16 v[34:35], v204 offset:0
	ds_read_b64_tr_b16 v[36:37], v204 offset:0x2000
	v_mfma_f32_16x16x32_bf16 v[66:69], v[66:69], v[12:15], v[70:73]
	ds_read_b64_tr_b16 v[70:71], v205 offset:0
	ds_read_b64_tr_b16 v[72:73], v205 offset:0x2000
	ds_read_b64_tr_b16 v[218:219], v206 offset:0
	ds_read_b64_tr_b16 v[220:221], v206 offset:0x2000
	v_mfma_f32_16x16x32_bf16 v[74:77], v[222:225], v[12:15], v[74:77]
	ds_read_b64_tr_b16 v[222:223], v207 offset:0
	ds_read_b64_tr_b16 v[224:225], v207 offset:0x2000
	s_waitcnt lgkmcnt(0)
	v_mfma_f32_16x16x32_bf16 v[78:81], v[210:213], v[12:15], v[78:81]
	v_mfma_f32_16x16x32_bf16 v[34:37], v[34:37], v[12:15], v[50:53]
	ds_read_b64_tr_b16 v[50:51], v192 offset:0x4000
	ds_read_b64_tr_b16 v[52:53], v192 offset:0x6000
	v_mfma_f32_16x16x32_bf16 v[70:73], v[70:73], v[12:15], v[82:85]
	ds_read_b64_tr_b16 v[82:83], v193 offset:0x4000
	ds_read_b64_tr_b16 v[84:85], v193 offset:0x6000
	ds_read_b64_tr_b16 v[210:211], v194 offset:0x4000
	ds_read_b64_tr_b16 v[212:213], v194 offset:0x6000
	v_mfma_f32_16x16x32_bf16 v[214:217], v[218:221], v[12:15], v[214:217]
	ds_read_b64_tr_b16 v[218:219], v195 offset:0x4000
	ds_read_b64_tr_b16 v[220:221], v195 offset:0x6000
	s_waitcnt lgkmcnt(0)
	v_mfma_f32_16x16x32_bf16 v[12:15], v[222:225], v[12:15], v[16:19]
	v_mfma_f32_16x16x32_bf16 v[16:19], v[50:53], v[8:11], v[20:23]
	ds_read_b64_tr_b16 v[20:21], v196 offset:0x4000
	ds_read_b64_tr_b16 v[22:23], v196 offset:0x6000
	ds_read_b64_tr_b16 v[50:51], v197 offset:0x4000
	ds_read_b64_tr_b16 v[52:53], v197 offset:0x6000
	v_mfma_f32_16x16x32_bf16 v[38:41], v[82:85], v[8:11], v[38:41]
	ds_read_b64_tr_b16 v[82:83], v198 offset:0x4000
	ds_read_b64_tr_b16 v[84:85], v198 offset:0x6000
	v_mfma_f32_16x16x32_bf16 v[42:45], v[210:213], v[8:11], v[42:45]
	ds_read_b64_tr_b16 v[210:211], v199 offset:0x4000
	ds_read_b64_tr_b16 v[212:213], v199 offset:0x6000
	s_waitcnt lgkmcnt(0)
	v_mfma_f32_16x16x32_bf16 v[46:49], v[218:221], v[8:11], v[46:49]
	v_mfma_f32_16x16x32_bf16 v[20:23], v[20:23], v[8:11], v[24:27]
	ds_read_b64_tr_b16 v[24:25], v200 offset:0x4000
	ds_read_b64_tr_b16 v[26:27], v200 offset:0x6000
	v_mfma_f32_16x16x32_bf16 v[50:53], v[50:53], v[8:11], v[54:57]
	ds_read_b64_tr_b16 v[54:55], v201 offset:0x4000
	ds_read_b64_tr_b16 v[56:57], v201 offset:0x6000
	ds_read_b64_tr_b16 v[218:219], v202 offset:0x4000
	ds_read_b64_tr_b16 v[220:221], v202 offset:0x6000
	v_mfma_f32_16x16x32_bf16 v[58:61], v[82:85], v[8:11], v[58:61]
	ds_read_b64_tr_b16 v[82:83], v203 offset:0x4000
	ds_read_b64_tr_b16 v[84:85], v203 offset:0x6000
	s_waitcnt lgkmcnt(0)
	v_mfma_f32_16x16x32_bf16 v[62:65], v[210:213], v[8:11], v[62:65]
	v_mfma_f32_16x16x32_bf16 v[24:27], v[24:27], v[8:11], v[28:31]
	ds_read_b64_tr_b16 v[28:29], v204 offset:0x4000
	ds_read_b64_tr_b16 v[30:31], v204 offset:0x6000
	v_mfma_f32_16x16x32_bf16 v[54:57], v[54:57], v[8:11], v[66:69]
	ds_read_b64_tr_b16 v[66:67], v205 offset:0x4000
	ds_read_b64_tr_b16 v[68:69], v205 offset:0x6000
	ds_read_b64_tr_b16 v[210:211], v206 offset:0x4000
	ds_read_b64_tr_b16 v[212:213], v206 offset:0x6000
	v_mfma_f32_16x16x32_bf16 v[74:77], v[218:221], v[8:11], v[74:77]
	ds_read_b64_tr_b16 v[218:219], v207 offset:0x4000
	ds_read_b64_tr_b16 v[220:221], v207 offset:0x6000
	s_waitcnt lgkmcnt(0)
	v_mfma_f32_16x16x32_bf16 v[78:81], v[82:85], v[8:11], v[78:81]
	v_mfma_f32_16x16x32_bf16 v[28:31], v[28:31], v[8:11], v[34:37]
	ds_read_b64_tr_b16 v[34:35], v192 offset:0x8000
	ds_read_b64_tr_b16 v[36:37], v192 offset:0xa000
	v_mfma_f32_16x16x32_bf16 v[66:69], v[66:69], v[8:11], v[70:73]
	ds_read_b64_tr_b16 v[70:71], v193 offset:0x8000
	ds_read_b64_tr_b16 v[72:73], v193 offset:0xa000
	ds_read_b64_tr_b16 v[82:83], v194 offset:0x8000
	ds_read_b64_tr_b16 v[84:85], v194 offset:0xa000
	v_mfma_f32_16x16x32_bf16 v[210:213], v[210:213], v[8:11], v[214:217]
	ds_read_b64_tr_b16 v[214:215], v195 offset:0x8000
	ds_read_b64_tr_b16 v[216:217], v195 offset:0xa000
	s_waitcnt lgkmcnt(0)
	v_mfma_f32_16x16x32_bf16 v[8:11], v[218:221], v[8:11], v[12:15]
	v_mfma_f32_16x16x32_bf16 v[12:15], v[34:37], v[4:7], v[16:19]
	ds_read_b64_tr_b16 v[16:17], v196 offset:0x8000
	ds_read_b64_tr_b16 v[18:19], v196 offset:0xa000
	v_mfma_f32_16x16x32_bf16 v[34:37], v[70:73], v[4:7], v[38:41]
	ds_read_b64_tr_b16 v[38:39], v197 offset:0x8000
	ds_read_b64_tr_b16 v[40:41], v197 offset:0xa000
	ds_read_b64_tr_b16 v[70:71], v198 offset:0x8000
	ds_read_b64_tr_b16 v[72:73], v198 offset:0xa000
	v_mfma_f32_16x16x32_bf16 v[42:45], v[82:85], v[4:7], v[42:45]
	ds_read_b64_tr_b16 v[82:83], v199 offset:0x8000
	ds_read_b64_tr_b16 v[84:85], v199 offset:0xa000
	s_waitcnt lgkmcnt(0)
	v_mfma_f32_16x16x32_bf16 v[46:49], v[214:217], v[4:7], v[46:49]
	v_mfma_f32_16x16x32_bf16 v[16:19], v[16:19], v[4:7], v[20:23]
	ds_read_b64_tr_b16 v[20:21], v200 offset:0x8000
	ds_read_b64_tr_b16 v[22:23], v200 offset:0xa000
	v_mfma_f32_16x16x32_bf16 v[38:41], v[38:41], v[4:7], v[50:53]
	ds_read_b64_tr_b16 v[50:51], v201 offset:0x8000
	ds_read_b64_tr_b16 v[52:53], v201 offset:0xa000
	ds_read_b64_tr_b16 v[214:215], v202 offset:0x8000
	ds_read_b64_tr_b16 v[216:217], v202 offset:0xa000
	v_mfma_f32_16x16x32_bf16 v[58:61], v[70:73], v[4:7], v[58:61]
	ds_read_b64_tr_b16 v[70:71], v203 offset:0x8000
	ds_read_b64_tr_b16 v[72:73], v203 offset:0xa000
	s_waitcnt lgkmcnt(0)
	v_mfma_f32_16x16x32_bf16 v[62:65], v[82:85], v[4:7], v[62:65]
	v_mfma_f32_16x16x32_bf16 v[20:23], v[20:23], v[4:7], v[24:27]
	ds_read_b64_tr_b16 v[24:25], v204 offset:0x8000
	ds_read_b64_tr_b16 v[26:27], v204 offset:0xa000
	v_mfma_f32_16x16x32_bf16 v[50:53], v[50:53], v[4:7], v[54:57]
	ds_read_b64_tr_b16 v[54:55], v205 offset:0x8000
	ds_read_b64_tr_b16 v[56:57], v205 offset:0xa000
	ds_read_b64_tr_b16 v[82:83], v206 offset:0x8000
	ds_read_b64_tr_b16 v[84:85], v206 offset:0xa000
	v_mfma_f32_16x16x32_bf16 v[74:77], v[214:217], v[4:7], v[74:77]
	ds_read_b64_tr_b16 v[214:215], v207 offset:0x8000
	ds_read_b64_tr_b16 v[216:217], v207 offset:0xa000
	s_waitcnt lgkmcnt(0)
	v_mfma_f32_16x16x32_bf16 v[70:73], v[70:73], v[4:7], v[78:81]
	v_mfma_f32_16x16x32_bf16 v[24:27], v[24:27], v[4:7], v[28:31]
	ds_read_b64_tr_b16 v[28:29], v192 offset:0xc000
	ds_read_b64_tr_b16 v[30:31], v192 offset:0xe000
	v_mfma_f32_16x16x32_bf16 v[54:57], v[54:57], v[4:7], v[66:69]
	ds_read_b64_tr_b16 v[66:67], v193 offset:0xc000
	ds_read_b64_tr_b16 v[68:69], v193 offset:0xe000
	ds_read_b64_tr_b16 v[78:79], v194 offset:0xc000
	ds_read_b64_tr_b16 v[80:81], v194 offset:0xe000
	v_mfma_f32_16x16x32_bf16 v[82:85], v[82:85], v[4:7], v[210:213]
	ds_read_b64_tr_b16 v[210:211], v195 offset:0xc000
	ds_read_b64_tr_b16 v[212:213], v195 offset:0xe000
	s_waitcnt lgkmcnt(0)
	v_mfma_f32_16x16x32_bf16 v[4:7], v[214:217], v[4:7], v[8:11]
	v_mfma_f32_16x16x32_bf16 v[8:11], v[28:31], v[0:3], v[12:15]
	ds_read_b64_tr_b16 v[12:13], v196 offset:0xc000
	ds_read_b64_tr_b16 v[14:15], v196 offset:0xe000
	v_mfma_f32_16x16x32_bf16 v[28:31], v[66:69], v[0:3], v[34:37]
	ds_read_b64_tr_b16 v[34:35], v197 offset:0xc000
	ds_read_b64_tr_b16 v[36:37], v197 offset:0xe000
	ds_read_b64_tr_b16 v[66:67], v198 offset:0xc000
	ds_read_b64_tr_b16 v[68:69], v198 offset:0xe000
	v_mfma_f32_16x16x32_bf16 v[42:45], v[78:81], v[0:3], v[42:45]
	ds_read_b64_tr_b16 v[78:79], v199 offset:0xc000
	ds_read_b64_tr_b16 v[80:81], v199 offset:0xe000
	s_waitcnt lgkmcnt(0)
	v_mfma_f32_16x16x32_bf16 v[46:49], v[210:213], v[0:3], v[46:49]
	v_mfma_f32_16x16x32_bf16 v[12:15], v[12:15], v[0:3], v[16:19]
	ds_read_b64_tr_b16 v[16:17], v200 offset:0xc000
	ds_read_b64_tr_b16 v[18:19], v200 offset:0xe000
	v_mfma_f32_16x16x32_bf16 v[34:37], v[34:37], v[0:3], v[38:41]
	ds_read_b64_tr_b16 v[38:39], v201 offset:0xc000
	ds_read_b64_tr_b16 v[40:41], v201 offset:0xe000
	ds_read_b64_tr_b16 v[210:211], v202 offset:0xc000
	ds_read_b64_tr_b16 v[212:213], v202 offset:0xe000
	v_mfma_f32_16x16x32_bf16 v[58:61], v[66:69], v[0:3], v[58:61]
	ds_read_b64_tr_b16 v[66:67], v203 offset:0xc000
	ds_read_b64_tr_b16 v[68:69], v203 offset:0xe000
	s_waitcnt lgkmcnt(0)
	v_mfma_f32_16x16x32_bf16 v[62:65], v[78:81], v[0:3], v[62:65]
	v_mfma_f32_16x16x32_bf16 v[16:19], v[16:19], v[0:3], v[20:23]
	ds_read_b64_tr_b16 v[20:21], v204 offset:0xc000
	ds_read_b64_tr_b16 v[22:23], v204 offset:0xe000
	v_mfma_f32_16x16x32_bf16 v[38:41], v[38:41], v[0:3], v[50:53]
	ds_read_b64_tr_b16 v[50:51], v205 offset:0xc000
	ds_read_b64_tr_b16 v[52:53], v205 offset:0xe000
	ds_read_b64_tr_b16 v[78:79], v206 offset:0xc000
	ds_read_b64_tr_b16 v[80:81], v206 offset:0xe000
	v_mfma_f32_16x16x32_bf16 v[74:77], v[210:213], v[0:3], v[74:77]
	ds_read_b64_tr_b16 v[210:211], v207 offset:0xc000
	ds_read_b64_tr_b16 v[212:213], v207 offset:0xe000
	s_waitcnt lgkmcnt(0)
	v_mfma_f32_16x16x32_bf16 v[66:69], v[66:69], v[0:3], v[70:73]
	v_div_scale_f32 v33, s[4:5], v32, v32, 1.0
	s_nop 1
	v_rcp_f32_e32 v70, v33
	v_mfma_f32_16x16x32_bf16 v[20:23], v[20:23], v[0:3], v[24:27]
	v_readlane_b32 s4, v255, 19
	s_add_u32 s0, s4, s0
	v_readlane_b32 s4, v255, 20
	v_fma_f32 v24, -v33, v70, 1.0
	v_fmac_f32_e32 v70, v24, v70
	v_mfma_f32_16x16x32_bf16 v[24:27], v[50:53], v[0:3], v[54:57]
	s_addc_u32 s1, s4, s1
	s_add_u32 s0, s0, s2
	s_addc_u32 s1, s1, s3
	v_div_scale_f32 v54, vcc, 1.0, v32, 1.0
	v_mul_f32_e32 v55, v54, v70
	v_fma_f32 v56, -v33, v55, v54
	v_fmac_f32_e32 v55, v56, v70
	v_fma_f32 v33, -v33, v55, v54
	v_mfma_f32_16x16x32_bf16 v[50:53], v[78:81], v[0:3], v[82:85]
	s_add_i32 s35, s35, s77
	s_cmpk_gt_i32 s35, 0x1ff
	v_mfma_f32_16x16x32_bf16 v[0:3], v[210:213], v[0:3], v[4:7]
	s_nop 2
	v_div_fmas_f32 v4, v33, v70, v55
	v_div_fixup_f32 v4, v4, v32, 1.0
	v_mul_f32_e32 v6, 0x41800000, v4
	v_mul_f32_e32 v7, v6, v8
	v_mul_f32_e32 v8, v6, v9
	v_mov_b32_e32 v9, v91
	v_cvt_pk_fp8_f32 v9, v7, v8
	v_mul_f32_e32 v7, v6, v10
	v_mul_f32_e32 v8, v6, v11
	v_mul_f32_e32 v10, v6, v28
	v_mul_f32_e32 v11, v6, v29
	v_mov_b32_e32 v28, v91
	v_cvt_pk_fp8_f32 v28, v10, v11
	v_cvt_pk_fp8_f32 v9, v7, v8 op_sel:[0,0,1]
	v_mul_f32_e32 v7, v6, v30
	v_mul_f32_e32 v8, v6, v31
	v_cvt_pk_fp8_f32 v28, v7, v8 op_sel:[0,0,1]
	v_mul_f32_e32 v7, v6, v42
	v_mul_f32_e32 v8, v6, v43
	v_mov_b32_e32 v10, v91
	v_cvt_pk_fp8_f32 v10, v7, v8
	v_mul_f32_e32 v11, v6, v46
	v_mul_f32_e32 v29, v6, v47
	v_mov_b32_e32 v30, v91
	v_cvt_pk_fp8_f32 v30, v11, v29
	v_mul_f32_e32 v7, v6, v44
	v_mul_f32_e32 v8, v6, v45
	v_lshl_add_u64 v[4:5], s[0:1], 0, v[100:101]
	v_cvt_pk_fp8_f32 v10, v7, v8 op_sel:[0,0,1]
	v_mul_f32_e32 v7, v6, v48
	v_mul_f32_e32 v8, v6, v49
	v_lshl_add_u64 v[4:5], v[4:5], 0, v[88:89]
	v_cvt_pk_fp8_f32 v30, v7, v8 op_sel:[0,0,1]
	global_store_dword v[4:5], v9, off
	global_store_dword v[4:5], v28, off offset:16
	global_store_dword v[4:5], v10, off offset:32
	global_store_dword v[4:5], v30, off offset:48
	v_mul_f32_e32 v7, v6, v12
	v_mul_f32_e32 v8, v6, v13
	v_mov_b32_e32 v9, v91
	v_cvt_pk_fp8_f32 v9, v7, v8
	v_mul_f32_e32 v10, v6, v34
	v_mul_f32_e32 v11, v6, v35
	v_mov_b32_e32 v12, v91
	v_cvt_pk_fp8_f32 v12, v10, v11
	v_mul_f32_e32 v7, v6, v14
	v_mul_f32_e32 v8, v6, v15
	v_cvt_pk_fp8_f32 v9, v7, v8 op_sel:[0,0,1]
	v_mul_f32_e32 v7, v6, v36
	v_mul_f32_e32 v8, v6, v37
	v_cvt_pk_fp8_f32 v12, v7, v8 op_sel:[0,0,1]
	v_mul_f32_e32 v7, v6, v58
	v_mul_f32_e32 v8, v6, v59
	v_mov_b32_e32 v10, v91
	v_cvt_pk_fp8_f32 v10, v7, v8
	v_mul_f32_e32 v11, v6, v62
	v_mul_f32_e32 v13, v6, v63
	v_mov_b32_e32 v14, v91
	v_cvt_pk_fp8_f32 v14, v11, v13
	v_mul_f32_e32 v7, v6, v60
	v_mul_f32_e32 v8, v6, v61
	v_cvt_pk_fp8_f32 v10, v7, v8 op_sel:[0,0,1]
	v_mul_f32_e32 v7, v6, v64
	v_mul_f32_e32 v8, v6, v65
	v_cvt_pk_fp8_f32 v14, v7, v8 op_sel:[0,0,1]
	global_store_dword v[4:5], v9, off offset:64
	global_store_dword v[4:5], v12, off offset:80
	global_store_dword v[4:5], v10, off offset:96
	global_store_dword v[4:5], v14, off offset:112
	v_mul_f32_e32 v7, v6, v16
	v_mul_f32_e32 v8, v6, v17
	v_mov_b32_e32 v9, v91
	v_cvt_pk_fp8_f32 v9, v7, v8
	v_mul_f32_e32 v10, v6, v38
	v_mul_f32_e32 v11, v6, v39
	v_mov_b32_e32 v12, v91
	v_cvt_pk_fp8_f32 v12, v10, v11
	v_mul_f32_e32 v7, v6, v18
	v_mul_f32_e32 v8, v6, v19
	v_cvt_pk_fp8_f32 v9, v7, v8 op_sel:[0,0,1]
	v_mul_f32_e32 v7, v6, v40
	v_mul_f32_e32 v8, v6, v41
	v_cvt_pk_fp8_f32 v12, v7, v8 op_sel:[0,0,1]
	v_mul_f32_e32 v7, v6, v74
	v_mul_f32_e32 v8, v6, v75
	v_mov_b32_e32 v10, v91
	v_cvt_pk_fp8_f32 v10, v7, v8
	v_mul_f32_e32 v11, v6, v66
	v_mul_f32_e32 v13, v6, v67
	v_mov_b32_e32 v14, v91
	v_cvt_pk_fp8_f32 v14, v11, v13
	v_mul_f32_e32 v7, v6, v76
	v_mul_f32_e32 v8, v6, v77
	v_cvt_pk_fp8_f32 v10, v7, v8 op_sel:[0,0,1]
	v_mul_f32_e32 v7, v6, v68
	v_mul_f32_e32 v8, v6, v69
	v_cvt_pk_fp8_f32 v14, v7, v8 op_sel:[0,0,1]
	global_store_dword v[4:5], v9, off offset:128
	global_store_dword v[4:5], v12, off offset:144
	global_store_dword v[4:5], v10, off offset:160
	global_store_dword v[4:5], v14, off offset:176
	v_mul_f32_e32 v7, v6, v20
	v_mul_f32_e32 v8, v6, v21
	v_mov_b32_e32 v9, v91
	v_cvt_pk_fp8_f32 v9, v7, v8
	v_mul_f32_e32 v10, v6, v24
	v_mul_f32_e32 v11, v6, v25
	v_mov_b32_e32 v12, v91
	v_cvt_pk_fp8_f32 v12, v10, v11
	v_mul_f32_e32 v7, v6, v22
	v_mul_f32_e32 v8, v6, v23
	v_cvt_pk_fp8_f32 v9, v7, v8 op_sel:[0,0,1]
	v_mul_f32_e32 v7, v6, v26
	v_mul_f32_e32 v8, v6, v27
	v_cvt_pk_fp8_f32 v12, v7, v8 op_sel:[0,0,1]
	v_mul_f32_e32 v7, v6, v50
	v_mul_f32_e32 v8, v6, v51
	v_mov_b32_e32 v10, v91
	v_cvt_pk_fp8_f32 v10, v7, v8
	v_mul_f32_e32 v0, v6, v0
	v_mul_f32_e32 v1, v6, v1
	v_mov_b32_e32 v11, v91
	v_cvt_pk_fp8_f32 v11, v0, v1
	v_mul_f32_e32 v7, v6, v52
	v_mul_f32_e32 v8, v6, v53
	v_cvt_pk_fp8_f32 v10, v7, v8 op_sel:[0,0,1]
	v_mul_f32_e32 v0, v6, v2
	v_mul_f32_e32 v1, v6, v3
	v_cvt_pk_fp8_f32 v11, v0, v1 op_sel:[0,0,1]
	global_store_dword v[4:5], v9, off offset:192
	global_store_dword v[4:5], v12, off offset:208
	global_store_dword v[4:5], v10, off offset:224
	global_store_dword v[4:5], v11, off offset:240
	s_waitcnt vmcnt(0) lgkmcnt(0)
	s_barrier
	s_cbranch_scc0 .LBB0_1108
	s_waitcnt vmcnt(0) lgkmcnt(0)
	s_barrier
	v_readlane_b32 s82, v255, 13
	v_readlane_b32 s84, v255, 11
	v_readlane_b32 s88, v255, 8
	v_readlane_b32 s90, v255, 5
	v_readlane_b32 s80, v255, 21
	v_readlane_b32 s83, v255, 14
	v_readlane_b32 s85, v255, 12
	v_readlane_b32 s86, v255, 10
	v_readlane_b32 s89, v255, 9
	v_readlane_b32 s87, v255, 7
	v_readlane_b32 s91, v255, 6
	v_readlane_b32 s92, v255, 4
